# v47 + MLA loop K-fragment LDS addresses from 4 bases + immediates (8 fewer VALU adds per tile) + softmax row-sum chain without the leading add-with-zero
# speedup vs baseline: 1.0196x; 1.0079x over previous
; #define LAS __attribute__((address_space(3)))
; DI void expsum(f32x16& p, float& l_reg, bf16x8& pa0, bf16x8& pa1) {
; #pragma unroll
;     for (int r = 0; r < 16; ++r) p[r] = __builtin_amdgcn_exp2f(p[r]);
;     float ps = 0.f;
; #pragma unroll
;     for (int r = 0; r < 16; ++r) ps += p[r];
;     l_reg += ps; asm volatile("" : "+v"(l_reg));
;     ...
;     ATT_PK4(p, 0, pa0); ATT_PK4(p, 8, pa1);
;     ...
; }
; DI int v_rd_base(int lane) { return ((lane & 3) << 3) | (((lane >> 2) & 3) << 6) | (((lane >> 4) & 1) << 5) | (((lane >> 5) & 1) << 8); }
; template <int OFF> DI s16x4 tr_read(int vb) { s16x4 r; asm volatile("ds_read_b64_tr_b16 %0, %1 offset:%2" : "=&v"(r) : "v"(vb), "i"(OFF) : "memory"); return r; }
; template <int H> DI void v_reads(s16x4* vf, int vb) {
;     vf[0] = tr_read<v_rd_off(0, 2 * H, 0)>(vb); vf[1] = tr_read<v_rd_off(0, 2 * H, 1)>(vb); vf[2] = tr_read<v_rd_off(0, 2 * H + 1, 0)>(vb); vf[3] = tr_read<v_rd_off(0, 2 * H + 1, 1)>(vb);
;     vf[4] = tr_read<v_rd_off(1, 2 * H, 0)>(vb); vf[5] = tr_read<v_rd_off(1, 2 * H, 1)>(vb); vf[6] = tr_read<v_rd_off(1, 2 * H + 1, 0)>(vb); vf[7] = tr_read<v_rd_off(1, 2 * H + 1, 1)>(vb);
;     vf[8] = tr_read<v_rd_off(2, 2 * H, 0)>(vb); vf[9] = tr_read<v_rd_off(2, 2 * H, 1)>(vb); vf[10] = tr_read<v_rd_off(2, 2 * H + 1, 0)>(vb); vf[11] = tr_read<v_rd_off(2, 2 * H + 1, 1)>(vb);
;     vf[12] = tr_read<v_rd_off(3, 2 * H, 0)>(vb); vf[13] = tr_read<v_rd_off(3, 2 * H, 1)>(vb); vf[14] = tr_read<v_rd_off(3, 2 * H + 1, 0)>(vb); vf[15] = tr_read<v_rd_off(3, 2 * H + 1, 1)>(vb);
; }
; DI void pv_mma(f32x16* o, const s16x4* vf, bf16x8 pa0, bf16x8 pa1) {
;     ...
; #pragma unroll
;     for (int d0 = 0; d0 < 4; ++d0) {
;         o[d0] = __builtin_amdgcn_mfma_f32_32x32x16_bf16(pa0, ATT_PK(vf[4 * d0], vf[4 * d0 + 1]), o[d0], 0, 0, 0);
;         o[d0] = __builtin_amdgcn_mfma_f32_32x32x16_bf16(pa1, ATT_PK(vf[4 * d0 + 2], vf[4 * d0 + 3]), o[d0], 0, 0, 0); }
;     ...
; }
; template <int DQK, int D0A, int D0B> DI void k_reads(bf16x8* kf, const LAS unsigned char* Ks, int half, int r32, int hi) {
; #pragma unroll
;     for (int d0 = D0A; d0 < D0B; ++d0) kf[d0 - D0A] = *(const LAS bf16x8*)(Ks + half * (32 * DQK * 2) + kswz<DQK>(r32, (d0 * 16 + hi * 8) * 2));
; }
; template <int D0A, int D0B> DI void qk_mma(f32x16& p, const bf16x8* kf, const bf16x8* qr) {
; #pragma unroll
;     for (int d0 = D0A; d0 < D0B; ++d0) {
.LBB0_1922:
	s_add_i32 s3, s0, -1
	s_add_i32 s2, s22, 0xffffa000
	s_and_b32 s2, s2, 0x6000
	v_add_u32_e32 v121, s2, v114
	v_add_u32_e32 v122, v121, v115
	v_add_u32_e32 v126, v121, v116
	ds_read_b128 v[122:125], v122 offset:4096
	ds_read_b128 v[132:135], v126 offset:4096
	v_add_u32_e32 v126, v121, v117
	v_add_u32_e32 v121, v121, v118
	s_lshl_b32 s2, s1, 14
	ds_read_b128 v[136:139], v126 offset:4096
	ds_read_b128 v[140:143], v121 offset:4096
	v_add_u32_e32 v121, s2, v106
	ds_read_b64_tr_b16 v[144:145], v121 offset:0
	ds_read_b64_tr_b16 v[146:147], v121 offset:0x800
	ds_read_b64_tr_b16 v[148:149], v121 offset:0x1000
	ds_read_b64_tr_b16 v[150:151], v121 offset:0x1800
	ds_read_b64_tr_b16 v[152:153], v121 offset:0x200
	ds_read_b64_tr_b16 v[154:155], v121 offset:0xa00
	ds_read_b64_tr_b16 v[156:157], v121 offset:0x1200
	ds_read_b64_tr_b16 v[158:159], v121 offset:0x1a00
	ds_read_b64_tr_b16 v[162:163], v121 offset:0x400
	ds_read_b64_tr_b16 v[164:165], v121 offset:0xc00
	ds_read_b64_tr_b16 v[166:167], v121 offset:0x1400
	ds_read_b64_tr_b16 v[168:169], v121 offset:0x1c00
	ds_read_b64_tr_b16 v[170:171], v121 offset:0x600
	ds_read_b64_tr_b16 v[172:173], v121 offset:0xe00
	ds_read_b64_tr_b16 v[174:175], v121 offset:0x1600
	ds_read_b64_tr_b16 v[176:177], v121 offset:0x1e00
	s_setprio 2
	v_exp_f32_e32 v64, v64
	v_exp_f32_e32 v65, v65
	v_exp_f32_e32 v66, v66
	v_exp_f32_e32 v67, v67
	v_exp_f32_e32 v68, v68
	v_exp_f32_e32 v69, v69
	v_add_f32_e32 v126, v65, v64
	v_exp_f32_e32 v70, v70
	v_add_f32_e32 v126, v66, v126
	v_exp_f32_e32 v71, v71
	v_add_f32_e32 v126, v67, v126
	v_exp_f32_e32 v72, v72
	v_add_f32_e32 v126, v68, v126
	v_exp_f32_e32 v73, v73
	v_add_f32_e32 v126, v69, v126
	v_exp_f32_e32 v74, v74
	v_add_f32_e32 v126, v70, v126
	v_exp_f32_e32 v75, v75
	v_add_f32_e32 v126, v71, v126
	v_exp_f32_e32 v76, v76
	v_add_f32_e32 v126, v72, v126
	v_exp_f32_e32 v77, v77
	v_add_f32_e32 v126, v73, v126
	v_exp_f32_e32 v78, v78
	v_add_f32_e32 v126, v74, v126
	v_exp_f32_e32 v79, v79
	v_add_f32_e32 v126, v75, v126
	v_add_f32_e32 v126, v76, v126
	v_add_f32_e32 v126, v77, v126
	v_add_f32_e32 v126, v78, v126
	v_add_f32_e32 v126, v79, v126
	v_add_f32_e32 v120, v126, v120
	v_cvt_pk_bf16_f32 v64, v64, v65
	v_cvt_pk_bf16_f32 v65, v66, v67
	v_cvt_pk_bf16_f32 v66, v68, v69
	v_cvt_pk_bf16_f32 v67, v70, v71
	v_cvt_pk_bf16_f32 v68, v72, v73
	v_cvt_pk_bf16_f32 v69, v74, v75
	v_cvt_pk_bf16_f32 v70, v76, v77
	v_cvt_pk_bf16_f32 v71, v78, v79
	s_nop 0
	v_permlane32_swap_b32_e32 v64, v66
	v_permlane32_swap_b32_e32 v65, v67
	v_permlane32_swap_b32_e32 v68, v70
	v_permlane32_swap_b32_e32 v69, v71
	s_waitcnt lgkmcnt(0)
	s_setprio 1
	v_mfma_f32_32x32x16_bf16 v[0:15], v[64:67], v[144:147], v[0:15]
	s_cmp_lt_i32 s3, s55
	s_cselect_b64 vcc, -1, 0
	s_cmp_ge_i32 s3, s97
	s_cselect_b64 s[74:75], -1, 0
	s_or_b64 s[74:75], vcc, s[74:75]
	s_and_b64 vcc, exec, s[74:75]
	v_mfma_f32_32x32x16_bf16 v[48:63], v[64:67], v[152:155], v[48:63]
	v_mfma_f32_32x32x16_bf16 v[32:47], v[64:67], v[162:165], v[32:47]
	v_mfma_f32_32x32x16_bf16 v[16:31], v[64:67], v[170:173], v[16:31]
	v_mfma_f32_32x32x16_bf16 v[0:15], v[68:71], v[148:151], v[0:15]
	v_mfma_f32_32x32x16_bf16 v[48:63], v[68:71], v[156:159], v[48:63]
	v_mfma_f32_32x32x16_bf16 v[32:47], v[68:71], v[166:169], v[32:47]
	v_mfma_f32_32x32x16_bf16 v[16:31], v[68:71], v[174:177], v[16:31]
	v_mfma_f32_32x32x16_bf16 v[64:79], v[122:125], v[92:95], 0
	v_mfma_f32_32x32x16_bf16 v[64:79], v[132:135], v[88:91], v[64:79]
	v_mfma_f32_32x32x16_bf16 v[64:79], v[136:139], v[84:87], v[64:79]
	v_mfma_f32_32x32x16_bf16 v[64:79], v[140:143], v[80:83], v[64:79]
	s_setprio 0
	v_add_u32_e32 v122, s7, v119
	s_cbranch_vccnz .LBB0_1924
	v_add_u32_e32 v138, 0x28908, v122
	v_add_u32_e32 v140, 0x28920, v122
	v_add_u32_e32 v142, 0x28928, v122
	v_add_u32_e32 v124, 0x28940, v122
	v_add_u32_e32 v126, 0x28948, v122
	v_add_u32_e32 v132, 0x28960, v122
	v_add_u32_e32 v134, 0x28968, v122
	v_add_u32_e32 v123, 0x28900, v122
	ds_read2_b32 v[124:125], v124 offset1:1
	ds_read2_b32 v[126:127], v126 offset1:1
	ds_read2_b32 v[132:133], v132 offset1:1
	ds_read2_b32 v[134:135], v134 offset1:1
	ds_read2_b32 v[136:137], v123 offset1:1
	ds_read2_b32 v[138:139], v138 offset1:1
	ds_read2_b32 v[140:141], v140 offset1:1
	ds_read2_b32 v[142:143], v142 offset1:1
	s_waitcnt lgkmcnt(0)
	v_pk_add_f32 v[78:79], v[78:79], v[134:135]
	v_pk_add_f32 v[76:77], v[76:77], v[132:133]
	v_pk_add_f32 v[74:75], v[74:75], v[126:127]
	v_pk_add_f32 v[72:73], v[72:73], v[124:125]
	v_pk_add_f32 v[70:71], v[70:71], v[142:143]
	v_pk_add_f32 v[68:69], v[68:69], v[140:141]
	v_pk_add_f32 v[66:67], v[66:67], v[138:139]
	v_pk_add_f32 v[64:65], v[64:65], v[136:137]
; DI void expsum(f32x16& p, float& l_reg, bf16x8& pa0, bf16x8& pa1) {
; #pragma unroll
;     for (int r = 0; r < 16; ++r) p[r] = __builtin_amdgcn_exp2f(p[r]);
;     float ps = 0.f;
; #pragma unroll
;     for (int r = 0; r < 16; ++r) ps += p[r];
;     l_reg += ps; asm volatile("" : "+v"(l_reg));
;     ...
;     ATT_PK4(p, 0, pa0); ATT_PK4(p, 8, pa1);
;     ...
; }
; DI int v_rd_base(int lane) { return ((lane & 3) << 3) | (((lane >> 2) & 3) << 6) | (((lane >> 4) & 1) << 5) | (((lane >> 5) & 1) << 8); }
; template <int OFF> DI s16x4 tr_read(int vb) { s16x4 r; asm volatile("ds_read_b64_tr_b16 %0, %1 offset:%2" : "=&v"(r) : "v"(vb), "i"(OFF) : "memory"); return r; }
; template <int H> DI void v_reads(s16x4* vf, int vb) {
;     vf[0] = tr_read<v_rd_off(0, 2 * H, 0)>(vb); vf[1] = tr_read<v_rd_off(0, 2 * H, 1)>(vb); vf[2] = tr_read<v_rd_off(0, 2 * H + 1, 0)>(vb); vf[3] = tr_read<v_rd_off(0, 2 * H + 1, 1)>(vb);
;     vf[4] = tr_read<v_rd_off(1, 2 * H, 0)>(vb); vf[5] = tr_read<v_rd_off(1, 2 * H, 1)>(vb); vf[6] = tr_read<v_rd_off(1, 2 * H + 1, 0)>(vb); vf[7] = tr_read<v_rd_off(1, 2 * H + 1, 1)>(vb);
;     vf[8] = tr_read<v_rd_off(2, 2 * H, 0)>(vb); vf[9] = tr_read<v_rd_off(2, 2 * H, 1)>(vb); vf[10] = tr_read<v_rd_off(2, 2 * H + 1, 0)>(vb); vf[11] = tr_read<v_rd_off(2, 2 * H + 1, 1)>(vb);
;     vf[12] = tr_read<v_rd_off(3, 2 * H, 0)>(vb); vf[13] = tr_read<v_rd_off(3, 2 * H, 1)>(vb); vf[14] = tr_read<v_rd_off(3, 2 * H + 1, 0)>(vb); vf[15] = tr_read<v_rd_off(3, 2 * H + 1, 1)>(vb);
; }
.LBB0_1924:
	s_add_i32 s3, s22, 0xffffc000
	s_and_b32 s3, s3, 0x6000
	v_add_u32_e32 v123, s3, v114
	v_add_u32_e32 v140, v123, v118
	v_add_u32_e32 v136, v123, v117
	v_add_u32_e32 v132, v123, v116
	v_add_u32_e32 v123, v123, v115
	ds_read_b128 v[124:127], v123
	ds_read_b128 v[132:135], v132
	ds_read_b128 v[136:139], v136
	ds_read_b128 v[140:143], v140
	ds_read_b64_tr_b16 v[144:145], v121 offset:0x2000
	ds_read_b64_tr_b16 v[146:147], v121 offset:0x2800
	ds_read_b64_tr_b16 v[148:149], v121 offset:0x3000
	ds_read_b64_tr_b16 v[150:151], v121 offset:0x3800
	ds_read_b64_tr_b16 v[152:153], v121 offset:0x2200
	ds_read_b64_tr_b16 v[154:155], v121 offset:0x2a00
	ds_read_b64_tr_b16 v[156:157], v121 offset:0x3200
	ds_read_b64_tr_b16 v[158:159], v121 offset:0x3a00
	ds_read_b64_tr_b16 v[162:163], v121 offset:0x2400
	ds_read_b64_tr_b16 v[164:165], v121 offset:0x2c00
	ds_read_b64_tr_b16 v[166:167], v121 offset:0x3400
	ds_read_b64_tr_b16 v[168:169], v121 offset:0x3c00
	ds_read_b64_tr_b16 v[170:171], v121 offset:0x2600
	ds_read_b64_tr_b16 v[172:173], v121 offset:0x2e00
	ds_read_b64_tr_b16 v[174:175], v121 offset:0x3600
	ds_read_b64_tr_b16 v[176:177], v121 offset:0x3e00
	s_setprio 2
	v_exp_f32_e32 v64, v64
	v_exp_f32_e32 v65, v65
	v_exp_f32_e32 v66, v66
	v_exp_f32_e32 v67, v67
	v_exp_f32_e32 v68, v68
	v_exp_f32_e32 v69, v69
	v_add_f32_e32 v121, v65, v64
	v_exp_f32_e32 v70, v70
	v_add_f32_e32 v121, v66, v121
	v_exp_f32_e32 v71, v71
	v_add_f32_e32 v121, v67, v121
	v_exp_f32_e32 v72, v72
	v_add_f32_e32 v121, v68, v121
	v_exp_f32_e32 v73, v73
	v_add_f32_e32 v121, v69, v121
	v_exp_f32_e32 v74, v74
	v_add_f32_e32 v121, v70, v121
	v_exp_f32_e32 v75, v75
	v_add_f32_e32 v121, v71, v121
	v_exp_f32_e32 v76, v76
	v_add_f32_e32 v121, v72, v121
	v_exp_f32_e32 v77, v77
	v_add_f32_e32 v121, v73, v121
	v_exp_f32_e32 v78, v78
	v_add_f32_e32 v121, v74, v121
	v_exp_f32_e32 v79, v79
	v_add_f32_e32 v121, v75, v121
	v_add_f32_e32 v121, v76, v121
	v_add_f32_e32 v121, v77, v121
	v_add_f32_e32 v121, v78, v121
	v_add_f32_e32 v121, v79, v121
	v_add_f32_e32 v120, v120, v121
	v_cvt_pk_bf16_f32 v64, v64, v65
	v_cvt_pk_bf16_f32 v65, v66, v67
	v_cvt_pk_bf16_f32 v66, v68, v69
	v_cvt_pk_bf16_f32 v67, v70, v71
	v_cvt_pk_bf16_f32 v68, v72, v73
	v_cvt_pk_bf16_f32 v69, v74, v75
	v_cvt_pk_bf16_f32 v70, v76, v77
	v_cvt_pk_bf16_f32 v71, v78, v79
	s_nop 0
	v_permlane32_swap_b32_e32 v64, v66
	v_permlane32_swap_b32_e32 v65, v67
	v_permlane32_swap_b32_e32 v68, v70
	v_permlane32_swap_b32_e32 v69, v71
	s_waitcnt lgkmcnt(0)
	s_setprio 1
	s_cmp_lt_u32 s33, 0x100
	s_cbranch_scc1 .Lstg_d0_mid_11
	s_waitcnt vmcnt(3)
	s_barrier

; #define LAS __attribute__((address_space(3)))
; DI void expsum(f32x16& p, float& l_reg, bf16x8& pa0, bf16x8& pa1) {
; #pragma unroll
;     for (int r = 0; r < 16; ++r) p[r] = __builtin_amdgcn_exp2f(p[r]);
;     float ps = 0.f;
; #pragma unroll
;     for (int r = 0; r < 16; ++r) ps += p[r];
;     l_reg += ps; asm volatile("" : "+v"(l_reg));
;     ...
;     ATT_PK4(p, 0, pa0); ATT_PK4(p, 8, pa1);
;     ...
; }
; DI int v_rd_base(int lane) { return ((lane & 3) << 3) | (((lane >> 2) & 3) << 6) | (((lane >> 4) & 1) << 5) | (((lane >> 5) & 1) << 8); }
; template <int OFF> DI s16x4 tr_read(int vb) { s16x4 r; asm volatile("ds_read_b64_tr_b16 %0, %1 offset:%2" : "=&v"(r) : "v"(vb), "i"(OFF) : "memory"); return r; }
; template <int H> DI void v_reads(s16x4* vf, int vb) {
;     vf[0] = tr_read<v_rd_off(0, 2 * H, 0)>(vb); vf[1] = tr_read<v_rd_off(0, 2 * H, 1)>(vb); vf[2] = tr_read<v_rd_off(0, 2 * H + 1, 0)>(vb); vf[3] = tr_read<v_rd_off(0, 2 * H + 1, 1)>(vb);
;     vf[4] = tr_read<v_rd_off(1, 2 * H, 0)>(vb); vf[5] = tr_read<v_rd_off(1, 2 * H, 1)>(vb); vf[6] = tr_read<v_rd_off(1, 2 * H + 1, 0)>(vb); vf[7] = tr_read<v_rd_off(1, 2 * H + 1, 1)>(vb);
;     vf[8] = tr_read<v_rd_off(2, 2 * H, 0)>(vb); vf[9] = tr_read<v_rd_off(2, 2 * H, 1)>(vb); vf[10] = tr_read<v_rd_off(2, 2 * H + 1, 0)>(vb); vf[11] = tr_read<v_rd_off(2, 2 * H + 1, 1)>(vb);
;     vf[12] = tr_read<v_rd_off(3, 2 * H, 0)>(vb); vf[13] = tr_read<v_rd_off(3, 2 * H, 1)>(vb); vf[14] = tr_read<v_rd_off(3, 2 * H + 1, 0)>(vb); vf[15] = tr_read<v_rd_off(3, 2 * H + 1, 1)>(vb);
; }
; DI void pv_mma(f32x16* o, const s16x4* vf, bf16x8 pa0, bf16x8 pa1) {
;     ...
; #pragma unroll
;     for (int d0 = 0; d0 < 4; ++d0) {
;         o[d0] = __builtin_amdgcn_mfma_f32_32x32x16_bf16(pa0, ATT_PK(vf[4 * d0], vf[4 * d0 + 1]), o[d0], 0, 0, 0);
;         o[d0] = __builtin_amdgcn_mfma_f32_32x32x16_bf16(pa1, ATT_PK(vf[4 * d0 + 2], vf[4 * d0 + 3]), o[d0], 0, 0, 0); }
;     ...
; }
; template <int DQK, int D0A, int D0B> DI void k_reads(bf16x8* kf, const LAS unsigned char* Ks, int half, int r32, int hi) {
; #pragma unroll
;     for (int d0 = D0A; d0 < D0B; ++d0) kf[d0 - D0A] = *(const LAS bf16x8*)(Ks + half * (32 * DQK * 2) + kswz<DQK>(r32, (d0 * 16 + hi * 8) * 2));
; }
; template <int D0A, int D0B> DI void qk_mma(f32x16& p, const bf16x8* kf, const bf16x8* qr) {
; #pragma unroll
;     for (int d0 = D0A; d0 < D0B; ++d0) {
.LBB0_1930:
	s_mov_b64 s[96:97], 0xc00
	ds_read_b128 v[98:101], v107 offset:12288
	ds_read_b128 v[102:105], v108 offset:12288
	ds_read_b128 v[114:117], v109 offset:12288
	ds_read_b128 v[122:125], v110 offset:12288
	v_lshl_add_u32 v96, s64, 14, v106
	ds_read_b64_tr_b16 v[132:133], v96 offset:0
	ds_read_b64_tr_b16 v[134:135], v96 offset:0x800
	ds_read_b64_tr_b16 v[136:137], v96 offset:0x1000
	ds_read_b64_tr_b16 v[138:139], v96 offset:0x1800
	ds_read_b64_tr_b16 v[140:141], v96 offset:0x200
	ds_read_b64_tr_b16 v[142:143], v96 offset:0xa00
	ds_read_b64_tr_b16 v[144:145], v96 offset:0x1200
	ds_read_b64_tr_b16 v[146:147], v96 offset:0x1a00
	ds_read_b64_tr_b16 v[148:149], v96 offset:0x400
	ds_read_b64_tr_b16 v[150:151], v96 offset:0xc00
	ds_read_b64_tr_b16 v[152:153], v96 offset:0x1400
	ds_read_b64_tr_b16 v[154:155], v96 offset:0x1c00
	ds_read_b64_tr_b16 v[156:157], v96 offset:0x600
	ds_read_b64_tr_b16 v[158:159], v96 offset:0xe00
	ds_read_b64_tr_b16 v[162:163], v96 offset:0x1600
	ds_read_b64_tr_b16 v[164:165], v96 offset:0x1e00
	s_setprio 2
	v_exp_f32_e32 v64, v64
	v_exp_f32_e32 v65, v65
	v_exp_f32_e32 v66, v66
	v_exp_f32_e32 v67, v67
	v_exp_f32_e32 v68, v68
	v_exp_f32_e32 v69, v69
	v_add_f32_e32 v97, v65, v64
	v_exp_f32_e32 v70, v70
	v_add_f32_e32 v97, v66, v97
	v_exp_f32_e32 v71, v71
	v_add_f32_e32 v97, v67, v97
	v_exp_f32_e32 v72, v72
	v_add_f32_e32 v97, v68, v97
	v_exp_f32_e32 v73, v73
	v_add_f32_e32 v97, v69, v97
	v_exp_f32_e32 v74, v74
	v_add_f32_e32 v97, v70, v97
	v_exp_f32_e32 v75, v75
	v_add_f32_e32 v97, v71, v97
	v_exp_f32_e32 v76, v76
	v_add_f32_e32 v97, v72, v97
	v_exp_f32_e32 v77, v77
	v_add_f32_e32 v97, v73, v97
	v_exp_f32_e32 v78, v78
	v_add_f32_e32 v97, v74, v97
	v_exp_f32_e32 v79, v79
	v_add_f32_e32 v97, v75, v97
	v_add_f32_e32 v97, v76, v97
	v_add_f32_e32 v97, v77, v97
	v_add_f32_e32 v97, v78, v97
	v_add_f32_e32 v97, v79, v97
	v_add_f32_e32 v97, v97, v120
	v_cvt_pk_bf16_f32 v64, v64, v65
	v_cvt_pk_bf16_f32 v65, v66, v67
	v_cvt_pk_bf16_f32 v66, v68, v69
	v_cvt_pk_bf16_f32 v67, v70, v71
	v_cvt_pk_bf16_f32 v68, v72, v73
	v_cvt_pk_bf16_f32 v69, v74, v75
	v_cvt_pk_bf16_f32 v70, v76, v77
	v_cvt_pk_bf16_f32 v71, v78, v79
	s_nop 0
	v_permlane32_swap_b32_e32 v64, v66
	v_permlane32_swap_b32_e32 v65, v67
	v_permlane32_swap_b32_e32 v68, v70
	v_permlane32_swap_b32_e32 v69, v71
	s_waitcnt lgkmcnt(0)
	s_setprio 1
	v_mfma_f32_32x32x16_bf16 v[0:15], v[64:67], v[132:135], v[0:15]
	s_cmp_gt_i32 s55, 61
	s_cselect_b64 s[0:1], -1, 0
	s_cmp_lt_i32 s58, 62
	s_cselect_b64 s[2:3], -1, 0
	s_or_b64 s[0:1], s[0:1], s[2:3]
	s_and_b64 vcc, exec, s[0:1]
	v_mfma_f32_32x32x16_bf16 v[48:63], v[64:67], v[140:143], v[48:63]
	v_mfma_f32_32x32x16_bf16 v[32:47], v[64:67], v[148:151], v[32:47]
	v_mfma_f32_32x32x16_bf16 v[16:31], v[64:67], v[156:159], v[16:31]
	v_mfma_f32_32x32x16_bf16 v[0:15], v[68:71], v[136:139], v[0:15]
	v_mfma_f32_32x32x16_bf16 v[48:63], v[68:71], v[144:147], v[48:63]
	v_mfma_f32_32x32x16_bf16 v[32:47], v[68:71], v[152:155], v[32:47]
	v_mfma_f32_32x32x16_bf16 v[16:31], v[68:71], v[162:165], v[16:31]
	s_waitcnt lgkmcnt(0)
	v_mfma_f32_32x32x16_bf16 v[64:79], v[98:101], v[92:95], 0
	v_mfma_f32_32x32x16_bf16 v[64:79], v[102:105], v[88:91], v[64:79]
	v_mfma_f32_32x32x16_bf16 v[64:79], v[114:117], v[84:87], v[64:79]
	v_mfma_f32_32x32x16_bf16 v[64:79], v[122:125], v[80:83], v[64:79]
	s_setprio 0
	s_cbranch_vccnz .LBB0_1932
	v_sub_u32_e32 v98, 0xf40, v111
	v_lshlrev_b32_e32 v98, 2, v98
	v_add3_u32 v98, s88, v98, v130
	v_add_u32_e32 v114, 0x400, v98
	v_add_u32_e32 v116, 0x408, v98
	v_add_u32_e32 v118, 0x420, v98
	v_add_u32_e32 v120, 0x428, v98
	v_add_u32_e32 v99, 0x440, v98
	v_add_u32_e32 v100, 0x448, v98
	v_add_u32_e32 v102, 0x460, v98
	v_add_u32_e32 v104, 0x468, v98
	ds_read2_b32 v[98:99], v99 offset1:1
	ds_read2_b32 v[100:101], v100 offset1:1
	ds_read2_b32 v[102:103], v102 offset1:1
	ds_read2_b32 v[104:105], v104 offset1:1
	ds_read2_b32 v[114:115], v114 offset1:1
	ds_read2_b32 v[116:117], v116 offset1:1
	ds_read2_b32 v[118:119], v118 offset1:1
	ds_read2_b32 v[120:121], v120 offset1:1
	s_waitcnt lgkmcnt(0)
	v_pk_add_f32 v[78:79], v[78:79], v[104:105]
	v_pk_add_f32 v[76:77], v[76:77], v[102:103]
	v_pk_add_f32 v[74:75], v[74:75], v[100:101]
	v_pk_add_f32 v[72:73], v[72:73], v[98:99]
	v_pk_add_f32 v[70:71], v[70:71], v[120:121]
	v_pk_add_f32 v[68:69], v[68:69], v[118:119]
	v_pk_add_f32 v[66:67], v[66:67], v[116:117]
	v_pk_add_f32 v[64:65], v[64:65], v[114:115]
.LBB0_1932:
	s_movk_i32 s64, 0x70
	ds_read_b128 v[98:101], v107 offset:16384
	ds_read_b128 v[102:105], v108 offset:16384
	ds_read_b128 v[114:117], v109 offset:16384
	ds_read_b128 v[118:121], v110 offset:16384
	ds_read_b64_tr_b16 v[122:123], v96 offset:0x2000
	ds_read_b64_tr_b16 v[124:125], v96 offset:0x2800
	ds_read_b64_tr_b16 v[132:133], v96 offset:0x3000
	ds_read_b64_tr_b16 v[134:135], v96 offset:0x3800
	ds_read_b64_tr_b16 v[136:137], v96 offset:0x2200
	ds_read_b64_tr_b16 v[138:139], v96 offset:0x2a00
	ds_read_b64_tr_b16 v[140:141], v96 offset:0x3200
	ds_read_b64_tr_b16 v[142:143], v96 offset:0x3a00
	ds_read_b64_tr_b16 v[144:145], v96 offset:0x2400
	ds_read_b64_tr_b16 v[146:147], v96 offset:0x2c00
	ds_read_b64_tr_b16 v[148:149], v96 offset:0x3400
	ds_read_b64_tr_b16 v[150:151], v96 offset:0x3c00
	ds_read_b64_tr_b16 v[152:153], v96 offset:0x2600
	ds_read_b64_tr_b16 v[154:155], v96 offset:0x2e00
	ds_read_b64_tr_b16 v[156:157], v96 offset:0x3600
	ds_read_b64_tr_b16 v[158:159], v96 offset:0x3e00
	s_nop 5
	s_setprio 2
	v_exp_f32_e32 v64, v64
	v_exp_f32_e32 v65, v65
	v_exp_f32_e32 v66, v66
	v_exp_f32_e32 v67, v67
	v_exp_f32_e32 v68, v68
	v_exp_f32_e32 v69, v69
	v_add_f32_e32 v96, v65, v64
	v_exp_f32_e32 v70, v70
	v_add_f32_e32 v96, v66, v96
	v_exp_f32_e32 v71, v71
	v_add_f32_e32 v96, v67, v96
	v_exp_f32_e32 v72, v72
	v_add_f32_e32 v96, v68, v96
	v_exp_f32_e32 v73, v73
	v_add_f32_e32 v96, v69, v96
	v_exp_f32_e32 v74, v74
	v_add_f32_e32 v96, v70, v96
	v_exp_f32_e32 v75, v75
	v_add_f32_e32 v96, v71, v96
	v_exp_f32_e32 v76, v76
	v_add_f32_e32 v96, v72, v96
	v_exp_f32_e32 v77, v77
	v_add_f32_e32 v96, v73, v96
	v_exp_f32_e32 v78, v78
	v_add_f32_e32 v96, v74, v96
	v_exp_f32_e32 v79, v79
	v_add_f32_e32 v96, v75, v96
	v_add_f32_e32 v96, v76, v96
	v_add_f32_e32 v96, v77, v96
	v_add_f32_e32 v96, v78, v96
	v_add_f32_e32 v96, v79, v96
	v_add_f32_e32 v96, v97, v96
	v_cvt_pk_bf16_f32 v64, v64, v65
	v_cvt_pk_bf16_f32 v65, v66, v67
	v_cvt_pk_bf16_f32 v66, v68, v69
	v_cvt_pk_bf16_f32 v67, v70, v71
	v_cvt_pk_bf16_f32 v68, v72, v73
	v_cvt_pk_bf16_f32 v69, v74, v75
	v_cvt_pk_bf16_f32 v70, v76, v77
	v_cvt_pk_bf16_f32 v71, v78, v79
	s_nop 0
	v_permlane32_swap_b32_e32 v64, v66
	v_permlane32_swap_b32_e32 v65, v67
	v_permlane32_swap_b32_e32 v68, v70
	v_permlane32_swap_b32_e32 v69, v71
	s_waitcnt lgkmcnt(0)
	s_setprio 1
	s_cmp_lt_u32 s33, 0x100
	s_cbranch_scc1 .Lstg_d0_m61_13
	s_waitcnt vmcnt(0)
	s_barrier

; #define LAS __attribute__((address_space(3)))
; DI void expsum(f32x16& p, float& l_reg, bf16x8& pa0, bf16x8& pa1) {
; #pragma unroll
;     for (int r = 0; r < 16; ++r) p[r] = __builtin_amdgcn_exp2f(p[r]);
;     float ps = 0.f;
; #pragma unroll
;     for (int r = 0; r < 16; ++r) ps += p[r];
;     l_reg += ps; asm volatile("" : "+v"(l_reg));
;     ...
;     ATT_PK4(p, 0, pa0); ATT_PK4(p, 8, pa1);
;     ...
; }
; DI int v_rd_base(int lane) { return ((lane & 3) << 3) | (((lane >> 2) & 3) << 6) | (((lane >> 4) & 1) << 5) | (((lane >> 5) & 1) << 8); }
; template <int OFF> DI s16x4 tr_read(int vb) { s16x4 r; asm volatile("ds_read_b64_tr_b16 %0, %1 offset:%2" : "=&v"(r) : "v"(vb), "i"(OFF) : "memory"); return r; }
; template <int H> DI void v_reads(s16x4* vf, int vb) {
;     vf[0] = tr_read<v_rd_off(0, 2 * H, 0)>(vb); vf[1] = tr_read<v_rd_off(0, 2 * H, 1)>(vb); vf[2] = tr_read<v_rd_off(0, 2 * H + 1, 0)>(vb); vf[3] = tr_read<v_rd_off(0, 2 * H + 1, 1)>(vb);
;     vf[4] = tr_read<v_rd_off(1, 2 * H, 0)>(vb); vf[5] = tr_read<v_rd_off(1, 2 * H, 1)>(vb); vf[6] = tr_read<v_rd_off(1, 2 * H + 1, 0)>(vb); vf[7] = tr_read<v_rd_off(1, 2 * H + 1, 1)>(vb);
;     vf[8] = tr_read<v_rd_off(2, 2 * H, 0)>(vb); vf[9] = tr_read<v_rd_off(2, 2 * H, 1)>(vb); vf[10] = tr_read<v_rd_off(2, 2 * H + 1, 0)>(vb); vf[11] = tr_read<v_rd_off(2, 2 * H + 1, 1)>(vb);
;     vf[12] = tr_read<v_rd_off(3, 2 * H, 0)>(vb); vf[13] = tr_read<v_rd_off(3, 2 * H, 1)>(vb); vf[14] = tr_read<v_rd_off(3, 2 * H + 1, 0)>(vb); vf[15] = tr_read<v_rd_off(3, 2 * H + 1, 1)>(vb);
; }
; DI void pv_mma(f32x16* o, const s16x4* vf, bf16x8 pa0, bf16x8 pa1) {
;     ...
; #pragma unroll
;     for (int d0 = 0; d0 < 4; ++d0) {
;         o[d0] = __builtin_amdgcn_mfma_f32_32x32x16_bf16(pa0, ATT_PK(vf[4 * d0], vf[4 * d0 + 1]), o[d0], 0, 0, 0);
;         o[d0] = __builtin_amdgcn_mfma_f32_32x32x16_bf16(pa1, ATT_PK(vf[4 * d0 + 2], vf[4 * d0 + 3]), o[d0], 0, 0, 0); }
;     ...
; }
; template <int DQK, int D0A, int D0B> DI void k_reads(bf16x8* kf, const LAS unsigned char* Ks, int half, int r32, int hi) {
; #pragma unroll
;     for (int d0 = D0A; d0 < D0B; ++d0) kf[d0 - D0A] = *(const LAS bf16x8*)(Ks + half * (32 * DQK * 2) + kswz<DQK>(r32, (d0 * 16 + hi * 8) * 2));
; }
; template <int D0A, int D0B> DI void qk_mma(f32x16& p, const bf16x8* kf, const bf16x8* qr) {
; #pragma unroll
;     for (int d0 = D0A; d0 < D0B; ++d0) {
.LBB0_1936:
	ds_read_b128 v[100:103], v107 offset:20480
	ds_read_b128 v[114:117], v108 offset:20480
	ds_read_b128 v[118:121], v109 offset:20480
	ds_read_b128 v[122:125], v110 offset:20480
	v_add_u32_e32 v98, 0x8000, v106
	ds_read_b64_tr_b16 v[132:133], v98 offset:0
	ds_read_b64_tr_b16 v[134:135], v98 offset:0x800
	ds_read_b64_tr_b16 v[136:137], v98 offset:0x1000
	ds_read_b64_tr_b16 v[138:139], v98 offset:0x1800
	ds_read_b64_tr_b16 v[140:141], v98 offset:0x200
	ds_read_b64_tr_b16 v[142:143], v98 offset:0xa00
	ds_read_b64_tr_b16 v[144:145], v98 offset:0x1200
	ds_read_b64_tr_b16 v[146:147], v98 offset:0x1a00
	ds_read_b64_tr_b16 v[148:149], v98 offset:0x400
	ds_read_b64_tr_b16 v[150:151], v98 offset:0xc00
	ds_read_b64_tr_b16 v[152:153], v98 offset:0x1400
	ds_read_b64_tr_b16 v[154:155], v98 offset:0x1c00
	ds_read_b64_tr_b16 v[156:157], v98 offset:0x600
	ds_read_b64_tr_b16 v[158:159], v98 offset:0xe00
	ds_read_b64_tr_b16 v[162:163], v98 offset:0x1600
	ds_read_b64_tr_b16 v[164:165], v98 offset:0x1e00
	s_setprio 2
	v_exp_f32_e32 v64, v64
	v_exp_f32_e32 v65, v65
	v_exp_f32_e32 v66, v66
	v_exp_f32_e32 v67, v67
	v_exp_f32_e32 v68, v68
	v_exp_f32_e32 v69, v69
	v_add_f32_e32 v99, v65, v64
	v_exp_f32_e32 v70, v70
	v_add_f32_e32 v99, v66, v99
	v_exp_f32_e32 v71, v71
	v_add_f32_e32 v99, v67, v99
	v_exp_f32_e32 v72, v72
	v_add_f32_e32 v99, v68, v99
	v_exp_f32_e32 v73, v73
	v_add_f32_e32 v99, v69, v99
	v_exp_f32_e32 v74, v74
	v_add_f32_e32 v99, v70, v99
	v_exp_f32_e32 v75, v75
	v_add_f32_e32 v99, v71, v99
	v_exp_f32_e32 v76, v76
	v_add_f32_e32 v99, v72, v99
	v_exp_f32_e32 v77, v77
	v_add_f32_e32 v99, v73, v99
	v_exp_f32_e32 v78, v78
	v_add_f32_e32 v99, v74, v99
	v_exp_f32_e32 v79, v79
	v_add_f32_e32 v99, v75, v99
	v_add_f32_e32 v99, v76, v99
	v_add_f32_e32 v99, v77, v99
	v_add_f32_e32 v99, v78, v99
	v_add_f32_e32 v99, v79, v99
	v_add_f32_e32 v96, v99, v96
	v_cvt_pk_bf16_f32 v64, v64, v65
	v_cvt_pk_bf16_f32 v65, v66, v67
	v_cvt_pk_bf16_f32 v66, v68, v69
	v_cvt_pk_bf16_f32 v67, v70, v71
	v_cvt_pk_bf16_f32 v68, v72, v73
	v_cvt_pk_bf16_f32 v69, v74, v75
	v_cvt_pk_bf16_f32 v70, v76, v77
	v_cvt_pk_bf16_f32 v71, v78, v79
	s_nop 0
	v_permlane32_swap_b32_e32 v64, v66
	v_permlane32_swap_b32_e32 v65, v67
	v_permlane32_swap_b32_e32 v68, v70
	v_permlane32_swap_b32_e32 v69, v71
	s_waitcnt lgkmcnt(0)
	s_setprio 1
	v_mfma_f32_32x32x16_bf16 v[0:15], v[64:67], v[132:135], v[0:15]
	s_and_b64 vcc, exec, s[2:3]
	v_mfma_f32_32x32x16_bf16 v[48:63], v[64:67], v[140:143], v[48:63]
	v_mfma_f32_32x32x16_bf16 v[32:47], v[64:67], v[148:151], v[32:47]
	v_mfma_f32_32x32x16_bf16 v[16:31], v[64:67], v[156:159], v[16:31]
	v_mfma_f32_32x32x16_bf16 v[0:15], v[68:71], v[136:139], v[0:15]
	v_mfma_f32_32x32x16_bf16 v[48:63], v[68:71], v[144:147], v[48:63]
	v_mfma_f32_32x32x16_bf16 v[32:47], v[68:71], v[152:155], v[32:47]
	v_mfma_f32_32x32x16_bf16 v[16:31], v[68:71], v[162:165], v[16:31]
	s_waitcnt lgkmcnt(0)
	v_mfma_f32_32x32x16_bf16 v[64:79], v[100:103], v[92:95], 0
	v_mfma_f32_32x32x16_bf16 v[64:79], v[114:117], v[88:91], v[64:79]
	v_mfma_f32_32x32x16_bf16 v[64:79], v[118:121], v[84:87], v[64:79]
	v_mfma_f32_32x32x16_bf16 v[64:79], v[122:125], v[80:83], v[64:79]
	s_setprio 0
	s_cbranch_vccnz .LBB0_1938
	v_add3_u32 v97, s88, v97, v130
	v_add_u32_e32 v118, 0x408, v97
	v_add_u32_e32 v120, 0x420, v97
	v_add_u32_e32 v122, 0x428, v97
	v_add_u32_e32 v100, 0x440, v97
	v_add_u32_e32 v102, 0x448, v97
	v_add_u32_e32 v104, 0x460, v97
	v_add_u32_e32 v99, 0x400, v97
	v_add_u32_e32 v97, 0x468, v97
	ds_read2_b32 v[100:101], v100 offset1:1
	ds_read2_b32 v[102:103], v102 offset1:1
	ds_read2_b32 v[104:105], v104 offset1:1
	ds_read2_b32 v[114:115], v97 offset1:1
	ds_read2_b32 v[116:117], v99 offset1:1
	ds_read2_b32 v[118:119], v118 offset1:1
	ds_read2_b32 v[120:121], v120 offset1:1
	ds_read2_b32 v[122:123], v122 offset1:1
	s_waitcnt lgkmcnt(0)
	v_pk_add_f32 v[78:79], v[78:79], v[114:115]
	v_pk_add_f32 v[76:77], v[76:77], v[104:105]
	v_pk_add_f32 v[74:75], v[74:75], v[102:103]
	v_pk_add_f32 v[72:73], v[72:73], v[100:101]
	v_pk_add_f32 v[70:71], v[70:71], v[122:123]
	v_pk_add_f32 v[68:69], v[68:69], v[120:121]
	v_pk_add_f32 v[66:67], v[66:67], v[118:119]
	v_pk_add_f32 v[64:65], v[64:65], v[116:117]
.LBB0_1938:
	ds_read_b128 v[100:103], v107 offset:24576
	ds_read_b128 v[114:117], v108 offset:24576
	ds_read_b128 v[118:121], v109 offset:24576
	ds_read_b128 v[122:125], v110 offset:24576
	ds_read_b64_tr_b16 v[132:133], v98 offset:0x2000
	ds_read_b64_tr_b16 v[134:135], v98 offset:0x2800
	ds_read_b64_tr_b16 v[136:137], v98 offset:0x3000
	ds_read_b64_tr_b16 v[138:139], v98 offset:0x3800
	ds_read_b64_tr_b16 v[140:141], v98 offset:0x2200
	ds_read_b64_tr_b16 v[142:143], v98 offset:0x2a00
	ds_read_b64_tr_b16 v[144:145], v98 offset:0x3200
	ds_read_b64_tr_b16 v[146:147], v98 offset:0x3a00
	ds_read_b64_tr_b16 v[148:149], v98 offset:0x2400
	ds_read_b64_tr_b16 v[150:151], v98 offset:0x2c00
	ds_read_b64_tr_b16 v[152:153], v98 offset:0x3400
	ds_read_b64_tr_b16 v[154:155], v98 offset:0x3c00
	ds_read_b64_tr_b16 v[156:157], v98 offset:0x2600
	ds_read_b64_tr_b16 v[158:159], v98 offset:0x2e00
	ds_read_b64_tr_b16 v[162:163], v98 offset:0x3600
	ds_read_b64_tr_b16 v[164:165], v98 offset:0x3e00
	s_nop 6
	s_setprio 2
	v_exp_f32_e32 v64, v64
	v_exp_f32_e32 v65, v65
	v_exp_f32_e32 v66, v66
	v_exp_f32_e32 v67, v67
	v_exp_f32_e32 v68, v68
	v_exp_f32_e32 v69, v69
	v_add_f32_e32 v97, v65, v64
	v_exp_f32_e32 v70, v70
	v_add_f32_e32 v97, v66, v97
	v_exp_f32_e32 v71, v71
	v_add_f32_e32 v97, v67, v97
	v_exp_f32_e32 v72, v72
	v_add_f32_e32 v97, v68, v97
	v_exp_f32_e32 v73, v73
	v_add_f32_e32 v97, v69, v97
	v_exp_f32_e32 v74, v74
	v_add_f32_e32 v97, v70, v97
	v_exp_f32_e32 v75, v75
	v_add_f32_e32 v97, v71, v97
	v_exp_f32_e32 v76, v76
	v_add_f32_e32 v97, v72, v97
	v_exp_f32_e32 v77, v77
	v_add_f32_e32 v97, v73, v97
	v_exp_f32_e32 v78, v78
	v_add_f32_e32 v97, v74, v97
	v_exp_f32_e32 v79, v79
	v_add_f32_e32 v97, v75, v97
	v_add_f32_e32 v97, v76, v97
	v_add_f32_e32 v97, v77, v97
	v_add_f32_e32 v97, v78, v97
	v_add_f32_e32 v97, v79, v97
	v_add_f32_e32 v96, v96, v97
	v_cvt_pk_bf16_f32 v64, v64, v65
	v_cvt_pk_bf16_f32 v65, v66, v67
	v_cvt_pk_bf16_f32 v66, v68, v69
	v_cvt_pk_bf16_f32 v67, v70, v71
	v_cvt_pk_bf16_f32 v68, v72, v73
	v_cvt_pk_bf16_f32 v69, v74, v75
	v_cvt_pk_bf16_f32 v70, v76, v77
	v_cvt_pk_bf16_f32 v71, v78, v79
	s_nop 0
	v_permlane32_swap_b32_e32 v64, v66
	v_permlane32_swap_b32_e32 v65, v67
	v_permlane32_swap_b32_e32 v68, v70
	v_permlane32_swap_b32_e32 v69, v71
	s_waitcnt lgkmcnt(0)
	s_setprio 1
	s_cmp_lt_u32 s33, 0x100
	s_cbranch_scc1 .Lstg_d0_m62_15
	s_waitcnt vmcnt(0)
	s_barrier

; #define LAS __attribute__((address_space(3)))
; DI void expsum(f32x16& p, float& l_reg, bf16x8& pa0, bf16x8& pa1) {
; #pragma unroll
;     for (int r = 0; r < 16; ++r) p[r] = __builtin_amdgcn_exp2f(p[r]);
;     float ps = 0.f;
; #pragma unroll
;     for (int r = 0; r < 16; ++r) ps += p[r];
;     l_reg += ps; asm volatile("" : "+v"(l_reg));
;     ...
;     ATT_PK4(p, 0, pa0); ATT_PK4(p, 8, pa1);
;     ...
; }
; DI int v_rd_base(int lane) { return ((lane & 3) << 3) | (((lane >> 2) & 3) << 6) | (((lane >> 4) & 1) << 5) | (((lane >> 5) & 1) << 8); }
; template <int OFF> DI s16x4 tr_read(int vb) { s16x4 r; asm volatile("ds_read_b64_tr_b16 %0, %1 offset:%2" : "=&v"(r) : "v"(vb), "i"(OFF) : "memory"); return r; }
; template <int H> DI void v_reads(s16x4* vf, int vb) {
;     vf[0] = tr_read<v_rd_off(0, 2 * H, 0)>(vb); vf[1] = tr_read<v_rd_off(0, 2 * H, 1)>(vb); vf[2] = tr_read<v_rd_off(0, 2 * H + 1, 0)>(vb); vf[3] = tr_read<v_rd_off(0, 2 * H + 1, 1)>(vb);
;     vf[4] = tr_read<v_rd_off(1, 2 * H, 0)>(vb); vf[5] = tr_read<v_rd_off(1, 2 * H, 1)>(vb); vf[6] = tr_read<v_rd_off(1, 2 * H + 1, 0)>(vb); vf[7] = tr_read<v_rd_off(1, 2 * H + 1, 1)>(vb);
;     vf[8] = tr_read<v_rd_off(2, 2 * H, 0)>(vb); vf[9] = tr_read<v_rd_off(2, 2 * H, 1)>(vb); vf[10] = tr_read<v_rd_off(2, 2 * H + 1, 0)>(vb); vf[11] = tr_read<v_rd_off(2, 2 * H + 1, 1)>(vb);
;     vf[12] = tr_read<v_rd_off(3, 2 * H, 0)>(vb); vf[13] = tr_read<v_rd_off(3, 2 * H, 1)>(vb); vf[14] = tr_read<v_rd_off(3, 2 * H + 1, 0)>(vb); vf[15] = tr_read<v_rd_off(3, 2 * H + 1, 1)>(vb);
; }
; DI void pv_mma(f32x16* o, const s16x4* vf, bf16x8 pa0, bf16x8 pa1) {
;     ...
; #pragma unroll
;     for (int d0 = 0; d0 < 4; ++d0) {
;         o[d0] = __builtin_amdgcn_mfma_f32_32x32x16_bf16(pa0, ATT_PK(vf[4 * d0], vf[4 * d0 + 1]), o[d0], 0, 0, 0);
;         o[d0] = __builtin_amdgcn_mfma_f32_32x32x16_bf16(pa1, ATT_PK(vf[4 * d0 + 2], vf[4 * d0 + 3]), o[d0], 0, 0, 0); }
;     ...
; }
; template <int DQK, int D0A, int D0B> DI void k_reads(bf16x8* kf, const LAS unsigned char* Ks, int half, int r32, int hi) {
; #pragma unroll
;     for (int d0 = D0A; d0 < D0B; ++d0) kf[d0 - D0A] = *(const LAS bf16x8*)(Ks + half * (32 * DQK * 2) + kswz<DQK>(r32, (d0 * 16 + hi * 8) * 2));
; }
; template <int D0A, int D0B> DI void qk_mma(f32x16& p, const bf16x8* kf, const bf16x8* qr) {
; #pragma unroll
;     for (int d0 = D0A; d0 < D0B; ++d0) {
.LBB0_1942:
	ds_read_b128 v[98:101], v107 offset:28672
	ds_read_b128 v[102:105], v108 offset:28672
	ds_read_b128 v[112:115], v109 offset:28672
	ds_read_b128 v[108:111], v110 offset:28672
	ds_read_b64_tr_b16 v[116:117], v106 offset:0
	ds_read_b64_tr_b16 v[118:119], v106 offset:0x800
	ds_read_b64_tr_b16 v[120:121], v106 offset:0x1000
	ds_read_b64_tr_b16 v[122:123], v106 offset:0x1800
	ds_read_b64_tr_b16 v[124:125], v106 offset:0x200
	ds_read_b64_tr_b16 v[126:127], v106 offset:0xa00
	ds_read_b64_tr_b16 v[132:133], v106 offset:0x1200
	ds_read_b64_tr_b16 v[134:135], v106 offset:0x1a00
	ds_read_b64_tr_b16 v[136:137], v106 offset:0x400
	ds_read_b64_tr_b16 v[138:139], v106 offset:0xc00
	ds_read_b64_tr_b16 v[140:141], v106 offset:0x1400
	ds_read_b64_tr_b16 v[142:143], v106 offset:0x1c00
	ds_read_b64_tr_b16 v[144:145], v106 offset:0x600
	ds_read_b64_tr_b16 v[146:147], v106 offset:0xe00
	ds_read_b64_tr_b16 v[148:149], v106 offset:0x1600
	ds_read_b64_tr_b16 v[150:151], v106 offset:0x1e00
	s_setprio 2
	v_exp_f32_e32 v64, v64
	v_exp_f32_e32 v65, v65
	v_exp_f32_e32 v66, v66
	v_exp_f32_e32 v67, v67
	v_exp_f32_e32 v68, v68
	v_exp_f32_e32 v69, v69
	v_add_f32_e32 v107, v65, v64
	v_exp_f32_e32 v70, v70
	v_add_f32_e32 v107, v66, v107
	v_exp_f32_e32 v71, v71
	v_add_f32_e32 v107, v67, v107
	v_exp_f32_e32 v72, v72
	v_add_f32_e32 v107, v68, v107
	v_exp_f32_e32 v73, v73
	v_add_f32_e32 v107, v69, v107
	v_exp_f32_e32 v74, v74
	v_add_f32_e32 v107, v70, v107
	v_exp_f32_e32 v75, v75
	v_add_f32_e32 v107, v71, v107
	v_exp_f32_e32 v76, v76
	v_add_f32_e32 v107, v72, v107
	v_exp_f32_e32 v77, v77
	v_add_f32_e32 v107, v73, v107
	v_exp_f32_e32 v78, v78
	v_add_f32_e32 v107, v74, v107
	v_exp_f32_e32 v79, v79
	v_add_f32_e32 v107, v75, v107
	v_add_f32_e32 v107, v76, v107
	v_add_f32_e32 v107, v77, v107
	v_add_f32_e32 v107, v78, v107
	v_add_f32_e32 v107, v79, v107
	v_add_f32_e32 v96, v107, v96
	v_cvt_pk_bf16_f32 v64, v64, v65
	v_cvt_pk_bf16_f32 v65, v66, v67
	v_cvt_pk_bf16_f32 v66, v68, v69
	v_cvt_pk_bf16_f32 v67, v70, v71
	v_cvt_pk_bf16_f32 v68, v72, v73
	v_cvt_pk_bf16_f32 v69, v74, v75
	v_cvt_pk_bf16_f32 v70, v76, v77
	v_cvt_pk_bf16_f32 v71, v78, v79
	s_nop 0
	v_permlane32_swap_b32_e32 v64, v66
	v_permlane32_swap_b32_e32 v65, v67
	v_permlane32_swap_b32_e32 v68, v70
	v_permlane32_swap_b32_e32 v69, v71
	s_waitcnt lgkmcnt(0)
	s_setprio 1
	v_mfma_f32_32x32x16_bf16 v[0:15], v[64:67], v[116:119], v[0:15]
	s_and_b64 vcc, exec, s[2:3]
	v_mfma_f32_32x32x16_bf16 v[48:63], v[64:67], v[124:127], v[48:63]
	v_mfma_f32_32x32x16_bf16 v[32:47], v[64:67], v[136:139], v[32:47]
	v_mfma_f32_32x32x16_bf16 v[16:31], v[64:67], v[144:147], v[16:31]
	v_mfma_f32_32x32x16_bf16 v[0:15], v[68:71], v[120:123], v[0:15]
	v_mfma_f32_32x32x16_bf16 v[48:63], v[68:71], v[132:135], v[48:63]
	v_mfma_f32_32x32x16_bf16 v[32:47], v[68:71], v[140:143], v[32:47]
	v_mfma_f32_32x32x16_bf16 v[16:31], v[68:71], v[148:151], v[16:31]
	s_waitcnt lgkmcnt(0)
	v_mfma_f32_32x32x16_bf16 v[64:79], v[98:101], v[92:95], 0
	v_mfma_f32_32x32x16_bf16 v[64:79], v[102:105], v[88:91], v[64:79]
	v_mfma_f32_32x32x16_bf16 v[64:79], v[112:115], v[84:87], v[64:79]
	v_mfma_f32_32x32x16_bf16 v[64:79], v[108:111], v[80:83], v[64:79]
	s_setprio 0
	s_cbranch_vccnz .LBB0_1944
	v_add3_u32 v80, s88, v97, v130
	v_add_u32_e32 v88, 0x400, v80
	v_add_u32_e32 v90, 0x408, v80
	v_add_u32_e32 v92, 0x420, v80
	v_add_u32_e32 v94, 0x428, v80
	v_add_u32_e32 v81, 0x440, v80
	v_add_u32_e32 v82, 0x448, v80
	v_add_u32_e32 v84, 0x460, v80
	v_add_u32_e32 v86, 0x468, v80
	ds_read2_b32 v[80:81], v81 offset1:1
	ds_read2_b32 v[82:83], v82 offset1:1
	ds_read2_b32 v[84:85], v84 offset1:1
	ds_read2_b32 v[86:87], v86 offset1:1
	ds_read2_b32 v[88:89], v88 offset1:1
	ds_read2_b32 v[90:91], v90 offset1:1
	ds_read2_b32 v[92:93], v92 offset1:1
	ds_read2_b32 v[94:95], v94 offset1:1
	s_waitcnt lgkmcnt(0)
	v_pk_add_f32 v[78:79], v[78:79], v[86:87]
	v_pk_add_f32 v[76:77], v[76:77], v[84:85]
	v_pk_add_f32 v[74:75], v[74:75], v[82:83]
	v_pk_add_f32 v[72:73], v[72:73], v[80:81]
	v_pk_add_f32 v[70:71], v[70:71], v[94:95]
	v_pk_add_f32 v[68:69], v[68:69], v[92:93]
	v_pk_add_f32 v[66:67], v[66:67], v[90:91]
	v_pk_add_f32 v[64:65], v[64:65], v[88:89]
.LBB0_1944:
	s_lshl_b32 s0, s54, 2
	s_add_i32 s0, s0, 0
	s_add_i32 s0, s0, 0x24000
	ds_read_b64_tr_b16 v[80:81], v106 offset:0x2000
	ds_read_b64_tr_b16 v[82:83], v106 offset:0x2800
	ds_read_b64_tr_b16 v[84:85], v106 offset:0x3000
	ds_read_b64_tr_b16 v[86:87], v106 offset:0x3800
	ds_read_b64_tr_b16 v[88:89], v106 offset:0x2200
	ds_read_b64_tr_b16 v[90:91], v106 offset:0x2a00
	ds_read_b64_tr_b16 v[92:93], v106 offset:0x3200
	ds_read_b64_tr_b16 v[94:95], v106 offset:0x3a00
	ds_read_b64_tr_b16 v[98:99], v106 offset:0x2400
	ds_read_b64_tr_b16 v[100:101], v106 offset:0x2c00
	ds_read_b64_tr_b16 v[102:103], v106 offset:0x3400
	ds_read_b64_tr_b16 v[104:105], v106 offset:0x3c00
	ds_read_b64_tr_b16 v[108:109], v106 offset:0x2600
	ds_read_b64_tr_b16 v[110:111], v106 offset:0x2e00
	ds_read_b64_tr_b16 v[112:113], v106 offset:0x3600
	ds_read_b64_tr_b16 v[114:115], v106 offset:0x3e00
	s_nop 7
	s_setprio 2
	v_exp_f32_e32 v97, v64
	v_exp_f32_e32 v65, v65
	v_exp_f32_e32 v106, v66
	v_exp_f32_e32 v67, v67
	v_exp_f32_e32 v68, v68
	v_exp_f32_e32 v69, v69
	v_add_f32_e32 v64, v65, v97
	v_exp_f32_e32 v70, v70
	v_add_f32_e32 v64, v106, v64
	v_exp_f32_e32 v71, v71
	v_add_f32_e32 v64, v67, v64
	v_exp_f32_e32 v72, v72
	v_add_f32_e32 v64, v68, v64
	v_exp_f32_e32 v73, v73
	v_add_f32_e32 v64, v69, v64
	v_exp_f32_e32 v74, v74
	v_add_f32_e32 v64, v70, v64
	v_exp_f32_e32 v75, v75
	v_add_f32_e32 v64, v71, v64
	v_exp_f32_e32 v76, v76
	v_add_f32_e32 v64, v72, v64
	v_exp_f32_e32 v77, v77
	v_add_f32_e32 v64, v73, v64
	v_exp_f32_e32 v78, v78
	v_add_f32_e32 v64, v74, v64
	v_exp_f32_e32 v79, v79
	v_add_f32_e32 v64, v75, v64
	v_add_f32_e32 v64, v76, v64
	v_add_f32_e32 v64, v77, v64
	v_add_f32_e32 v64, v78, v64
	v_add_f32_e32 v64, v79, v64
	v_add_f32_e32 v64, v96, v64
	v_cvt_pk_bf16_f32 v66, v97, v65
	v_cvt_pk_bf16_f32 v67, v106, v67
	v_cvt_pk_bf16_f32 v68, v68, v69
	v_cvt_pk_bf16_f32 v69, v70, v71
	v_cvt_pk_bf16_f32 v70, v72, v73
	v_cvt_pk_bf16_f32 v71, v74, v75
	v_cvt_pk_bf16_f32 v72, v76, v77
	v_cvt_pk_bf16_f32 v73, v78, v79
	s_nop 0
	v_permlane32_swap_b32_e32 v66, v68
	v_permlane32_swap_b32_e32 v67, v69
	v_permlane32_swap_b32_e32 v70, v72
	v_permlane32_swap_b32_e32 v71, v73
	s_waitcnt lgkmcnt(0)
; template <int TAG = 0> DI int fresh_tid(int wv) { int l; asm volatile("v_mbcnt_lo_u32_b32 %0, -1, 0\n\tv_mbcnt_hi_u32_b32 %0, -1, %0 ; site %1" : "=v"(l) : "n"(TAG)); return wv * 64 + l; }
; DI unsigned short f2bf(float x) { unsigned u = __float_as_uint(x); u += 0x7fffu + ((u >> 16) & 1u); return (unsigned short)(u >> 16); }
; DI int crow(int r, int hi) { return (r & 3) + 8 * (r >> 2) + 4 * hi; }
; DI float swap_sum(float v) { auto rr = __builtin_amdgcn_permlane32_swap(__float_as_uint(v), __float_as_uint(v), false, false); return __uint_as_float(rr[0]) + __uint_as_float(rr[1]); }
; DI void pv_mma(f32x16* o, const s16x4* vf, bf16x8 pa0, bf16x8 pa1) {
;     ...
; #pragma unroll
;     for (int d0 = 0; d0 < 4; ++d0) {
;         o[d0] = __builtin_amdgcn_mfma_f32_32x32x16_bf16(pa0, ATT_PK(vf[4 * d0], vf[4 * d0 + 1]), o[d0], 0, 0, 0);
;         o[d0] = __builtin_amdgcn_mfma_f32_32x32x16_bf16(pa1, ATT_PK(vf[4 * d0 + 2], vf[4 * d0 + 3]), o[d0], 0, 0, 0); }
;     ...
; }
; template <int DQK, int MODE, int LDQ, int LDK, int LDV> ...
;     ...
;     l_reg = swap_sum(l_reg);
;     { const int lane2 = fresh_tid<110 + MODE>(wv) & 63, r32 = lane2 & 31, hi = lane2 >> 5;
;     if (hi == 0) li_l[r32] = l_reg;
;     asm volatile("s_waitcnt lgkmcnt(0)" ::: "memory");
;     float s0v[MODE == 2 ? 16 : 1][4];
;     if constexpr (MODE == 2) {
; #pragma unroll
;         for (int r = 0; r < 16; ++r)
; #pragma unroll
;             for (int d0 = 0; d0 < 4; ++d0) s0v[r][d0] = S0[(size_t)(wid * 32 + crow(r, hi)) * 512 + d0 * 32 + r32];
;     }
; #pragma unroll
;     for (int r = 0; r < 16; ++r) { const int orow = wid * 32 + crow(r, hi); const float rl = __builtin_amdgcn_rcpf(li_l[crow(r, hi)]);
;         if constexpr (MODE == 0) {
; #pragma unroll
;             for (int d0 = 0; d0 < 4; ++d0) AOb[(size_t)orow * 1024 + d0 * 32 + r32] = f2bf(o[d0][r] * rl);
;         } else if constexpr (MODE == 1) {
; #pragma unroll
;             for (int d0 = 0; d0 < 4; ++d0) S0[(size_t)orow * 512 + d0 * 32 + r32] = o[d0][r] * rl;
	s_setprio 1
	v_mfma_f32_32x32x16_bf16 v[0:15], v[66:69], v[80:83], v[0:15]
	v_mfma_f32_32x32x16_bf16 v[48:63], v[66:69], v[88:91], v[48:63]
	v_mfma_f32_32x32x16_bf16 v[32:47], v[66:69], v[98:101], v[32:47]
	v_mfma_f32_32x32x16_bf16 v[16:31], v[66:69], v[108:111], v[16:31]
	v_mfma_f32_32x32x16_bf16 v[0:15], v[70:73], v[84:87], v[0:15]
	v_mfma_f32_32x32x16_bf16 v[48:63], v[70:73], v[92:95], v[48:63]
	v_mfma_f32_32x32x16_bf16 v[32:47], v[70:73], v[102:105], v[32:47]
	v_mfma_f32_32x32x16_bf16 v[16:31], v[70:73], v[112:115], v[16:31]
	s_setprio 0
	v_mbcnt_lo_u32_b32 v66, -1, 0
	v_mbcnt_hi_u32_b32 v66, -1, v66
	v_mov_b32_e32 v67, v64
	v_and_b32_e32 v65, 31, v66
	v_bfe_u32 v66, v66, 5, 1
	v_permlane32_swap_b32_e32 v64, v67
	v_cmp_eq_u32_e32 vcc, 0, v66
	s_and_saveexec_b64 s[2:3], vcc
	v_lshl_add_u32 v68, v65, 2, s0
	v_add_f32_e32 v64, v64, v67
	ds_write_b32 v68, v64
	s_or_b64 exec, exec, s[2:3]
	s_waitcnt lgkmcnt(0)
	v_lshl_add_u32 v68, v66, 4, s0
	ds_read_b128 v[70:73], v68
	ds_read_b128 v[74:77], v68 offset:32
	s_lshl_b64 s[58:59], s[40:41], 11
	v_readlane_b32 s1, v255, 2
	s_add_u32 s1, s1, s58
	v_readlane_b32 s2, v255, 0
	s_addc_u32 s2, s2, s59
	s_lshl_b32 s3, s87, 2
	s_waitcnt lgkmcnt(0)
	v_rcp_f32_e32 v69, v70
	s_add_u32 s54, s1, s3
	v_lshl_or_b32 v66, v66, 2, s94
	s_addc_u32 s55, s2, 0
	v_lshlrev_b32_e32 v130, 2, v65
	v_ashrrev_i32_e32 v67, 31, v66
	v_lshl_add_u64 v[64:65], s[54:55], 0, v[130:131]
	v_lshlrev_b64 v[78:79], 11, v[66:67]
	v_lshl_add_u64 v[78:79], v[64:65], 0, v[78:79]
	v_mul_f32_e32 v0, v0, v69
	global_store_dword v[78:79], v0, off
	v_mul_f32_e32 v0, v48, v69
	global_store_dword v[78:79], v0, off offset:128
	v_mul_f32_e32 v0, v32, v69
	global_store_dword v[78:79], v0, off offset:256
	v_mul_f32_e32 v0, v16, v69
	global_store_dword v[78:79], v0, off offset:384
	v_rcp_f32_e32 v0, v71
	v_or_b32_e32 v70, 1, v66
	v_ashrrev_i32_e32 v71, 31, v70
	v_lshlrev_b64 v[70:71], 11, v[70:71]
	v_lshl_add_u64 v[70:71], v[64:65], 0, v[70:71]
	v_mul_f32_e32 v1, v1, v0
	global_store_dword v[70:71], v1, off
	v_mul_f32_e32 v1, v49, v0
	global_store_dword v[70:71], v1, off offset:128
	v_mul_f32_e32 v1, v33, v0
	v_mul_f32_e32 v0, v17, v0
	v_rcp_f32_e32 v16, v72
	global_store_dword v[70:71], v0, off offset:384
	v_or_b32_e32 v0, 2, v66
	global_store_dword v[70:71], v1, off offset:256
	v_ashrrev_i32_e32 v1, 31, v0
	v_lshlrev_b64 v[0:1], 11, v[0:1]
	v_lshl_add_u64 v[0:1], v[64:65], 0, v[0:1]
	v_mul_f32_e32 v2, v2, v16
	global_store_dword v[0:1], v2, off
	v_mul_f32_e32 v2, v50, v16
	global_store_dword v[0:1], v2, off offset:128
	v_mul_f32_e32 v2, v34, v16
	global_store_dword v[0:1], v2, off offset:256
	v_mul_f32_e32 v2, v18, v16
	global_store_dword v[0:1], v2, off offset:384
	v_rcp_f32_e32 v2, v73
	v_or_b32_e32 v0, 3, v66
	v_ashrrev_i32_e32 v1, 31, v0
	v_lshlrev_b64 v[0:1], 11, v[0:1]
	v_lshl_add_u64 v[0:1], v[64:65], 0, v[0:1]
	v_mul_f32_e32 v3, v3, v2
	global_store_dword v[0:1], v3, off
	v_mul_f32_e32 v3, v51, v2
	global_store_dword v[0:1], v3, off offset:128
	v_mul_f32_e32 v3, v35, v2
	v_mul_f32_e32 v2, v19, v2
	global_store_dword v[0:1], v2, off offset:384
	v_rcp_f32_e32 v2, v74
	global_store_dword v[0:1], v3, off offset:256
	v_or_b32_e32 v0, 8, v66
	v_ashrrev_i32_e32 v1, 31, v0
	v_lshlrev_b64 v[0:1], 11, v[0:1]
	v_lshl_add_u64 v[0:1], v[64:65], 0, v[0:1]
	v_mul_f32_e32 v3, v4, v2
	global_store_dword v[0:1], v3, off
	v_mul_f32_e32 v3, v52, v2
	global_store_dword v[0:1], v3, off offset:128
	v_mul_f32_e32 v3, v36, v2
	v_mul_f32_e32 v2, v20, v2
	global_store_dword v[0:1], v2, off offset:384
	v_rcp_f32_e32 v2, v75
	global_store_dword v[0:1], v3, off offset:256
	v_or_b32_e32 v0, 9, v66
	v_ashrrev_i32_e32 v1, 31, v0
	v_lshlrev_b64 v[0:1], 11, v[0:1]
	v_lshl_add_u64 v[0:1], v[64:65], 0, v[0:1]
	v_mul_f32_e32 v3, v5, v2
	global_store_dword v[0:1], v3, off
	v_mul_f32_e32 v3, v53, v2
	global_store_dword v[0:1], v3, off offset:128
	v_mul_f32_e32 v3, v37, v2
	v_mul_f32_e32 v2, v21, v2
	global_store_dword v[0:1], v2, off offset:384
	v_rcp_f32_e32 v2, v76
	global_store_dword v[0:1], v3, off offset:256
	v_or_b32_e32 v0, 10, v66
	v_ashrrev_i32_e32 v1, 31, v0
	v_lshlrev_b64 v[0:1], 11, v[0:1]
	v_lshl_add_u64 v[0:1], v[64:65], 0, v[0:1]
	v_mul_f32_e32 v3, v6, v2
	global_store_dword v[0:1], v3, off
	v_mul_f32_e32 v3, v54, v2
	global_store_dword v[0:1], v3, off offset:128
	v_mul_f32_e32 v3, v38, v2
	v_mul_f32_e32 v2, v22, v2
	v_rcp_f32_e32 v6, v77
	global_store_dword v[0:1], v3, off offset:256
	global_store_dword v[0:1], v2, off offset:384
	v_or_b32_e32 v0, 11, v66
	v_ashrrev_i32_e32 v1, 31, v0
	v_lshlrev_b64 v[0:1], 11, v[0:1]
	v_lshl_add_u64 v[4:5], v[64:65], 0, v[0:1]
	v_mul_f32_e32 v0, v7, v6
	global_store_dword v[4:5], v0, off
	v_mul_f32_e32 v0, v55, v6
	global_store_dword v[4:5], v0, off offset:128
	v_mul_f32_e32 v0, v39, v6
	global_store_dword v[4:5], v0, off offset:256
	ds_read_b128 v[0:3], v68 offset:64
	v_mul_f32_e32 v6, v23, v6
	global_store_dword v[4:5], v6, off offset:384
	ds_read_b128 v[4:7], v68 offset:96
	v_or_b32_e32 v16, 16, v66
	s_waitcnt lgkmcnt(0)
; DI unsigned short f2bf(float x) { unsigned u = __float_as_uint(x); u += 0x7fffu + ((u >> 16) & 1u); return (unsigned short)(u >> 16); }
; DI int crow(int r, int hi) { return (r & 3) + 8 * (r >> 2) + 4 * hi; }
; template <int DQK, int MODE, int LDQ, int LDK, int LDV> ...
;     ...
;     for (int r = 0; r < 16; ++r) { const int orow = wid * 32 + crow(r, hi); const float rl = __builtin_amdgcn_rcpf(li_l[crow(r, hi)]);
;         if constexpr (MODE == 0) {
; #pragma unroll
;             for (int d0 = 0; d0 < 4; ++d0) AOb[(size_t)orow * 1024 + d0 * 32 + r32] = f2bf(o[d0][r] * rl);
;         } else if constexpr (MODE == 1) {
; #pragma unroll
;             for (int d0 = 0; d0 < 4; ++d0) S0[(size_t)orow * 512 + d0 * 32 + r32] = o[d0][r] * rl;
	v_rcp_f32_e32 v0, v0
	v_ashrrev_i32_e32 v17, 31, v16
	v_lshlrev_b64 v[16:17], 11, v[16:17]
	v_lshl_add_u64 v[16:17], v[64:65], 0, v[16:17]
	v_mul_f32_e32 v8, v8, v0
	global_store_dword v[16:17], v8, off
	v_mul_f32_e32 v8, v56, v0
	global_store_dword v[16:17], v8, off offset:128
	v_mul_f32_e32 v8, v40, v0
	global_store_dword v[16:17], v8, off offset:256
	v_mul_f32_e32 v0, v24, v0
	v_rcp_f32_e32 v8, v1
	global_store_dword v[16:17], v0, off offset:384
	v_or_b32_e32 v0, 17, v66
	v_ashrrev_i32_e32 v1, 31, v0
	v_lshlrev_b64 v[0:1], 11, v[0:1]
	v_lshl_add_u64 v[0:1], v[64:65], 0, v[0:1]
	v_mul_f32_e32 v9, v9, v8
	global_store_dword v[0:1], v9, off
	v_mul_f32_e32 v9, v57, v8
	global_store_dword v[0:1], v9, off offset:128
	v_mul_f32_e32 v9, v41, v8
	v_mul_f32_e32 v8, v25, v8
	v_rcp_f32_e32 v2, v2
	global_store_dword v[0:1], v9, off offset:256
	global_store_dword v[0:1], v8, off offset:384
	v_or_b32_e32 v0, 18, v66
	v_ashrrev_i32_e32 v1, 31, v0
	v_lshlrev_b64 v[0:1], 11, v[0:1]
	v_lshl_add_u64 v[0:1], v[64:65], 0, v[0:1]
	v_mul_f32_e32 v8, v10, v2
	global_store_dword v[0:1], v8, off
	v_mul_f32_e32 v8, v58, v2
	global_store_dword v[0:1], v8, off offset:128
	v_mul_f32_e32 v8, v42, v2
	v_mul_f32_e32 v2, v26, v2
	global_store_dword v[0:1], v2, off offset:384
	v_rcp_f32_e32 v2, v3
	global_store_dword v[0:1], v8, off offset:256
	v_or_b32_e32 v0, 19, v66
	v_ashrrev_i32_e32 v1, 31, v0
	v_lshlrev_b64 v[0:1], 11, v[0:1]
	v_lshl_add_u64 v[0:1], v[64:65], 0, v[0:1]
	v_mul_f32_e32 v3, v11, v2
	global_store_dword v[0:1], v3, off
	v_mul_f32_e32 v3, v59, v2
	global_store_dword v[0:1], v3, off offset:128
	v_mul_f32_e32 v3, v43, v2
	v_mul_f32_e32 v2, v27, v2
	global_store_dword v[0:1], v2, off offset:384
	v_rcp_f32_e32 v2, v4
	global_store_dword v[0:1], v3, off offset:256
	v_or_b32_e32 v0, 24, v66
	v_ashrrev_i32_e32 v1, 31, v0
	v_lshlrev_b64 v[0:1], 11, v[0:1]
	v_lshl_add_u64 v[0:1], v[64:65], 0, v[0:1]
	v_mul_f32_e32 v3, v12, v2
	global_store_dword v[0:1], v3, off
	v_mul_f32_e32 v3, v60, v2
	global_store_dword v[0:1], v3, off offset:128
	v_mul_f32_e32 v3, v44, v2
	v_mul_f32_e32 v2, v28, v2
	global_store_dword v[0:1], v2, off offset:384
	v_rcp_f32_e32 v2, v5
	global_store_dword v[0:1], v3, off offset:256
	v_or_b32_e32 v0, 25, v66
	v_ashrrev_i32_e32 v1, 31, v0
	v_lshlrev_b64 v[0:1], 11, v[0:1]
	v_lshl_add_u64 v[0:1], v[64:65], 0, v[0:1]
	v_mul_f32_e32 v3, v13, v2
	global_store_dword v[0:1], v3, off
	v_mul_f32_e32 v3, v61, v2
	global_store_dword v[0:1], v3, off offset:128
	v_mul_f32_e32 v3, v45, v2
	v_mul_f32_e32 v2, v29, v2
	global_store_dword v[0:1], v2, off offset:384
	v_rcp_f32_e32 v2, v6
	global_store_dword v[0:1], v3, off offset:256
	v_or_b32_e32 v0, 26, v66
	v_ashrrev_i32_e32 v1, 31, v0
	v_lshlrev_b64 v[0:1], 11, v[0:1]
	v_lshl_add_u64 v[0:1], v[64:65], 0, v[0:1]
	v_mul_f32_e32 v3, v14, v2
	global_store_dword v[0:1], v3, off
	v_mul_f32_e32 v3, v62, v2
	global_store_dword v[0:1], v3, off offset:128
	v_mul_f32_e32 v3, v46, v2
	v_mul_f32_e32 v2, v30, v2
	global_store_dword v[0:1], v2, off offset:384
	v_rcp_f32_e32 v2, v7
	global_store_dword v[0:1], v3, off offset:256
	v_or_b32_e32 v0, 27, v66
	v_ashrrev_i32_e32 v1, 31, v0
	v_lshlrev_b64 v[0:1], 11, v[0:1]
	v_lshl_add_u64 v[0:1], v[64:65], 0, v[0:1]
	v_mul_f32_e32 v3, v15, v2
	global_store_dword v[0:1], v3, off
	v_mul_f32_e32 v3, v63, v2
	global_store_dword v[0:1], v3, off offset:128
	v_mul_f32_e32 v3, v47, v2
	v_mul_f32_e32 v2, v31, v2
	global_store_dword v[0:1], v3, off offset:256
	global_store_dword v[0:1], v2, off offset:384
	s_waitcnt vmcnt(0)
	s_barrier
; DI float bf2f(unsigned short h) { return __uint_as_float((unsigned)h << 16); }
; template <int DQK, int MODE, int LDQ, int LDK, int LDV> ...
;     ...
;     int kgo[NKP], vgo[2];
; #pragma unroll
;     for (int i = 0; i < NKP; ++i) { const int L = (wid + 8 * i) * 64 + lane, row = L / CPR, slot = L % CPR, cc = (slot & ~7) | ((slot & 7) ^ ((row >> 1) & 7)); kgo[i] = row * LDK + cc * 8; }
; #pragma unroll
;     for (int i = 0; i < 2; ++i) { const int L = (2 * wid + i) * 64 + lane, st = L >> 5, w5 = L & 31, kk = (st >> 2) * 8 + (w5 >> 2), c = (st & 3) * 32 + (w5 & 3) * 8;
;         const int k = (kk & ~0xC) | ((kk & 4) << 1) | ((kk & 8) >> 1); vgo[i] = k * LDV + c; }
;     ...
;     ATT_DMA_K(0); ATT_DMA_K(1); ATT_DMA_V(0, 0); ATT_DMA_K(2); ATT_DMA_V(1, 1);
;     bf16x8 qr[ND0];
;     { const bf16_t* Qw = Qb + (size_t)(wid * 32 + r32) * LDQ + hi * 8;
; #pragma unroll
;       for (int d0 = 0; d0 < ND0; ++d0) qr[d0] = *(const bf16x8*)(Qw + d0 * 16);
;       if constexpr (MODE == 0) {
;           float ss = 0.f;
; #pragma unroll
;           for (int d0 = 0; d0 < ND0; ++d0)
; #pragma unroll
;               for (int j = 0; j < 8; ++j) { const float f = bf2f((unsigned short)qr[d0][j]); ss += f * f; }
;           ss = swap_sum(ss);
;           const float rstd = rsqrtf(ss * (1.f / DQK) + EPS) * C;
; #pragma unroll
;           for (int d0 = 0; d0 < ND0; ++d0) { const float* g = gq + d0 * 16 + hi * 8;
;               { float f[8]; _Pragma("unroll") for (int j = 0; j < 8; ++j) f[j] = bf2f((unsigned short)qr[d0][j]) * rstd * g[j];
;                 u32x4 w = {cvtpk(f[0], f[1]), cvtpk(f[2], f[3]), cvtpk(f[4], f[5]), cvtpk(f[6], f[7])}; qr[d0] = __builtin_bit_cast(bf16x8, w); asm volatile("" ::: "memory"); } }
;       } }
;     const int qlo = q0 + wid * 32, qpos = qlo + r32;
;     const int tL = MODE == 0 ? 0 : (qlo >= 191 ? (qlo - 127) >> 6 : 0), tR = MODE == 0 ? NT : min(NT, (qlo + 222) >> 6);
;     float fL = 1.f, fR = 1.f; if constexpr (MODE != 0) { fL = __builtin_amdgcn_exp2f(bt[0]); fR = __builtin_amdgcn_exp2f(-bt[448]); }
;     ...
;     const int vbase = (int)(unsigned)(size_t)lds + V_OFF + v_rd_base(lane);
;     ...
;     constexpr int NDA = ND0 > 6 ? 6 : ND0;
;     ...
;     f32x16 pA, pB; bf16x8 pa0, pa1;
;     int v0 = 0, v1 = 1, v2 = 2;
;     ATT_TOP(NKP + 2);
;     { bf16x8 kf[NDA]; k_reads<DQK, 0, NDA>(kf, lds, 0, r32, hi); ATT_LGKM0(); qk_mma<0, NDA>(pA, kf, qr);
	v_mbcnt_lo_u32_b32 v7, -1, 0
	v_mbcnt_hi_u32_b32 v7, -1, v7
	s_mov_b64 s[4:5], 0x880
	v_add_u32_e32 v0, s33, v7
	v_bfe_u32 v4, v0, 2, 2
	v_readfirstlane_b32 s0, v0
	s_ashr_i32 s2, s0, 31
	s_ashr_i32 s1, s0, 6
	v_mov_b32_e32 v1, s0
	v_bfi_b32 v1, s63, v1, v7
	s_lshr_b32 s2, s2, 29
	v_add_u32_e32 v3, s2, v1
	s_lshl_b32 s2, s1, 7
	v_ashrrev_i32_e32 v9, 3, v3
	v_and_b32_e32 v3, 0x1ffffff8, v3
	s_ashr_i32 s3, s2, 4
	v_lshrrev_b32_e32 v0, 1, v0
	v_sub_u32_e32 v1, v1, v3
	v_lshrrev_b32_e32 v3, 1, v9
	v_lshlrev_b32_e32 v18, 3, v7
	s_and_b32 s2, s3, -16
	v_and_b32_e32 v6, 8, v0
	s_lshr_b32 s3, s3, 1
	v_bitop3_b32 v1, v3, v1, 7 bitop3:0x6c
	v_and_b32_e32 v3, 32, v7
	v_and_b32_e32 v5, 24, v18
	s_and_b32 s3, s3, 4
	v_or3_b32 v0, v6, v4, s2
	v_or_b32_e32 v10, v3, v5
	v_or_b32_e32 v0, s3, v0
	v_lshl_or_b32 v96, v0, 11, v10
	v_lshlrev_b32_e32 v0, 11, v9
	v_lshl_add_u32 v0, v1, 3, v0
	v_ashrrev_i32_e32 v1, 31, v0
	v_lshlrev_b64 v[10:11], 1, v[0:1]
	v_lshl_add_u64 v[12:13], s[46:47], 0, v[10:11]
	v_lshl_add_u64 v[12:13], v[12:13], 0, s[4:5]
	s_lshl_b32 s4, s1, 10
	s_add_i32 s94, s4, 0
	s_mov_b32 m0, s94
	v_lshl_add_u64 v[10:11], s[48:49], 0, v[10:11]
	s_mov_b64 s[4:5], 0x40080
	global_load_lds_dwordx4 v[12:13], off
	v_lshl_add_u64 v[12:13], v[10:11], 0, s[4:5]
	s_add_i32 m0, s94, 0x2000
	s_lshl_b32 s4, s1, 11
	v_ashrrev_i32_e32 v97, 31, v96
	global_load_lds_dwordx4 v[12:13], off
	s_add_i32 s6, s4, 0
	v_lshlrev_b64 v[12:13], 1, v[96:97]
	s_add_i32 s48, s6, 0x18000
	v_lshl_add_u64 v[14:15], s[46:47], 0, v[12:13]
	v_lshl_add_u64 v[16:17], v[14:15], 0, s[96:97]
	s_mov_b32 m0, s48
	s_mov_b64 s[4:5], 0xc80
	global_load_lds_dwordx4 v[16:17], off
	v_lshl_add_u64 v[14:15], v[14:15], 0, s[4:5]
	s_add_i32 m0, s6, 0x18400
	s_mov_b64 s[4:5], 0x80080
	v_or_b32_e32 v98, 64, v96
	global_load_lds_dwordx4 v[14:15], off
	v_lshl_add_u64 v[10:11], v[10:11], 0, s[4:5]
	s_add_i32 m0, s94, 0x4000
	v_ashrrev_i32_e32 v99, 31, v98
	global_load_lds_dwordx4 v[10:11], off
	s_add_i32 m0, s6, 0x1c000
	v_lshl_add_u64 v[10:11], s[52:53], 0, v[12:13]
	v_and_b32_e32 v2, 31, v7
	global_load_lds_dwordx4 v[10:11], off
	v_lshl_add_u64 v[10:11], v[98:99], 1, s[52:53]
	s_add_i32 m0, s6, 0x1c400
	s_lshl_b32 s46, s1, 5
	global_load_lds_dwordx4 v[10:11], off
	v_or_b32_e32 v10, s46, v2
	v_ashrrev_i32_e32 v11, 31, v10
	v_bfe_u32 v8, v7, 5, 1
	v_lshlrev_b64 v[10:11], 12, v[10:11]
	v_lshl_add_u64 v[10:11], s[44:45], 0, v[10:11]
	v_lshlrev_b32_e32 v130, 4, v8
	v_lshl_add_u64 v[10:11], v[10:11], 0, v[130:131]
	global_load_dwordx4 v[92:95], v[10:11], off offset:1152
	global_load_dwordx4 v[88:91], v[10:11], off offset:1184
	global_load_dwordx4 v[84:87], v[10:11], off offset:1216
	global_load_dwordx4 v[80:83], v[10:11], off offset:1248
	v_and_b32_e32 v11, 0x70, v18
	v_mov_b32_e32 v9, s88
	v_mov_b32_e32 v10, s81
	v_lshl_add_u32 v114, v2, 7, 0
	v_bitop3_b32 v115, v130, v18, s64 bitop3:0x78
	v_bitop3_b32 v117, v130, v11, 64 bitop3:0x36
	s_add_i32 s4, s46, s89
	ds_read_b32 v9, v9
	ds_read_b32 v10, v10
	s_waitcnt vmcnt(3)
	s_barrier
	v_add_u32_e32 v107, v114, v115
	v_bitop3_b32 v116, v130, v11, 32 bitop3:0x36
	v_add_u32_e32 v109, v114, v117
	v_bitop3_b32 v118, v130, v11, s65 bitop3:0x36
	s_add_i32 s5, s4, 0xffffff81
	v_add_u32_e32 v108, v114, v116
	ds_read_b128 v[12:15], v107
	ds_read_b128 v[16:19], v108
	v_add_u32_e32 v110, v114, v118
	ds_read_b128 v[20:23], v109
	ds_read_b128 v[24:27], v110
	s_ashr_i32 s5, s5, 6
	s_cmpk_gt_i32 s4, 0xbe
	v_or_b32_e32 v111, s4, v2
	s_cselect_b32 s47, s5, 0
	s_addk_i32 s4, 0xde
	s_ashr_i32 s45, s4, 6
	s_waitcnt lgkmcnt(0)
	s_waitcnt vmcnt(0) lgkmcnt(0)
	v_mfma_f32_32x32x16_bf16 v[64:79], v[12:15], v[92:95], 0
	s_cmp_gt_i32 s47, 0
	s_cselect_b64 s[4:5], -1, 0
	s_cmp_lt_i32 s45, 1
	s_cselect_b64 s[6:7], -1, 0
	s_or_b64 s[4:5], s[6:7], s[4:5]
	s_and_b64 vcc, exec, s[4:5]
	v_mfma_f32_32x32x16_bf16 v[64:79], v[16:19], v[88:91], v[64:79]
	v_mfma_f32_32x32x16_bf16 v[64:79], v[20:23], v[84:87], v[64:79]
	v_mfma_f32_32x32x16_bf16 v[64:79], v[24:27], v[80:83], v[64:79]
	s_cbranch_vccnz .LBB0_1948
	v_lshlrev_b32_e32 v8, 2, v8
	v_sub_u32_e32 v8, v8, v111
	v_lshl_add_u32 v8, v8, 2, s88
	ds_read2_b32 v[12:13], v8 offset0:240 offset1:241
	ds_read2_b32 v[14:15], v8 offset0:242 offset1:243
	ds_read2_b32 v[16:17], v8 offset0:248 offset1:249
	ds_read2_b32 v[18:19], v8 offset0:250 offset1:251
	ds_read2_b32 v[20:21], v8 offset0:224 offset1:225
	ds_read2_b32 v[22:23], v8 offset0:226 offset1:227
	ds_read2_b32 v[24:25], v8 offset0:232 offset1:233
	ds_read2_b32 v[26:27], v8 offset0:234 offset1:235
	s_waitcnt lgkmcnt(4)
	v_pk_add_f32 v[78:79], v[78:79], v[18:19]
	v_pk_add_f32 v[76:77], v[76:77], v[16:17]
	v_pk_add_f32 v[74:75], v[74:75], v[14:15]
	v_pk_add_f32 v[72:73], v[72:73], v[12:13]
	s_waitcnt lgkmcnt(0)
	v_pk_add_f32 v[70:71], v[70:71], v[26:27]
	v_pk_add_f32 v[68:69], v[68:69], v[24:25]
	v_pk_add_f32 v[66:67], v[66:67], v[22:23]
	v_pk_add_f32 v[64:65], v[64:65], v[20:21]

; #define LAS __attribute__((address_space(3)))
; DI void expsum(f32x16& p, float& l_reg, bf16x8& pa0, bf16x8& pa1) {
; #pragma unroll
;     for (int r = 0; r < 16; ++r) p[r] = __builtin_amdgcn_exp2f(p[r]);
;     float ps = 0.f;
; #pragma unroll
;     for (int r = 0; r < 16; ++r) ps += p[r];
;     l_reg += ps; asm volatile("" : "+v"(l_reg));
;     ...
;     ATT_PK4(p, 0, pa0); ATT_PK4(p, 8, pa1);
;     ...
; }
; DI int v_rd_base(int lane) { return ((lane & 3) << 3) | (((lane >> 2) & 3) << 6) | (((lane >> 4) & 1) << 5) | (((lane >> 5) & 1) << 8); }
; template <int OFF> DI s16x4 tr_read(int vb) { s16x4 r; asm volatile("ds_read_b64_tr_b16 %0, %1 offset:%2" : "=&v"(r) : "v"(vb), "i"(OFF) : "memory"); return r; }
; template <int H> DI void v_reads(s16x4* vf, int vb) {
;     vf[0] = tr_read<v_rd_off(0, 2 * H, 0)>(vb); vf[1] = tr_read<v_rd_off(0, 2 * H, 1)>(vb); vf[2] = tr_read<v_rd_off(0, 2 * H + 1, 0)>(vb); vf[3] = tr_read<v_rd_off(0, 2 * H + 1, 1)>(vb);
;     vf[4] = tr_read<v_rd_off(1, 2 * H, 0)>(vb); vf[5] = tr_read<v_rd_off(1, 2 * H, 1)>(vb); vf[6] = tr_read<v_rd_off(1, 2 * H + 1, 0)>(vb); vf[7] = tr_read<v_rd_off(1, 2 * H + 1, 1)>(vb);
;     vf[8] = tr_read<v_rd_off(2, 2 * H, 0)>(vb); vf[9] = tr_read<v_rd_off(2, 2 * H, 1)>(vb); vf[10] = tr_read<v_rd_off(2, 2 * H + 1, 0)>(vb); vf[11] = tr_read<v_rd_off(2, 2 * H + 1, 1)>(vb);
;     vf[12] = tr_read<v_rd_off(3, 2 * H, 0)>(vb); vf[13] = tr_read<v_rd_off(3, 2 * H, 1)>(vb); vf[14] = tr_read<v_rd_off(3, 2 * H + 1, 0)>(vb); vf[15] = tr_read<v_rd_off(3, 2 * H + 1, 1)>(vb);
; }
; DI void pv_mma(f32x16* o, const s16x4* vf, bf16x8 pa0, bf16x8 pa1) {
;     ...
; #pragma unroll
;     for (int d0 = 0; d0 < 4; ++d0) {
;         o[d0] = __builtin_amdgcn_mfma_f32_32x32x16_bf16(pa0, ATT_PK(vf[4 * d0], vf[4 * d0 + 1]), o[d0], 0, 0, 0);
;         o[d0] = __builtin_amdgcn_mfma_f32_32x32x16_bf16(pa1, ATT_PK(vf[4 * d0 + 2], vf[4 * d0 + 3]), o[d0], 0, 0, 0); }
;     ...
; }
; template <int DQK, int D0A, int D0B> DI void k_reads(bf16x8* kf, const LAS unsigned char* Ks, int half, int r32, int hi) {
; #pragma unroll
;     for (int d0 = D0A; d0 < D0B; ++d0) kf[d0 - D0A] = *(const LAS bf16x8*)(Ks + half * (32 * DQK * 2) + kswz<DQK>(r32, (d0 * 16 + hi * 8) * 2));
; }
; template <int D0A, int D0B> DI void qk_mma(f32x16& p, const bf16x8* kf, const bf16x8* qr) {
; #pragma unroll
;     for (int d0 = D0A; d0 < D0B; ++d0) {
.LBB0_1953:
	s_add_i32 s3, s0, -1
	s_add_i32 s2, s22, 0xffffa000
	s_and_b32 s2, s2, 0x6000
	v_add_u32_e32 v121, s2, v114
	v_add_u32_e32 v122, v121, v115
	v_add_u32_e32 v126, v121, v116
	ds_read_b128 v[122:125], v122 offset:4096
	ds_read_b128 v[132:135], v126 offset:4096
	v_add_u32_e32 v126, v121, v117
	v_add_u32_e32 v121, v121, v118
	s_lshl_b32 s2, s23, 14
	ds_read_b128 v[136:139], v126 offset:4096
	ds_read_b128 v[140:143], v121 offset:4096
	v_add_u32_e32 v121, s2, v106
	ds_read_b64_tr_b16 v[144:145], v121 offset:0
	ds_read_b64_tr_b16 v[146:147], v121 offset:0x800
	ds_read_b64_tr_b16 v[148:149], v121 offset:0x1000
	ds_read_b64_tr_b16 v[150:151], v121 offset:0x1800
	ds_read_b64_tr_b16 v[152:153], v121 offset:0x200
	ds_read_b64_tr_b16 v[154:155], v121 offset:0xa00
	ds_read_b64_tr_b16 v[156:157], v121 offset:0x1200
	ds_read_b64_tr_b16 v[158:159], v121 offset:0x1a00
	ds_read_b64_tr_b16 v[162:163], v121 offset:0x400
	ds_read_b64_tr_b16 v[164:165], v121 offset:0xc00
	ds_read_b64_tr_b16 v[166:167], v121 offset:0x1400
	ds_read_b64_tr_b16 v[168:169], v121 offset:0x1c00
	ds_read_b64_tr_b16 v[170:171], v121 offset:0x600
	ds_read_b64_tr_b16 v[172:173], v121 offset:0xe00
	ds_read_b64_tr_b16 v[174:175], v121 offset:0x1600
	ds_read_b64_tr_b16 v[176:177], v121 offset:0x1e00
	s_setprio 2
	v_exp_f32_e32 v64, v64
	v_exp_f32_e32 v65, v65
	v_exp_f32_e32 v66, v66
	v_exp_f32_e32 v67, v67
	v_exp_f32_e32 v68, v68
	v_exp_f32_e32 v69, v69
	v_add_f32_e32 v126, v65, v64
	v_exp_f32_e32 v70, v70
	v_add_f32_e32 v126, v66, v126
	v_exp_f32_e32 v71, v71
	v_add_f32_e32 v126, v67, v126
	v_exp_f32_e32 v72, v72
	v_add_f32_e32 v126, v68, v126
	v_exp_f32_e32 v73, v73
	v_add_f32_e32 v126, v69, v126
	v_exp_f32_e32 v74, v74
	v_add_f32_e32 v126, v70, v126
	v_exp_f32_e32 v75, v75
	v_add_f32_e32 v126, v71, v126
	v_exp_f32_e32 v76, v76
	v_add_f32_e32 v126, v72, v126
	v_exp_f32_e32 v77, v77
	v_add_f32_e32 v126, v73, v126
	v_exp_f32_e32 v78, v78
	v_add_f32_e32 v126, v74, v126
	v_exp_f32_e32 v79, v79
	v_add_f32_e32 v126, v75, v126
	v_add_f32_e32 v126, v76, v126
	v_add_f32_e32 v126, v77, v126
	v_add_f32_e32 v126, v78, v126
	v_add_f32_e32 v126, v79, v126
	v_add_f32_e32 v120, v126, v120
	v_cvt_pk_bf16_f32 v64, v64, v65
	v_cvt_pk_bf16_f32 v65, v66, v67
	v_cvt_pk_bf16_f32 v66, v68, v69
	v_cvt_pk_bf16_f32 v67, v70, v71
	v_cvt_pk_bf16_f32 v68, v72, v73
	v_cvt_pk_bf16_f32 v69, v74, v75
	v_cvt_pk_bf16_f32 v70, v76, v77
	v_cvt_pk_bf16_f32 v71, v78, v79
	s_nop 0
	v_permlane32_swap_b32_e32 v64, v66
	v_permlane32_swap_b32_e32 v65, v67
	v_permlane32_swap_b32_e32 v68, v70
	v_permlane32_swap_b32_e32 v69, v71
	s_waitcnt lgkmcnt(0)
	s_setprio 1
	v_mfma_f32_32x32x16_bf16 v[0:15], v[64:67], v[144:147], v[0:15]
	s_cmp_lt_i32 s3, s47
	s_cselect_b64 s[74:75], -1, 0
	s_cmp_ge_i32 s3, s52
	s_cselect_b64 s[90:91], -1, 0
	s_or_b64 s[74:75], s[74:75], s[90:91]
	s_and_b64 vcc, exec, s[74:75]
	v_mfma_f32_32x32x16_bf16 v[48:63], v[64:67], v[152:155], v[48:63]
	v_mfma_f32_32x32x16_bf16 v[16:31], v[64:67], v[162:165], v[16:31]
	v_mfma_f32_32x32x16_bf16 v[32:47], v[64:67], v[170:173], v[32:47]
	v_mfma_f32_32x32x16_bf16 v[0:15], v[68:71], v[148:151], v[0:15]
	v_mfma_f32_32x32x16_bf16 v[48:63], v[68:71], v[156:159], v[48:63]
	v_mfma_f32_32x32x16_bf16 v[16:31], v[68:71], v[166:169], v[16:31]
	v_mfma_f32_32x32x16_bf16 v[32:47], v[68:71], v[174:177], v[32:47]
	v_mfma_f32_32x32x16_bf16 v[64:79], v[122:125], v[92:95], 0
	v_mfma_f32_32x32x16_bf16 v[64:79], v[132:135], v[88:91], v[64:79]
	v_mfma_f32_32x32x16_bf16 v[64:79], v[136:139], v[84:87], v[64:79]
	v_mfma_f32_32x32x16_bf16 v[64:79], v[140:143], v[80:83], v[64:79]
	s_setprio 0
	v_add_u32_e32 v122, s7, v119
	s_cbranch_vccnz .LBB0_1955
	v_add_u32_e32 v138, 0x28908, v122
	v_add_u32_e32 v140, 0x28920, v122
	v_add_u32_e32 v142, 0x28928, v122
	v_add_u32_e32 v124, 0x28940, v122
	v_add_u32_e32 v126, 0x28948, v122
	v_add_u32_e32 v132, 0x28960, v122
	v_add_u32_e32 v134, 0x28968, v122
	v_add_u32_e32 v123, 0x28900, v122
	ds_read2_b32 v[124:125], v124 offset1:1
	ds_read2_b32 v[126:127], v126 offset1:1
	ds_read2_b32 v[132:133], v132 offset1:1
	ds_read2_b32 v[134:135], v134 offset1:1
	ds_read2_b32 v[136:137], v123 offset1:1
	ds_read2_b32 v[138:139], v138 offset1:1
	ds_read2_b32 v[140:141], v140 offset1:1
	ds_read2_b32 v[142:143], v142 offset1:1
	s_waitcnt lgkmcnt(0)
	v_pk_add_f32 v[78:79], v[78:79], v[134:135]
	v_pk_add_f32 v[76:77], v[76:77], v[132:133]
	v_pk_add_f32 v[74:75], v[74:75], v[126:127]
	v_pk_add_f32 v[72:73], v[72:73], v[124:125]
	v_pk_add_f32 v[70:71], v[70:71], v[142:143]
	v_pk_add_f32 v[68:69], v[68:69], v[140:141]
	v_pk_add_f32 v[66:67], v[66:67], v[138:139]
	v_pk_add_f32 v[64:65], v[64:65], v[136:137]

; #define LAS __attribute__((address_space(3)))
; DI void expsum(f32x16& p, float& l_reg, bf16x8& pa0, bf16x8& pa1) {
; #pragma unroll
;     for (int r = 0; r < 16; ++r) p[r] = __builtin_amdgcn_exp2f(p[r]);
;     float ps = 0.f;
; #pragma unroll
;     for (int r = 0; r < 16; ++r) ps += p[r];
;     l_reg += ps; asm volatile("" : "+v"(l_reg));
;     ...
;     ATT_PK4(p, 0, pa0); ATT_PK4(p, 8, pa1);
;     ...
; }
; DI int v_rd_base(int lane) { return ((lane & 3) << 3) | (((lane >> 2) & 3) << 6) | (((lane >> 4) & 1) << 5) | (((lane >> 5) & 1) << 8); }
; template <int OFF> DI s16x4 tr_read(int vb) { s16x4 r; asm volatile("ds_read_b64_tr_b16 %0, %1 offset:%2" : "=&v"(r) : "v"(vb), "i"(OFF) : "memory"); return r; }
; template <int H> DI void v_reads(s16x4* vf, int vb) {
;     vf[0] = tr_read<v_rd_off(0, 2 * H, 0)>(vb); vf[1] = tr_read<v_rd_off(0, 2 * H, 1)>(vb); vf[2] = tr_read<v_rd_off(0, 2 * H + 1, 0)>(vb); vf[3] = tr_read<v_rd_off(0, 2 * H + 1, 1)>(vb);
;     vf[4] = tr_read<v_rd_off(1, 2 * H, 0)>(vb); vf[5] = tr_read<v_rd_off(1, 2 * H, 1)>(vb); vf[6] = tr_read<v_rd_off(1, 2 * H + 1, 0)>(vb); vf[7] = tr_read<v_rd_off(1, 2 * H + 1, 1)>(vb);
;     vf[8] = tr_read<v_rd_off(2, 2 * H, 0)>(vb); vf[9] = tr_read<v_rd_off(2, 2 * H, 1)>(vb); vf[10] = tr_read<v_rd_off(2, 2 * H + 1, 0)>(vb); vf[11] = tr_read<v_rd_off(2, 2 * H + 1, 1)>(vb);
;     vf[12] = tr_read<v_rd_off(3, 2 * H, 0)>(vb); vf[13] = tr_read<v_rd_off(3, 2 * H, 1)>(vb); vf[14] = tr_read<v_rd_off(3, 2 * H + 1, 0)>(vb); vf[15] = tr_read<v_rd_off(3, 2 * H + 1, 1)>(vb);
; }
; DI void pv_mma(f32x16* o, const s16x4* vf, bf16x8 pa0, bf16x8 pa1) {
;     ...
; #pragma unroll
;     for (int d0 = 0; d0 < 4; ++d0) {
;         o[d0] = __builtin_amdgcn_mfma_f32_32x32x16_bf16(pa0, ATT_PK(vf[4 * d0], vf[4 * d0 + 1]), o[d0], 0, 0, 0);
;         o[d0] = __builtin_amdgcn_mfma_f32_32x32x16_bf16(pa1, ATT_PK(vf[4 * d0 + 2], vf[4 * d0 + 3]), o[d0], 0, 0, 0); }
;     ...
; }
; template <int DQK, int D0A, int D0B> DI void k_reads(bf16x8* kf, const LAS unsigned char* Ks, int half, int r32, int hi) {
; #pragma unroll
;     for (int d0 = D0A; d0 < D0B; ++d0) kf[d0 - D0A] = *(const LAS bf16x8*)(Ks + half * (32 * DQK * 2) + kswz<DQK>(r32, (d0 * 16 + hi * 8) * 2));
; }
; template <int D0A, int D0B> DI void qk_mma(f32x16& p, const bf16x8* kf, const bf16x8* qr) {
; #pragma unroll
;     for (int d0 = D0A; d0 < D0B; ++d0) {
.LBB0_1961:
	ds_read_b128 v[98:101], v107 offset:12288
	ds_read_b128 v[102:105], v108 offset:12288
	ds_read_b128 v[114:117], v109 offset:12288
	ds_read_b128 v[122:125], v110 offset:12288
	v_lshl_add_u32 v96, s49, 14, v106
	ds_read_b64_tr_b16 v[132:133], v96 offset:0
	ds_read_b64_tr_b16 v[134:135], v96 offset:0x800
	ds_read_b64_tr_b16 v[136:137], v96 offset:0x1000
	ds_read_b64_tr_b16 v[138:139], v96 offset:0x1800
	ds_read_b64_tr_b16 v[140:141], v96 offset:0x200
	ds_read_b64_tr_b16 v[142:143], v96 offset:0xa00
	ds_read_b64_tr_b16 v[144:145], v96 offset:0x1200
	ds_read_b64_tr_b16 v[146:147], v96 offset:0x1a00
	ds_read_b64_tr_b16 v[148:149], v96 offset:0x400
	ds_read_b64_tr_b16 v[150:151], v96 offset:0xc00
	ds_read_b64_tr_b16 v[152:153], v96 offset:0x1400
	ds_read_b64_tr_b16 v[154:155], v96 offset:0x1c00
	ds_read_b64_tr_b16 v[156:157], v96 offset:0x600
	ds_read_b64_tr_b16 v[158:159], v96 offset:0xe00
	ds_read_b64_tr_b16 v[162:163], v96 offset:0x1600
	ds_read_b64_tr_b16 v[164:165], v96 offset:0x1e00
	s_setprio 2
	v_exp_f32_e32 v64, v64
	v_exp_f32_e32 v65, v65
	v_exp_f32_e32 v66, v66
	v_exp_f32_e32 v67, v67
	v_exp_f32_e32 v68, v68
	v_exp_f32_e32 v69, v69
	v_add_f32_e32 v97, v65, v64
	v_exp_f32_e32 v70, v70
	v_add_f32_e32 v97, v66, v97
	v_exp_f32_e32 v71, v71
	v_add_f32_e32 v97, v67, v97
	v_exp_f32_e32 v72, v72
	v_add_f32_e32 v97, v68, v97
	v_exp_f32_e32 v73, v73
	v_add_f32_e32 v97, v69, v97
	v_exp_f32_e32 v74, v74
	v_add_f32_e32 v97, v70, v97
	v_exp_f32_e32 v75, v75
	v_add_f32_e32 v97, v71, v97
	v_exp_f32_e32 v76, v76
	v_add_f32_e32 v97, v72, v97
	v_exp_f32_e32 v77, v77
	v_add_f32_e32 v97, v73, v97
	v_exp_f32_e32 v78, v78
	v_add_f32_e32 v97, v74, v97
	v_exp_f32_e32 v79, v79
	v_add_f32_e32 v97, v75, v97
	v_add_f32_e32 v97, v76, v97
	v_add_f32_e32 v97, v77, v97
	v_add_f32_e32 v97, v78, v97
	v_add_f32_e32 v97, v79, v97
	v_add_f32_e32 v97, v97, v120
	v_cvt_pk_bf16_f32 v64, v64, v65
	v_cvt_pk_bf16_f32 v65, v66, v67
	v_cvt_pk_bf16_f32 v66, v68, v69
	v_cvt_pk_bf16_f32 v67, v70, v71
	v_cvt_pk_bf16_f32 v68, v72, v73
	v_cvt_pk_bf16_f32 v69, v74, v75
	v_cvt_pk_bf16_f32 v70, v76, v77
	v_cvt_pk_bf16_f32 v71, v78, v79
	s_nop 0
	v_permlane32_swap_b32_e32 v64, v66
	v_permlane32_swap_b32_e32 v65, v67
	v_permlane32_swap_b32_e32 v68, v70
	v_permlane32_swap_b32_e32 v69, v71
	s_waitcnt lgkmcnt(0)
	s_setprio 1
	v_mfma_f32_32x32x16_bf16 v[0:15], v[64:67], v[132:135], v[0:15]
	s_cmp_gt_i32 s47, 61
	s_cselect_b64 s[0:1], -1, 0
	s_cmp_lt_i32 s45, 62
	s_cselect_b64 s[2:3], -1, 0
	s_or_b64 s[0:1], s[0:1], s[2:3]
	s_and_b64 vcc, exec, s[0:1]
	v_mfma_f32_32x32x16_bf16 v[48:63], v[64:67], v[140:143], v[48:63]
	v_mfma_f32_32x32x16_bf16 v[16:31], v[64:67], v[148:151], v[16:31]
	v_mfma_f32_32x32x16_bf16 v[32:47], v[64:67], v[156:159], v[32:47]
	v_mfma_f32_32x32x16_bf16 v[0:15], v[68:71], v[136:139], v[0:15]
	v_mfma_f32_32x32x16_bf16 v[48:63], v[68:71], v[144:147], v[48:63]
	v_mfma_f32_32x32x16_bf16 v[16:31], v[68:71], v[152:155], v[16:31]
	v_mfma_f32_32x32x16_bf16 v[32:47], v[68:71], v[162:165], v[32:47]
	s_waitcnt lgkmcnt(0)
	v_mfma_f32_32x32x16_bf16 v[64:79], v[98:101], v[92:95], 0
	v_mfma_f32_32x32x16_bf16 v[64:79], v[102:105], v[88:91], v[64:79]
	v_mfma_f32_32x32x16_bf16 v[64:79], v[114:117], v[84:87], v[64:79]
	v_mfma_f32_32x32x16_bf16 v[64:79], v[122:125], v[80:83], v[64:79]
	s_setprio 0
	s_cbranch_vccnz .LBB0_1963
	v_sub_u32_e32 v98, 0xf40, v111
	v_lshlrev_b32_e32 v98, 2, v98
	v_add3_u32 v98, s88, v98, v130
	v_add_u32_e32 v114, 0x400, v98
	v_add_u32_e32 v116, 0x408, v98
	v_add_u32_e32 v118, 0x420, v98
	v_add_u32_e32 v120, 0x428, v98
	v_add_u32_e32 v99, 0x440, v98
	v_add_u32_e32 v100, 0x448, v98
	v_add_u32_e32 v102, 0x460, v98
	v_add_u32_e32 v104, 0x468, v98
	ds_read2_b32 v[98:99], v99 offset1:1
	ds_read2_b32 v[100:101], v100 offset1:1
	ds_read2_b32 v[102:103], v102 offset1:1
	ds_read2_b32 v[104:105], v104 offset1:1
	ds_read2_b32 v[114:115], v114 offset1:1
	ds_read2_b32 v[116:117], v116 offset1:1
	ds_read2_b32 v[118:119], v118 offset1:1
	ds_read2_b32 v[120:121], v120 offset1:1
	s_waitcnt lgkmcnt(0)
	v_pk_add_f32 v[78:79], v[78:79], v[104:105]
	v_pk_add_f32 v[76:77], v[76:77], v[102:103]
	v_pk_add_f32 v[74:75], v[74:75], v[100:101]
	v_pk_add_f32 v[72:73], v[72:73], v[98:99]
	v_pk_add_f32 v[70:71], v[70:71], v[120:121]
	v_pk_add_f32 v[68:69], v[68:69], v[118:119]
	v_pk_add_f32 v[66:67], v[66:67], v[116:117]
	v_pk_add_f32 v[64:65], v[64:65], v[114:115]
.LBB0_1963:
	ds_read_b128 v[98:101], v107 offset:16384
	ds_read_b128 v[102:105], v108 offset:16384
	ds_read_b128 v[114:117], v109 offset:16384
	ds_read_b128 v[118:121], v110 offset:16384
	ds_read_b64_tr_b16 v[122:123], v96 offset:0x2000
	ds_read_b64_tr_b16 v[124:125], v96 offset:0x2800
	ds_read_b64_tr_b16 v[132:133], v96 offset:0x3000
	ds_read_b64_tr_b16 v[134:135], v96 offset:0x3800
	ds_read_b64_tr_b16 v[136:137], v96 offset:0x2200
	ds_read_b64_tr_b16 v[138:139], v96 offset:0x2a00
	ds_read_b64_tr_b16 v[140:141], v96 offset:0x3200
	ds_read_b64_tr_b16 v[142:143], v96 offset:0x3a00
	ds_read_b64_tr_b16 v[144:145], v96 offset:0x2400
	ds_read_b64_tr_b16 v[146:147], v96 offset:0x2c00
	ds_read_b64_tr_b16 v[148:149], v96 offset:0x3400
	ds_read_b64_tr_b16 v[150:151], v96 offset:0x3c00
	ds_read_b64_tr_b16 v[152:153], v96 offset:0x2600
	ds_read_b64_tr_b16 v[154:155], v96 offset:0x2e00
	ds_read_b64_tr_b16 v[156:157], v96 offset:0x3600
	ds_read_b64_tr_b16 v[158:159], v96 offset:0x3e00
	s_nop 6
	s_setprio 2
	v_exp_f32_e32 v64, v64
	v_exp_f32_e32 v65, v65
	v_exp_f32_e32 v66, v66
	v_exp_f32_e32 v67, v67
	v_exp_f32_e32 v68, v68
	v_exp_f32_e32 v69, v69
	v_add_f32_e32 v96, v65, v64
	v_exp_f32_e32 v70, v70
	v_add_f32_e32 v96, v66, v96
	v_exp_f32_e32 v71, v71
	v_add_f32_e32 v96, v67, v96
	v_exp_f32_e32 v72, v72
	v_add_f32_e32 v96, v68, v96
	v_exp_f32_e32 v73, v73
	v_add_f32_e32 v96, v69, v96
	v_exp_f32_e32 v74, v74
	v_add_f32_e32 v96, v70, v96
	v_exp_f32_e32 v75, v75
	v_add_f32_e32 v96, v71, v96
	v_exp_f32_e32 v76, v76
	v_add_f32_e32 v96, v72, v96
	v_exp_f32_e32 v77, v77
	v_add_f32_e32 v96, v73, v96
	v_exp_f32_e32 v78, v78
	v_add_f32_e32 v96, v74, v96
	v_exp_f32_e32 v79, v79
	v_add_f32_e32 v96, v75, v96
	v_add_f32_e32 v96, v76, v96
	v_add_f32_e32 v96, v77, v96
	v_add_f32_e32 v96, v78, v96
	v_add_f32_e32 v96, v79, v96
	v_add_f32_e32 v96, v97, v96
	v_cvt_pk_bf16_f32 v64, v64, v65
	v_cvt_pk_bf16_f32 v65, v66, v67
	v_cvt_pk_bf16_f32 v66, v68, v69
	v_cvt_pk_bf16_f32 v67, v70, v71
	v_cvt_pk_bf16_f32 v68, v72, v73
	v_cvt_pk_bf16_f32 v69, v74, v75
	v_cvt_pk_bf16_f32 v70, v76, v77
	v_cvt_pk_bf16_f32 v71, v78, v79
	s_nop 0
	v_permlane32_swap_b32_e32 v64, v66
	v_permlane32_swap_b32_e32 v65, v67
	v_permlane32_swap_b32_e32 v68, v70
	v_permlane32_swap_b32_e32 v69, v71
	s_waitcnt lgkmcnt(0)
	s_setprio 1
	s_cmp_lt_u32 s33, 0x100
	s_cbranch_scc1 .Lstg_d1_m61_21
	s_waitcnt vmcnt(0)
	s_barrier

; #define LAS __attribute__((address_space(3)))
; DI void expsum(f32x16& p, float& l_reg, bf16x8& pa0, bf16x8& pa1) {
; #pragma unroll
;     for (int r = 0; r < 16; ++r) p[r] = __builtin_amdgcn_exp2f(p[r]);
;     float ps = 0.f;
; #pragma unroll
;     for (int r = 0; r < 16; ++r) ps += p[r];
;     l_reg += ps; asm volatile("" : "+v"(l_reg));
;     ...
;     ATT_PK4(p, 0, pa0); ATT_PK4(p, 8, pa1);
;     ...
; }
; DI int v_rd_base(int lane) { return ((lane & 3) << 3) | (((lane >> 2) & 3) << 6) | (((lane >> 4) & 1) << 5) | (((lane >> 5) & 1) << 8); }
; template <int OFF> DI s16x4 tr_read(int vb) { s16x4 r; asm volatile("ds_read_b64_tr_b16 %0, %1 offset:%2" : "=&v"(r) : "v"(vb), "i"(OFF) : "memory"); return r; }
; template <int H> DI void v_reads(s16x4* vf, int vb) {
;     vf[0] = tr_read<v_rd_off(0, 2 * H, 0)>(vb); vf[1] = tr_read<v_rd_off(0, 2 * H, 1)>(vb); vf[2] = tr_read<v_rd_off(0, 2 * H + 1, 0)>(vb); vf[3] = tr_read<v_rd_off(0, 2 * H + 1, 1)>(vb);
;     vf[4] = tr_read<v_rd_off(1, 2 * H, 0)>(vb); vf[5] = tr_read<v_rd_off(1, 2 * H, 1)>(vb); vf[6] = tr_read<v_rd_off(1, 2 * H + 1, 0)>(vb); vf[7] = tr_read<v_rd_off(1, 2 * H + 1, 1)>(vb);
;     vf[8] = tr_read<v_rd_off(2, 2 * H, 0)>(vb); vf[9] = tr_read<v_rd_off(2, 2 * H, 1)>(vb); vf[10] = tr_read<v_rd_off(2, 2 * H + 1, 0)>(vb); vf[11] = tr_read<v_rd_off(2, 2 * H + 1, 1)>(vb);
;     vf[12] = tr_read<v_rd_off(3, 2 * H, 0)>(vb); vf[13] = tr_read<v_rd_off(3, 2 * H, 1)>(vb); vf[14] = tr_read<v_rd_off(3, 2 * H + 1, 0)>(vb); vf[15] = tr_read<v_rd_off(3, 2 * H + 1, 1)>(vb);
; }
; DI void pv_mma(f32x16* o, const s16x4* vf, bf16x8 pa0, bf16x8 pa1) {
;     ...
; #pragma unroll
;     for (int d0 = 0; d0 < 4; ++d0) {
;         o[d0] = __builtin_amdgcn_mfma_f32_32x32x16_bf16(pa0, ATT_PK(vf[4 * d0], vf[4 * d0 + 1]), o[d0], 0, 0, 0);
;         o[d0] = __builtin_amdgcn_mfma_f32_32x32x16_bf16(pa1, ATT_PK(vf[4 * d0 + 2], vf[4 * d0 + 3]), o[d0], 0, 0, 0); }
;     ...
; }
; template <int DQK, int D0A, int D0B> DI void k_reads(bf16x8* kf, const LAS unsigned char* Ks, int half, int r32, int hi) {
; #pragma unroll
;     for (int d0 = D0A; d0 < D0B; ++d0) kf[d0 - D0A] = *(const LAS bf16x8*)(Ks + half * (32 * DQK * 2) + kswz<DQK>(r32, (d0 * 16 + hi * 8) * 2));
; }
; template <int D0A, int D0B> DI void qk_mma(f32x16& p, const bf16x8* kf, const bf16x8* qr) {
; #pragma unroll
;     for (int d0 = D0A; d0 < D0B; ++d0) {
.LBB0_1967:
	ds_read_b128 v[100:103], v107 offset:20480
	ds_read_b128 v[114:117], v108 offset:20480
	ds_read_b128 v[118:121], v109 offset:20480
	ds_read_b128 v[122:125], v110 offset:20480
	v_add_u32_e32 v98, 0x8000, v106
	ds_read_b64_tr_b16 v[132:133], v98 offset:0
	ds_read_b64_tr_b16 v[134:135], v98 offset:0x800
	ds_read_b64_tr_b16 v[136:137], v98 offset:0x1000
	ds_read_b64_tr_b16 v[138:139], v98 offset:0x1800
	ds_read_b64_tr_b16 v[140:141], v98 offset:0x200
	ds_read_b64_tr_b16 v[142:143], v98 offset:0xa00
	ds_read_b64_tr_b16 v[144:145], v98 offset:0x1200
	ds_read_b64_tr_b16 v[146:147], v98 offset:0x1a00
	ds_read_b64_tr_b16 v[148:149], v98 offset:0x400
	ds_read_b64_tr_b16 v[150:151], v98 offset:0xc00
	ds_read_b64_tr_b16 v[152:153], v98 offset:0x1400
	ds_read_b64_tr_b16 v[154:155], v98 offset:0x1c00
	ds_read_b64_tr_b16 v[156:157], v98 offset:0x600
	ds_read_b64_tr_b16 v[158:159], v98 offset:0xe00
	ds_read_b64_tr_b16 v[162:163], v98 offset:0x1600
	ds_read_b64_tr_b16 v[164:165], v98 offset:0x1e00
	s_setprio 2
	v_exp_f32_e32 v64, v64
	v_exp_f32_e32 v65, v65
	v_exp_f32_e32 v66, v66
	v_exp_f32_e32 v67, v67
	v_exp_f32_e32 v68, v68
	v_exp_f32_e32 v69, v69
	v_add_f32_e32 v99, v65, v64
	v_exp_f32_e32 v70, v70
	v_add_f32_e32 v99, v66, v99
	v_exp_f32_e32 v71, v71
	v_add_f32_e32 v99, v67, v99
	v_exp_f32_e32 v72, v72
	v_add_f32_e32 v99, v68, v99
	v_exp_f32_e32 v73, v73
	v_add_f32_e32 v99, v69, v99
	v_exp_f32_e32 v74, v74
	v_add_f32_e32 v99, v70, v99
	v_exp_f32_e32 v75, v75
	v_add_f32_e32 v99, v71, v99
	v_exp_f32_e32 v76, v76
	v_add_f32_e32 v99, v72, v99
	v_exp_f32_e32 v77, v77
	v_add_f32_e32 v99, v73, v99
	v_exp_f32_e32 v78, v78
	v_add_f32_e32 v99, v74, v99
	v_exp_f32_e32 v79, v79
	v_add_f32_e32 v99, v75, v99
	v_add_f32_e32 v99, v76, v99
	v_add_f32_e32 v99, v77, v99
	v_add_f32_e32 v99, v78, v99
	v_add_f32_e32 v99, v79, v99
	v_add_f32_e32 v96, v99, v96
	v_cvt_pk_bf16_f32 v64, v64, v65
	v_cvt_pk_bf16_f32 v65, v66, v67
	v_cvt_pk_bf16_f32 v66, v68, v69
	v_cvt_pk_bf16_f32 v67, v70, v71
	v_cvt_pk_bf16_f32 v68, v72, v73
	v_cvt_pk_bf16_f32 v69, v74, v75
	v_cvt_pk_bf16_f32 v70, v76, v77
	v_cvt_pk_bf16_f32 v71, v78, v79
	s_nop 0
	v_permlane32_swap_b32_e32 v64, v66
	v_permlane32_swap_b32_e32 v65, v67
	v_permlane32_swap_b32_e32 v68, v70
	v_permlane32_swap_b32_e32 v69, v71
	s_waitcnt lgkmcnt(0)
	s_setprio 1
	v_mfma_f32_32x32x16_bf16 v[0:15], v[64:67], v[132:135], v[0:15]
	s_and_b64 vcc, exec, s[2:3]
	v_mfma_f32_32x32x16_bf16 v[48:63], v[64:67], v[140:143], v[48:63]
	v_mfma_f32_32x32x16_bf16 v[16:31], v[64:67], v[148:151], v[16:31]
	v_mfma_f32_32x32x16_bf16 v[32:47], v[64:67], v[156:159], v[32:47]
	v_mfma_f32_32x32x16_bf16 v[0:15], v[68:71], v[136:139], v[0:15]
	v_mfma_f32_32x32x16_bf16 v[48:63], v[68:71], v[144:147], v[48:63]
	v_mfma_f32_32x32x16_bf16 v[16:31], v[68:71], v[152:155], v[16:31]
	v_mfma_f32_32x32x16_bf16 v[32:47], v[68:71], v[162:165], v[32:47]
	s_waitcnt lgkmcnt(0)
	v_mfma_f32_32x32x16_bf16 v[64:79], v[100:103], v[92:95], 0
	v_mfma_f32_32x32x16_bf16 v[64:79], v[114:117], v[88:91], v[64:79]
	v_mfma_f32_32x32x16_bf16 v[64:79], v[118:121], v[84:87], v[64:79]
	v_mfma_f32_32x32x16_bf16 v[64:79], v[122:125], v[80:83], v[64:79]
	s_setprio 0
	s_cbranch_vccnz .LBB0_1969
	v_add3_u32 v97, s88, v97, v130
	v_add_u32_e32 v118, 0x408, v97
	v_add_u32_e32 v120, 0x420, v97
	v_add_u32_e32 v122, 0x428, v97
	v_add_u32_e32 v100, 0x440, v97
	v_add_u32_e32 v102, 0x448, v97
	v_add_u32_e32 v104, 0x460, v97
	v_add_u32_e32 v99, 0x400, v97
	v_add_u32_e32 v97, 0x468, v97
	ds_read2_b32 v[100:101], v100 offset1:1
	ds_read2_b32 v[102:103], v102 offset1:1
	ds_read2_b32 v[104:105], v104 offset1:1
	ds_read2_b32 v[114:115], v97 offset1:1
	ds_read2_b32 v[116:117], v99 offset1:1
	ds_read2_b32 v[118:119], v118 offset1:1
	ds_read2_b32 v[120:121], v120 offset1:1
	ds_read2_b32 v[122:123], v122 offset1:1
	s_waitcnt lgkmcnt(0)
	v_pk_add_f32 v[78:79], v[78:79], v[114:115]
	v_pk_add_f32 v[76:77], v[76:77], v[104:105]
	v_pk_add_f32 v[74:75], v[74:75], v[102:103]
	v_pk_add_f32 v[72:73], v[72:73], v[100:101]
	v_pk_add_f32 v[70:71], v[70:71], v[122:123]
	v_pk_add_f32 v[68:69], v[68:69], v[120:121]
	v_pk_add_f32 v[66:67], v[66:67], v[118:119]
	v_pk_add_f32 v[64:65], v[64:65], v[116:117]

; #define LAS __attribute__((address_space(3)))
; DI void expsum(f32x16& p, float& l_reg, bf16x8& pa0, bf16x8& pa1) {
; #pragma unroll
;     for (int r = 0; r < 16; ++r) p[r] = __builtin_amdgcn_exp2f(p[r]);
;     float ps = 0.f;
; #pragma unroll
;     for (int r = 0; r < 16; ++r) ps += p[r];
;     l_reg += ps; asm volatile("" : "+v"(l_reg));
;     ...
;     ATT_PK4(p, 0, pa0); ATT_PK4(p, 8, pa1);
;     ...
; }
; DI int v_rd_base(int lane) { return ((lane & 3) << 3) | (((lane >> 2) & 3) << 6) | (((lane >> 4) & 1) << 5) | (((lane >> 5) & 1) << 8); }
; template <int OFF> DI s16x4 tr_read(int vb) { s16x4 r; asm volatile("ds_read_b64_tr_b16 %0, %1 offset:%2" : "=&v"(r) : "v"(vb), "i"(OFF) : "memory"); return r; }
; template <int H> DI void v_reads(s16x4* vf, int vb) {
;     vf[0] = tr_read<v_rd_off(0, 2 * H, 0)>(vb); vf[1] = tr_read<v_rd_off(0, 2 * H, 1)>(vb); vf[2] = tr_read<v_rd_off(0, 2 * H + 1, 0)>(vb); vf[3] = tr_read<v_rd_off(0, 2 * H + 1, 1)>(vb);
;     vf[4] = tr_read<v_rd_off(1, 2 * H, 0)>(vb); vf[5] = tr_read<v_rd_off(1, 2 * H, 1)>(vb); vf[6] = tr_read<v_rd_off(1, 2 * H + 1, 0)>(vb); vf[7] = tr_read<v_rd_off(1, 2 * H + 1, 1)>(vb);
;     vf[8] = tr_read<v_rd_off(2, 2 * H, 0)>(vb); vf[9] = tr_read<v_rd_off(2, 2 * H, 1)>(vb); vf[10] = tr_read<v_rd_off(2, 2 * H + 1, 0)>(vb); vf[11] = tr_read<v_rd_off(2, 2 * H + 1, 1)>(vb);
;     vf[12] = tr_read<v_rd_off(3, 2 * H, 0)>(vb); vf[13] = tr_read<v_rd_off(3, 2 * H, 1)>(vb); vf[14] = tr_read<v_rd_off(3, 2 * H + 1, 0)>(vb); vf[15] = tr_read<v_rd_off(3, 2 * H + 1, 1)>(vb);
; }
; DI void pv_mma(f32x16* o, const s16x4* vf, bf16x8 pa0, bf16x8 pa1) {
;     ...
; #pragma unroll
;     for (int d0 = 0; d0 < 4; ++d0) {
;         o[d0] = __builtin_amdgcn_mfma_f32_32x32x16_bf16(pa0, ATT_PK(vf[4 * d0], vf[4 * d0 + 1]), o[d0], 0, 0, 0);
;         o[d0] = __builtin_amdgcn_mfma_f32_32x32x16_bf16(pa1, ATT_PK(vf[4 * d0 + 2], vf[4 * d0 + 3]), o[d0], 0, 0, 0); }
;     ...
; }
; template <int DQK, int D0A, int D0B> DI void k_reads(bf16x8* kf, const LAS unsigned char* Ks, int half, int r32, int hi) {
; #pragma unroll
;     for (int d0 = D0A; d0 < D0B; ++d0) kf[d0 - D0A] = *(const LAS bf16x8*)(Ks + half * (32 * DQK * 2) + kswz<DQK>(r32, (d0 * 16 + hi * 8) * 2));
; }
; template <int D0A, int D0B> DI void qk_mma(f32x16& p, const bf16x8* kf, const bf16x8* qr) {
; #pragma unroll
;     for (int d0 = D0A; d0 < D0B; ++d0) {
.LBB0_1973:
	ds_read_b128 v[98:101], v107 offset:28672
	ds_read_b128 v[102:105], v108 offset:28672
	ds_read_b128 v[112:115], v109 offset:28672
	ds_read_b128 v[108:111], v110 offset:28672
	ds_read_b64_tr_b16 v[116:117], v106 offset:0
	ds_read_b64_tr_b16 v[118:119], v106 offset:0x800
	ds_read_b64_tr_b16 v[120:121], v106 offset:0x1000
	ds_read_b64_tr_b16 v[122:123], v106 offset:0x1800
	ds_read_b64_tr_b16 v[124:125], v106 offset:0x200
	ds_read_b64_tr_b16 v[126:127], v106 offset:0xa00
	ds_read_b64_tr_b16 v[132:133], v106 offset:0x1200
	ds_read_b64_tr_b16 v[134:135], v106 offset:0x1a00
	ds_read_b64_tr_b16 v[136:137], v106 offset:0x400
	ds_read_b64_tr_b16 v[138:139], v106 offset:0xc00
	ds_read_b64_tr_b16 v[140:141], v106 offset:0x1400
	ds_read_b64_tr_b16 v[142:143], v106 offset:0x1c00
	ds_read_b64_tr_b16 v[144:145], v106 offset:0x600
	ds_read_b64_tr_b16 v[146:147], v106 offset:0xe00
	ds_read_b64_tr_b16 v[148:149], v106 offset:0x1600
	ds_read_b64_tr_b16 v[150:151], v106 offset:0x1e00
	s_setprio 2
	v_exp_f32_e32 v64, v64
	v_exp_f32_e32 v65, v65
	v_exp_f32_e32 v66, v66
	v_exp_f32_e32 v67, v67
	v_exp_f32_e32 v68, v68
	v_exp_f32_e32 v69, v69
	v_add_f32_e32 v107, v65, v64
	v_exp_f32_e32 v70, v70
	v_add_f32_e32 v107, v66, v107
	v_exp_f32_e32 v71, v71
	v_add_f32_e32 v107, v67, v107
	v_exp_f32_e32 v72, v72
	v_add_f32_e32 v107, v68, v107
	v_exp_f32_e32 v73, v73
	v_add_f32_e32 v107, v69, v107
	v_exp_f32_e32 v74, v74
	v_add_f32_e32 v107, v70, v107
	v_exp_f32_e32 v75, v75
	v_add_f32_e32 v107, v71, v107
	v_exp_f32_e32 v76, v76
	v_add_f32_e32 v107, v72, v107
	v_exp_f32_e32 v77, v77
	v_add_f32_e32 v107, v73, v107
	v_exp_f32_e32 v78, v78
	v_add_f32_e32 v107, v74, v107
	v_exp_f32_e32 v79, v79
	v_add_f32_e32 v107, v75, v107
	v_add_f32_e32 v107, v76, v107
	v_add_f32_e32 v107, v77, v107
	v_add_f32_e32 v107, v78, v107
	v_add_f32_e32 v107, v79, v107
	v_add_f32_e32 v96, v107, v96
	v_cvt_pk_bf16_f32 v64, v64, v65
	v_cvt_pk_bf16_f32 v65, v66, v67
	v_cvt_pk_bf16_f32 v66, v68, v69
	v_cvt_pk_bf16_f32 v67, v70, v71
	v_cvt_pk_bf16_f32 v68, v72, v73
	v_cvt_pk_bf16_f32 v69, v74, v75
	v_cvt_pk_bf16_f32 v70, v76, v77
	v_cvt_pk_bf16_f32 v71, v78, v79
	s_nop 0
	v_permlane32_swap_b32_e32 v64, v66
	v_permlane32_swap_b32_e32 v65, v67
	v_permlane32_swap_b32_e32 v68, v70
	v_permlane32_swap_b32_e32 v69, v71
	s_waitcnt lgkmcnt(0)
	s_setprio 1
	v_mfma_f32_32x32x16_bf16 v[0:15], v[64:67], v[116:119], v[0:15]
	s_and_b64 vcc, exec, s[2:3]
	v_mfma_f32_32x32x16_bf16 v[48:63], v[64:67], v[124:127], v[48:63]
	v_mfma_f32_32x32x16_bf16 v[16:31], v[64:67], v[136:139], v[16:31]
	v_mfma_f32_32x32x16_bf16 v[32:47], v[64:67], v[144:147], v[32:47]
	v_mfma_f32_32x32x16_bf16 v[0:15], v[68:71], v[120:123], v[0:15]
	v_mfma_f32_32x32x16_bf16 v[48:63], v[68:71], v[132:135], v[48:63]
	v_mfma_f32_32x32x16_bf16 v[16:31], v[68:71], v[140:143], v[16:31]
	v_mfma_f32_32x32x16_bf16 v[32:47], v[68:71], v[148:151], v[32:47]
	s_waitcnt lgkmcnt(0)
	v_mfma_f32_32x32x16_bf16 v[64:79], v[98:101], v[92:95], 0
	v_mfma_f32_32x32x16_bf16 v[64:79], v[102:105], v[88:91], v[64:79]
	v_mfma_f32_32x32x16_bf16 v[64:79], v[112:115], v[84:87], v[64:79]
	v_mfma_f32_32x32x16_bf16 v[64:79], v[108:111], v[80:83], v[64:79]
	s_setprio 0
	s_cbranch_vccnz .LBB0_1975
	v_add3_u32 v80, s88, v97, v130
	v_add_u32_e32 v88, 0x400, v80
	v_add_u32_e32 v90, 0x408, v80
	v_add_u32_e32 v92, 0x420, v80
	v_add_u32_e32 v94, 0x428, v80
	v_add_u32_e32 v81, 0x440, v80
	v_add_u32_e32 v82, 0x448, v80
	v_add_u32_e32 v84, 0x460, v80
	v_add_u32_e32 v86, 0x468, v80
	ds_read2_b32 v[80:81], v81 offset1:1
	ds_read2_b32 v[82:83], v82 offset1:1
	ds_read2_b32 v[84:85], v84 offset1:1
	ds_read2_b32 v[86:87], v86 offset1:1
	ds_read2_b32 v[88:89], v88 offset1:1
	ds_read2_b32 v[90:91], v90 offset1:1
	ds_read2_b32 v[92:93], v92 offset1:1
	ds_read2_b32 v[94:95], v94 offset1:1
	s_waitcnt lgkmcnt(0)
	v_pk_add_f32 v[78:79], v[78:79], v[86:87]
	v_pk_add_f32 v[76:77], v[76:77], v[84:85]
	v_pk_add_f32 v[74:75], v[74:75], v[82:83]
	v_pk_add_f32 v[72:73], v[72:73], v[80:81]
	v_pk_add_f32 v[70:71], v[70:71], v[94:95]
	v_pk_add_f32 v[68:69], v[68:69], v[92:93]
	v_pk_add_f32 v[66:67], v[66:67], v[90:91]
	v_pk_add_f32 v[64:65], v[64:65], v[88:89]
.LBB0_1975:
	s_lshl_b32 s0, s44, 2
	s_add_i32 s0, s0, 0
	s_add_i32 s0, s0, 0x24000
	ds_read_b64_tr_b16 v[80:81], v106 offset:0x2000
	ds_read_b64_tr_b16 v[82:83], v106 offset:0x2800
	ds_read_b64_tr_b16 v[84:85], v106 offset:0x3000
	ds_read_b64_tr_b16 v[86:87], v106 offset:0x3800
	ds_read_b64_tr_b16 v[88:89], v106 offset:0x2200
	ds_read_b64_tr_b16 v[90:91], v106 offset:0x2a00
	ds_read_b64_tr_b16 v[92:93], v106 offset:0x3200
	ds_read_b64_tr_b16 v[94:95], v106 offset:0x3a00
	ds_read_b64_tr_b16 v[98:99], v106 offset:0x2400
	ds_read_b64_tr_b16 v[100:101], v106 offset:0x2c00
	ds_read_b64_tr_b16 v[102:103], v106 offset:0x3400
	ds_read_b64_tr_b16 v[104:105], v106 offset:0x3c00
	ds_read_b64_tr_b16 v[108:109], v106 offset:0x2600
	ds_read_b64_tr_b16 v[110:111], v106 offset:0x2e00
	ds_read_b64_tr_b16 v[112:113], v106 offset:0x3600
	ds_read_b64_tr_b16 v[114:115], v106 offset:0x3e00
	s_nop 7
	s_setprio 2
	v_exp_f32_e32 v97, v64
	v_exp_f32_e32 v65, v65
	v_exp_f32_e32 v106, v66
	v_exp_f32_e32 v67, v67
	v_exp_f32_e32 v68, v68
	v_exp_f32_e32 v69, v69
	v_add_f32_e32 v64, v65, v97
	v_exp_f32_e32 v70, v70
	v_add_f32_e32 v64, v106, v64
	v_exp_f32_e32 v71, v71
	v_add_f32_e32 v64, v67, v64
	v_exp_f32_e32 v72, v72
	v_add_f32_e32 v64, v68, v64
	v_exp_f32_e32 v73, v73
	v_add_f32_e32 v64, v69, v64
	v_exp_f32_e32 v74, v74
	v_add_f32_e32 v64, v70, v64
	v_exp_f32_e32 v75, v75
	v_add_f32_e32 v64, v71, v64
	v_exp_f32_e32 v76, v76
	v_add_f32_e32 v64, v72, v64
	v_exp_f32_e32 v77, v77
	v_add_f32_e32 v64, v73, v64
	v_exp_f32_e32 v78, v78
	v_add_f32_e32 v64, v74, v64
	v_exp_f32_e32 v79, v79
	v_add_f32_e32 v64, v75, v64
	v_add_f32_e32 v64, v76, v64
	v_add_f32_e32 v64, v77, v64
	v_add_f32_e32 v64, v78, v64
	v_add_f32_e32 v64, v79, v64
	v_add_f32_e32 v64, v96, v64
	v_cvt_pk_bf16_f32 v66, v97, v65
	v_cvt_pk_bf16_f32 v67, v106, v67
	v_cvt_pk_bf16_f32 v68, v68, v69
	v_cvt_pk_bf16_f32 v69, v70, v71
	v_cvt_pk_bf16_f32 v70, v72, v73
	v_cvt_pk_bf16_f32 v71, v74, v75
	v_cvt_pk_bf16_f32 v72, v76, v77
	v_cvt_pk_bf16_f32 v73, v78, v79
	s_nop 0
	v_permlane32_swap_b32_e32 v66, v68
	v_permlane32_swap_b32_e32 v67, v69
	v_permlane32_swap_b32_e32 v70, v72
	v_permlane32_swap_b32_e32 v71, v73
	s_waitcnt lgkmcnt(0)
; template <int TAG = 0> DI int fresh_tid(int wv) { int l; asm volatile("v_mbcnt_lo_u32_b32 %0, -1, 0\n\tv_mbcnt_hi_u32_b32 %0, -1, %0 ; site %1" : "=v"(l) : "n"(TAG)); return wv * 64 + l; }
; DI int crow(int r, int hi) { return (r & 3) + 8 * (r >> 2) + 4 * hi; }
; DI float swap_sum(float v) { auto rr = __builtin_amdgcn_permlane32_swap(__float_as_uint(v), __float_as_uint(v), false, false); return __uint_as_float(rr[0]) + __uint_as_float(rr[1]); }
; template <int DQK, int MODE, int LDQ, int LDK, int LDV> ...
;     ...
;     l_reg = swap_sum(l_reg);
;     { const int lane2 = fresh_tid<110 + MODE>(wv) & 63, r32 = lane2 & 31, hi = lane2 >> 5;
;     if (hi == 0) li_l[r32] = l_reg;
;     asm volatile("s_waitcnt lgkmcnt(0)" ::: "memory");
;     float s0v[MODE == 2 ? 16 : 1][4];
;     if constexpr (MODE == 2) {
; #pragma unroll
;         for (int r = 0; r < 16; ++r)
; #pragma unroll
;             for (int d0 = 0; d0 < 4; ++d0) s0v[r][d0] = S0[(size_t)(wid * 32 + crow(r, hi)) * 512 + d0 * 32 + r32];
;     }
	s_setprio 1
	v_mfma_f32_32x32x16_bf16 v[0:15], v[66:69], v[80:83], v[0:15]
	v_mfma_f32_32x32x16_bf16 v[48:63], v[66:69], v[88:91], v[48:63]
	v_mfma_f32_32x32x16_bf16 v[16:31], v[66:69], v[98:101], v[16:31]
	v_mfma_f32_32x32x16_bf16 v[32:47], v[66:69], v[108:111], v[32:47]
	v_mfma_f32_32x32x16_bf16 v[0:15], v[70:73], v[84:87], v[0:15]
	v_mfma_f32_32x32x16_bf16 v[48:63], v[70:73], v[92:95], v[48:63]
	v_mfma_f32_32x32x16_bf16 v[16:31], v[70:73], v[102:105], v[16:31]
	v_mfma_f32_32x32x16_bf16 v[32:47], v[70:73], v[112:115], v[32:47]
	s_setprio 0
	v_mov_b32_e32 v66, v64
	v_mbcnt_lo_u32_b32 v65, -1, 0
	v_mbcnt_hi_u32_b32 v65, -1, v65
	s_nop 1
	v_permlane32_swap_b32_e32 v64, v66
	v_and_b32_e32 v114, 63, v65
	v_and_b32_e32 v170, 31, v65
	v_cmp_gt_u32_e32 vcc, 32, v114
	s_and_saveexec_b64 s[2:3], vcc
	v_lshl_add_u32 v67, v170, 2, s0
	v_add_f32_e32 v64, v64, v66
	ds_write_b32 v67, v64
	s_or_b64 exec, exec, s[2:3]
	v_lshrrev_b32_e32 v64, 3, v65
	v_and_b32_e32 v69, 4, v64
	v_or_b32_e32 v102, s46, v69
	v_lshlrev_b32_e32 v130, 2, v170
	v_ashrrev_i32_e32 v103, 31, v102
	v_or_b32_e32 v66, 1, v102
	v_lshl_add_u64 v[92:93], s[54:55], 0, v[130:131]
	v_lshlrev_b64 v[156:157], 11, v[102:103]
	v_ashrrev_i32_e32 v67, 31, v66
	s_waitcnt lgkmcnt(0)
	v_lshl_add_u64 v[64:65], v[92:93], 0, v[156:157]
	v_lshlrev_b64 v[148:149], 11, v[66:67]
	v_lshl_add_u64 v[66:67], v[92:93], 0, v[148:149]
	global_load_dword v110, v[64:65], off
	global_load_dword v111, v[64:65], off offset:128
	global_load_dword v109, v[64:65], off offset:256
	global_load_dword v108, v[64:65], off offset:384
	global_load_dword v106, v[66:67], off
	global_load_dword v107, v[66:67], off offset:128
	global_load_dword v105, v[66:67], off offset:256
	global_load_dword v104, v[66:67], off offset:384
	v_or_b32_e32 v64, 2, v102
	v_or_b32_e32 v66, 3, v102
	v_ashrrev_i32_e32 v65, 31, v64
	v_ashrrev_i32_e32 v67, 31, v66
	v_lshlrev_b64 v[146:147], 11, v[64:65]
	v_lshlrev_b64 v[136:137], 11, v[66:67]
	v_lshl_add_u64 v[64:65], v[92:93], 0, v[146:147]
	v_lshl_add_u64 v[66:67], v[92:93], 0, v[136:137]
	global_load_dword v158, v[64:65], off
	global_load_dword v159, v[64:65], off offset:128
	global_load_dword v155, v[64:65], off offset:256
	global_load_dword v154, v[64:65], off offset:384
	global_load_dword v152, v[66:67], off
	global_load_dword v153, v[66:67], off offset:128
	global_load_dword v151, v[66:67], off offset:256
	global_load_dword v150, v[66:67], off offset:384
	v_or_b32_e32 v64, 8, v102
	v_or_b32_e32 v66, 9, v102
	v_ashrrev_i32_e32 v65, 31, v64
	v_ashrrev_i32_e32 v67, 31, v66
	v_lshlrev_b64 v[134:135], 11, v[64:65]
	v_lshlrev_b64 v[120:121], 11, v[66:67]
	v_lshl_add_u64 v[64:65], v[92:93], 0, v[134:135]
	v_lshl_add_u64 v[66:67], v[92:93], 0, v[120:121]
	global_load_dword v144, v[64:65], off
	global_load_dword v145, v[64:65], off offset:128
	global_load_dword v143, v[64:65], off offset:256
	global_load_dword v142, v[64:65], off offset:384
	global_load_dword v140, v[66:67], off
	global_load_dword v141, v[66:67], off offset:128
	global_load_dword v139, v[66:67], off offset:256
	global_load_dword v138, v[66:67], off offset:384
	v_or_b32_e32 v64, 10, v102
	v_or_b32_e32 v66, 11, v102
	v_ashrrev_i32_e32 v65, 31, v64
	v_ashrrev_i32_e32 v67, 31, v66
	v_lshlrev_b64 v[118:119], 11, v[64:65]
	v_lshlrev_b64 v[90:91], 11, v[66:67]
	v_lshl_add_u64 v[64:65], v[92:93], 0, v[118:119]
	v_lshl_add_u64 v[66:67], v[92:93], 0, v[90:91]
	global_load_dword v132, v[64:65], off
	global_load_dword v133, v[64:65], off offset:128
	global_load_dword v127, v[64:65], off offset:256
	global_load_dword v126, v[64:65], off offset:384
	global_load_dword v124, v[66:67], off
	global_load_dword v125, v[66:67], off offset:128
	global_load_dword v123, v[66:67], off offset:256
	global_load_dword v122, v[66:67], off offset:384
	v_or_b32_e32 v64, 16, v102
	v_or_b32_e32 v66, 17, v102
	v_ashrrev_i32_e32 v65, 31, v64
	v_ashrrev_i32_e32 v67, 31, v66
	v_lshlrev_b64 v[86:87], 11, v[64:65]
	v_lshlrev_b64 v[78:79], 11, v[66:67]
	v_lshl_add_u64 v[64:65], v[92:93], 0, v[86:87]
	v_lshl_add_u64 v[66:67], v[92:93], 0, v[78:79]
	global_load_dword v100, v[64:65], off
	global_load_dword v101, v[64:65], off offset:128
	global_load_dword v99, v[64:65], off offset:256
	global_load_dword v98, v[64:65], off offset:384
	global_load_dword v96, v[66:67], off
	global_load_dword v97, v[66:67], off offset:128
	global_load_dword v95, v[66:67], off offset:256
	global_load_dword v94, v[66:67], off offset:384
	v_or_b32_e32 v64, 18, v102
	v_or_b32_e32 v66, 19, v102
	v_ashrrev_i32_e32 v65, 31, v64
	v_ashrrev_i32_e32 v67, 31, v66
	v_lshlrev_b64 v[76:77], 11, v[64:65]
	v_lshlrev_b64 v[72:73], 11, v[66:67]
	v_lshl_add_u64 v[64:65], v[92:93], 0, v[76:77]
	v_lshl_add_u64 v[66:67], v[92:93], 0, v[72:73]
	v_lshl_add_u32 v169, v69, 2, s0
	global_load_dword v88, v[64:65], off
	global_load_dword v89, v[64:65], off offset:128
	global_load_dword v85, v[64:65], off offset:256
	global_load_dword v84, v[64:65], off offset:384
	global_load_dword v82, v[66:67], off
	global_load_dword v83, v[66:67], off offset:128
	global_load_dword v81, v[66:67], off offset:256
	global_load_dword v80, v[66:67], off offset:384
	ds_read_b128 v[64:67], v169
	v_or_b32_e32 v68, 24, v102
	v_ashrrev_i32_e32 v69, 31, v68
	v_lshlrev_b64 v[74:75], 11, v[68:69]
	ds_read_b128 v[68:71], v169 offset:32
	s_waitcnt lgkmcnt(0)
; DI unsigned short f2bf(float x) { unsigned u = __float_as_uint(x); u += 0x7fffu + ((u >> 16) & 1u); return (unsigned short)(u >> 16); }
; DI float shx(float v, int mask, int lane) { return __int_as_float(__builtin_amdgcn_ds_bpermute((lane ^ mask) << 2, __float_as_int(v))); }
; DI int crow(int r, int hi) { return (r & 3) + 8 * (r >> 2) + 4 * hi; }
; template <int DQK, int MODE, int LDQ, int LDK, int LDV> ...
;     ...
;     for (int r = 0; r < 16; ++r) { const int orow = wid * 32 + crow(r, hi); const float rl = __builtin_amdgcn_rcpf(li_l[crow(r, hi)]);
;         if constexpr (MODE == 0) {
; #pragma unroll
;             for (int d0 = 0; d0 < 4; ++d0) AOb[(size_t)orow * 1024 + d0 * 32 + r32] = f2bf(o[d0][r] * rl);
;         } else if constexpr (MODE == 1) {
; #pragma unroll
;             for (int d0 = 0; d0 < 4; ++d0) S0[(size_t)orow * 512 + d0 * 32 + r32] = o[d0][r] * rl;
;         } else {
;             float v[4]; float ss = 0.f;
; #pragma unroll
;             for (int d0 = 0; d0 < 4; ++d0) { v[d0] = s0v[r][d0] - lam * (o[d0][r] * rl); ss += v[d0] * v[d0]; }
; #pragma unroll
;             for (int mk = 1; mk <= 16; mk <<= 1) ss += shx(ss, mk, lane2);
;             const float rs = rsqrtf(ss * (1.f / 128.f) + EPS) * 0.8f;
; #pragma unroll
;             for (int d0 = 0; d0 < 4; ++d0) AOb[(size_t)orow * 1024 + d0 * 32 + r32] = f2bf(v[d0] * rs * gout[d0 * 32 + r32]);
;         } }
	v_rcp_f32_e32 v64, v64
	v_mov_b32_e32 v162, v0
	v_mov_b32_e32 v163, v48
	v_rcp_f32_e32 v0, v65
	v_pk_mul_f32 v[162:163], v[162:163], v[64:65] op_sel_hi:[1,0]
	v_mov_b32_e32 v48, v1
	v_lshlrev_b32_e32 v166, 2, v114
	v_pk_mul_f32 v[48:49], v[48:49], v[0:1] op_sel_hi:[1,0]
	v_xor_b32_e32 v164, 4, v166
	v_xor_b32_e32 v165, 8, v166
	v_xor_b32_e32 v168, 16, v166
	v_xor_b32_e32 v167, 32, v166
	v_or_b32_e32 v116, 25, v102
	v_ashrrev_i32_e32 v117, 31, v116
	v_xor_b32_e32 v166, 64, v166
	v_lshl_add_u64 v[112:113], v[92:93], 0, v[74:75]
	s_add_u32 s1, s60, s58
	s_mov_b32 s0, 0x358637bd
	s_addc_u32 s3, s61, s59
	s_lshl_b32 s2, s87, 1
	s_add_u32 s2, s1, s2
	s_addc_u32 s3, s3, 0
	s_waitcnt vmcnt(0)
	v_pk_fma_f32 v[172:173], v[128:129], v[162:163], v[110:111] neg_lo:[1,0,0] neg_hi:[1,0,0]
	v_mov_b32_e32 v162, v32
	v_mov_b32_e32 v163, v16
	v_pk_mul_f32 v[162:163], v[162:163], v[64:65] op_sel_hi:[1,0]
	v_mov_b32_e32 v16, v33
	v_pk_fma_f32 v[174:175], v[128:129], v[162:163], v[108:109] neg_lo:[1,0,0] neg_hi:[1,0,0]
	global_load_dword v163, v130, s[50:51]
	global_load_dword v162, v130, s[50:51] offset:128
	global_load_dword v161, v130, s[50:51] offset:256
	s_nop 0
	global_load_dword v130, v130, s[50:51] offset:384
	v_pk_fma_f32 v[176:177], v[128:129], v[48:49], v[106:107] neg_lo:[1,0,0] neg_hi:[1,0,0]
	v_pk_mul_f32 v[0:1], v[16:17], v[0:1] op_sel_hi:[1,0]
	v_pk_mul_f32 v[110:111], v[172:173], v[172:173]
	v_pk_mul_f32 v[48:49], v[176:177], v[176:177]
	v_pk_fma_f32 v[0:1], v[128:129], v[0:1], v[104:105] neg_lo:[1,0,0] neg_hi:[1,0,0]
	v_pk_mul_f32 v[108:109], v[174:175], v[174:175]
	v_pk_mul_f32 v[16:17], v[0:1], v[0:1]
	v_mov_b32_e32 v32, v48
	v_mov_b32_e32 v33, v110
	v_mov_b32_e32 v110, v49
	v_pk_add_f32 v[32:33], v[32:33], v[110:111]
	v_mov_b32_e32 v48, v17
	v_mov_b32_e32 v49, v109
	v_pk_add_f32 v[32:33], v[48:49], v[32:33]
	v_mov_b32_e32 v17, v108
	v_pk_add_f32 v[16:17], v[16:17], v[32:33]
	ds_bpermute_b32 v33, v164, v17
	ds_bpermute_b32 v32, v164, v16
	v_lshlrev_b64 v[64:65], 11, v[116:117]
	v_lshl_add_u64 v[48:49], v[92:93], 0, v[64:65]
	global_load_dword v116, v[112:113], off
	global_load_dword v117, v[112:113], off offset:128
	global_load_dword v115, v[112:113], off offset:256
	global_load_dword v114, v[112:113], off offset:384
	s_nop 0
	global_load_dword v112, v[48:49], off
	global_load_dword v113, v[48:49], off offset:128
	global_load_dword v111, v[48:49], off offset:256
	global_load_dword v110, v[48:49], off offset:384
	v_or_b32_e32 v48, 26, v102
	s_waitcnt lgkmcnt(0)
	v_pk_add_f32 v[16:17], v[16:17], v[32:33]
	ds_bpermute_b32 v33, v165, v17
	ds_bpermute_b32 v32, v165, v16
	v_or_b32_e32 v102, 27, v102
	v_ashrrev_i32_e32 v49, 31, v48
	v_ashrrev_i32_e32 v103, 31, v102
	v_lshlrev_b64 v[48:49], 11, v[48:49]
	s_waitcnt lgkmcnt(0)
	v_pk_add_f32 v[16:17], v[16:17], v[32:33]
	ds_bpermute_b32 v33, v168, v17
	ds_bpermute_b32 v32, v168, v16
	v_lshl_add_u64 v[104:105], v[92:93], 0, v[48:49]
	v_lshlrev_b32_e32 v170, 1, v170
	v_mov_b32_e32 v171, v131
	v_rcp_f32_e32 v66, v66
	s_waitcnt lgkmcnt(0)
	v_pk_add_f32 v[32:33], v[16:17], v[32:33]
	ds_bpermute_b32 v107, v167, v33
	ds_bpermute_b32 v106, v167, v32
	v_lshlrev_b64 v[16:17], 11, v[102:103]
	v_lshl_add_u64 v[92:93], v[92:93], 0, v[16:17]
	s_waitcnt lgkmcnt(0)
	v_pk_add_f32 v[32:33], v[32:33], v[106:107]
	ds_bpermute_b32 v179, v166, v33
	ds_bpermute_b32 v178, v166, v32
	global_load_dword v108, v[104:105], off
	global_load_dword v109, v[104:105], off offset:128
	global_load_dword v107, v[104:105], off offset:256
	global_load_dword v106, v[104:105], off offset:384
	s_nop 0
	global_load_dword v104, v[92:93], off
	global_load_dword v105, v[92:93], off offset:128
	global_load_dword v103, v[92:93], off offset:256
	global_load_dword v102, v[92:93], off offset:384
	v_mov_b64_e32 v[92:93], s[0:1]
	s_waitcnt lgkmcnt(0)
	v_pk_add_f32 v[32:33], v[32:33], v[178:179]
	s_nop 0
	v_pk_fma_f32 v[178:179], v[32:33], s[24:25], v[92:93] op_sel_hi:[1,0,0]
	s_nop 0
	v_mul_f32_e32 v32, 0x4b800000, v179
	v_cmp_gt_f32_e32 vcc, s67, v179
	s_nop 1
	v_cndmask_b32_e32 v32, v179, v32, vcc
	v_rsq_f32_e32 v179, v32
	v_lshl_add_u64 v[32:33], s[2:3], 0, v[170:171]
	v_lshl_add_u64 v[156:157], v[32:33], 0, v[156:157]
	v_lshl_add_u64 v[148:149], v[32:33], 0, v[148:149]
	v_mul_f32_e32 v170, 0x45800000, v179
	v_cndmask_b32_e32 v170, v179, v170, vcc
	v_mul_f32_e32 v170, 0x3f4ccccd, v170
	v_mul_f32_e32 v171, v172, v170
	v_cmp_gt_f32_e32 vcc, s67, v178
	s_mov_b64 s[2:3], 0
	s_waitcnt vmcnt(19)
	v_mul_f32_e32 v171, v163, v171
	v_bfe_u32 v172, v171, 16, 1
	v_add3_u32 v171, v171, v172, s68
	global_store_short_d16_hi v[156:157], v171, off offset:1024
	v_mul_f32_e32 v171, v173, v170
	s_waitcnt vmcnt(19)
	v_mul_f32_e32 v171, v162, v171
	v_bfe_u32 v172, v171, 16, 1
	v_add3_u32 v171, v171, v172, s68
	global_store_short_d16_hi v[156:157], v171, off offset:1088
	v_mul_f32_e32 v171, v175, v170
	s_waitcnt vmcnt(19)
	v_mul_f32_e32 v171, v161, v171
	v_bfe_u32 v172, v171, 16, 1
	v_add3_u32 v171, v171, v172, s68
	global_store_short_d16_hi v[156:157], v171, off offset:1152
	v_mul_f32_e32 v171, 0x4b800000, v178
	v_cndmask_b32_e32 v171, v178, v171, vcc
	v_mul_f32_e32 v170, v174, v170
	v_rsq_f32_e32 v171, v171
	s_waitcnt vmcnt(19)
; DI unsigned short f2bf(float x) { unsigned u = __float_as_uint(x); u += 0x7fffu + ((u >> 16) & 1u); return (unsigned short)(u >> 16); }
; DI float shx(float v, int mask, int lane) { return __int_as_float(__builtin_amdgcn_ds_bpermute((lane ^ mask) << 2, __float_as_int(v))); }
; DI int crow(int r, int hi) { return (r & 3) + 8 * (r >> 2) + 4 * hi; }
; template <int DQK, int MODE, int LDQ, int LDK, int LDV> ...
;     ...
;     for (int r = 0; r < 16; ++r) { const int orow = wid * 32 + crow(r, hi); const float rl = __builtin_amdgcn_rcpf(li_l[crow(r, hi)]);
;         if constexpr (MODE == 0) {
; #pragma unroll
;             for (int d0 = 0; d0 < 4; ++d0) AOb[(size_t)orow * 1024 + d0 * 32 + r32] = f2bf(o[d0][r] * rl);
;         } else if constexpr (MODE == 1) {
; #pragma unroll
;             for (int d0 = 0; d0 < 4; ++d0) S0[(size_t)orow * 512 + d0 * 32 + r32] = o[d0][r] * rl;
;         } else {
;             float v[4]; float ss = 0.f;
; #pragma unroll
;             for (int d0 = 0; d0 < 4; ++d0) { v[d0] = s0v[r][d0] - lam * (o[d0][r] * rl); ss += v[d0] * v[d0]; }
; #pragma unroll
;             for (int mk = 1; mk <= 16; mk <<= 1) ss += shx(ss, mk, lane2);
;             const float rs = rsqrtf(ss * (1.f / 128.f) + EPS) * 0.8f;
; #pragma unroll
;             for (int d0 = 0; d0 < 4; ++d0) AOb[(size_t)orow * 1024 + d0 * 32 + r32] = f2bf(v[d0] * rs * gout[d0 * 32 + r32]);
;         } }
	v_mul_f32_e32 v170, v130, v170
	v_bfe_u32 v172, v170, 16, 1
	v_add3_u32 v170, v170, v172, s68
	global_store_short_d16_hi v[156:157], v170, off offset:1216
	v_mul_f32_e32 v156, 0x45800000, v171
	v_cndmask_b32_e32 v172, v171, v156, vcc
	v_mov_b32_e32 v156, v2
	v_rcp_f32_e32 v2, v67
	v_mov_b32_e32 v157, v50
	v_mov_b32_e32 v50, v3
	v_pk_mul_f32 v[156:157], v[156:157], v[66:67] op_sel_hi:[1,0]
	v_mov_b32_e32 v170, v34
	v_mov_b32_e32 v171, v18
	v_pk_mul_f32 v[50:51], v[50:51], v[2:3] op_sel_hi:[1,0]
	v_mov_b32_e32 v18, v35
	v_pk_fma_f32 v[156:157], v[128:129], v[156:157], v[158:159] neg_lo:[1,0,0] neg_hi:[1,0,0]
	v_pk_mul_f32 v[170:171], v[170:171], v[66:67] op_sel_hi:[1,0]
	v_pk_fma_f32 v[50:51], v[128:129], v[50:51], v[152:153] neg_lo:[1,0,0] neg_hi:[1,0,0]
	v_pk_mul_f32 v[2:3], v[18:19], v[2:3] op_sel_hi:[1,0]
	v_pk_mul_f32 v[158:159], v[156:157], v[156:157]
	v_pk_fma_f32 v[66:67], v[128:129], v[170:171], v[154:155] neg_lo:[1,0,0] neg_hi:[1,0,0]
	v_pk_mul_f32 v[152:153], v[50:51], v[50:51]
	v_pk_fma_f32 v[2:3], v[128:129], v[2:3], v[150:151] neg_lo:[1,0,0] neg_hi:[1,0,0]
	v_pk_mul_f32 v[154:155], v[66:67], v[66:67]
	v_pk_mul_f32 v[18:19], v[2:3], v[2:3]
	v_mov_b32_e32 v34, v152
	v_mov_b32_e32 v35, v158
	v_mov_b32_e32 v158, v153
	v_pk_add_f32 v[34:35], v[34:35], v[158:159]
	v_mov_b32_e32 v150, v19
	v_mov_b32_e32 v151, v155
	v_pk_add_f32 v[34:35], v[150:151], v[34:35]
	v_mov_b32_e32 v19, v154
	v_pk_add_f32 v[18:19], v[18:19], v[34:35]
	ds_bpermute_b32 v35, v164, v19
	ds_bpermute_b32 v34, v164, v18
	v_mul_f32_e32 v150, 0x3f4ccccd, v172
	v_mul_f32_e32 v151, v176, v150
	v_mul_f32_e32 v151, v163, v151
	v_bfe_u32 v152, v151, 16, 1
	s_waitcnt lgkmcnt(0)
	v_pk_add_f32 v[18:19], v[18:19], v[34:35]
	ds_bpermute_b32 v35, v165, v19
	ds_bpermute_b32 v34, v165, v18
	v_add3_u32 v151, v151, v152, s68
	global_store_short_d16_hi v[148:149], v151, off offset:1024
	v_mul_f32_e32 v151, v177, v150
	v_mul_f32_e32 v151, v162, v151
	s_waitcnt lgkmcnt(0)
	v_pk_add_f32 v[18:19], v[18:19], v[34:35]
	ds_bpermute_b32 v35, v168, v19
	ds_bpermute_b32 v34, v168, v18
	v_bfe_u32 v152, v151, 16, 1
	v_mul_f32_e32 v1, v1, v150
	v_add3_u32 v151, v151, v152, s68
	v_mul_f32_e32 v1, v161, v1
	s_waitcnt lgkmcnt(0)
	v_pk_add_f32 v[18:19], v[18:19], v[34:35]
	ds_bpermute_b32 v35, v167, v19
	ds_bpermute_b32 v34, v167, v18
	global_store_short_d16_hi v[148:149], v151, off offset:1088
	v_bfe_u32 v151, v1, 16, 1
	v_add3_u32 v1, v1, v151, s68
	v_mul_f32_e32 v0, v0, v150
	s_waitcnt lgkmcnt(0)
	v_pk_add_f32 v[18:19], v[18:19], v[34:35]
	ds_bpermute_b32 v35, v166, v19
	ds_bpermute_b32 v34, v166, v18
	global_store_short_d16_hi v[148:149], v1, off offset:1152
	v_mul_f32_e32 v150, v130, v0
	v_bfe_u32 v151, v150, 16, 1
	s_waitcnt lgkmcnt(0)
	v_pk_add_f32 v[0:1], v[18:19], v[34:35]
	s_nop 0
	v_pk_fma_f32 v[0:1], v[0:1], s[24:25], v[92:93] op_sel_hi:[1,0,0]
	s_nop 0
	v_mul_f32_e32 v18, 0x4b800000, v1
	v_cmp_gt_f32_e32 vcc, s67, v1
	s_nop 1
	v_cndmask_b32_e32 v1, v1, v18, vcc
	v_rsq_f32_e32 v1, v1
	v_add3_u32 v18, v150, v151, s68
	global_store_short_d16_hi v[148:149], v18, off offset:1216
	v_lshl_add_u64 v[18:19], v[32:33], 0, v[146:147]
	v_mul_f32_e32 v34, 0x45800000, v1
	v_cndmask_b32_e32 v1, v1, v34, vcc
	v_mul_f32_e32 v1, 0x3f4ccccd, v1
	v_mul_f32_e32 v34, v156, v1
	v_mul_f32_e32 v34, v163, v34
	v_bfe_u32 v35, v34, 16, 1
	v_add3_u32 v34, v34, v35, s68
	global_store_short_d16_hi v[18:19], v34, off offset:1024
	v_mul_f32_e32 v34, v157, v1
	v_mul_f32_e32 v34, v162, v34
	v_bfe_u32 v35, v34, 16, 1
	v_add3_u32 v34, v34, v35, s68
	global_store_short_d16_hi v[18:19], v34, off offset:1088
	v_mul_f32_e32 v34, v67, v1
	v_mul_f32_e32 v34, v161, v34
	v_bfe_u32 v35, v34, 16, 1
	v_add3_u32 v34, v34, v35, s68
	global_store_short_d16_hi v[18:19], v34, off offset:1152
	v_mul_f32_e32 v1, v66, v1
	v_mul_f32_e32 v34, 0x4b800000, v0
	v_cmp_gt_f32_e32 vcc, s67, v0
	v_mul_f32_e32 v1, v130, v1
	v_mov_b32_e32 v66, v36
	v_cndmask_b32_e32 v0, v0, v34, vcc
	v_rsq_f32_e32 v34, v0
	v_bfe_u32 v0, v1, 16, 1
	v_add3_u32 v0, v1, v0, s68
	global_store_short_d16_hi v[18:19], v0, off offset:1216
	v_rcp_f32_e32 v0, v68
	v_mov_b32_e32 v18, v4
	v_rcp_f32_e32 v4, v69
	v_mul_f32_e32 v1, 0x45800000, v34
	v_mov_b32_e32 v19, v52
	v_mov_b32_e32 v52, v5
	v_pk_mul_f32 v[18:19], v[18:19], v[0:1] op_sel_hi:[1,0]
	v_mov_b32_e32 v67, v20
	v_pk_mul_f32 v[52:53], v[52:53], v[4:5] op_sel_hi:[1,0]
	v_mov_b32_e32 v20, v37
	v_cndmask_b32_e32 v146, v34, v1, vcc
	v_pk_fma_f32 v[18:19], v[128:129], v[18:19], v[144:145] neg_lo:[1,0,0] neg_hi:[1,0,0]
	v_pk_mul_f32 v[0:1], v[66:67], v[0:1] op_sel_hi:[1,0]
	v_pk_fma_f32 v[52:53], v[128:129], v[52:53], v[140:141] neg_lo:[1,0,0] neg_hi:[1,0,0]
	v_pk_mul_f32 v[4:5], v[20:21], v[4:5] op_sel_hi:[1,0]
	v_pk_mul_f32 v[34:35], v[18:19], v[18:19]
	v_pk_fma_f32 v[0:1], v[128:129], v[0:1], v[142:143] neg_lo:[1,0,0] neg_hi:[1,0,0]
	v_pk_mul_f32 v[68:69], v[52:53], v[52:53]
	v_pk_fma_f32 v[4:5], v[128:129], v[4:5], v[138:139] neg_lo:[1,0,0] neg_hi:[1,0,0]
	v_pk_mul_f32 v[66:67], v[0:1], v[0:1]
	v_pk_mul_f32 v[20:21], v[4:5], v[4:5]
	v_mov_b32_e32 v36, v68
	v_mov_b32_e32 v37, v34
	v_mov_b32_e32 v34, v69
	v_pk_add_f32 v[34:35], v[36:37], v[34:35]
	v_mov_b32_e32 v36, v21
	v_mov_b32_e32 v37, v67
	v_pk_add_f32 v[34:35], v[36:37], v[34:35]
	v_mov_b32_e32 v21, v66
	v_pk_add_f32 v[20:21], v[20:21], v[34:35]
	ds_bpermute_b32 v35, v164, v21
	ds_bpermute_b32 v34, v164, v20
	v_mul_f32_e32 v66, 0x3f4ccccd, v146
	v_mul_f32_e32 v50, v50, v66
	v_mul_f32_e32 v50, v163, v50
	v_bfe_u32 v67, v50, 16, 1
	s_waitcnt lgkmcnt(0)
; DI unsigned short f2bf(float x) { unsigned u = __float_as_uint(x); u += 0x7fffu + ((u >> 16) & 1u); return (unsigned short)(u >> 16); }
; DI float shx(float v, int mask, int lane) { return __int_as_float(__builtin_amdgcn_ds_bpermute((lane ^ mask) << 2, __float_as_int(v))); }
; DI int crow(int r, int hi) { return (r & 3) + 8 * (r >> 2) + 4 * hi; }
; template <int DQK, int MODE, int LDQ, int LDK, int LDV> ...
;     ...
;     for (int r = 0; r < 16; ++r) { const int orow = wid * 32 + crow(r, hi); const float rl = __builtin_amdgcn_rcpf(li_l[crow(r, hi)]);
;         if constexpr (MODE == 0) {
; #pragma unroll
;             for (int d0 = 0; d0 < 4; ++d0) AOb[(size_t)orow * 1024 + d0 * 32 + r32] = f2bf(o[d0][r] * rl);
;         } else if constexpr (MODE == 1) {
; #pragma unroll
;             for (int d0 = 0; d0 < 4; ++d0) S0[(size_t)orow * 512 + d0 * 32 + r32] = o[d0][r] * rl;
;         } else {
;             float v[4]; float ss = 0.f;
; #pragma unroll
;             for (int d0 = 0; d0 < 4; ++d0) { v[d0] = s0v[r][d0] - lam * (o[d0][r] * rl); ss += v[d0] * v[d0]; }
; #pragma unroll
;             for (int mk = 1; mk <= 16; mk <<= 1) ss += shx(ss, mk, lane2);
;             const float rs = rsqrtf(ss * (1.f / 128.f) + EPS) * 0.8f;
; #pragma unroll
;             for (int d0 = 0; d0 < 4; ++d0) AOb[(size_t)orow * 1024 + d0 * 32 + r32] = f2bf(v[d0] * rs * gout[d0 * 32 + r32]);
;         } }
	v_pk_add_f32 v[20:21], v[20:21], v[34:35]
	ds_bpermute_b32 v35, v165, v21
	ds_bpermute_b32 v34, v165, v20
	v_lshl_add_u64 v[36:37], v[32:33], 0, v[136:137]
	v_add3_u32 v50, v50, v67, s68
	global_store_short_d16_hi v[36:37], v50, off offset:1024
	v_mul_f32_e32 v50, v51, v66
	s_waitcnt lgkmcnt(0)
	v_pk_add_f32 v[20:21], v[20:21], v[34:35]
	ds_bpermute_b32 v35, v168, v21
	ds_bpermute_b32 v34, v168, v20
	v_mul_f32_e32 v50, v162, v50
	v_bfe_u32 v51, v50, 16, 1
	v_mul_f32_e32 v3, v3, v66
	v_add3_u32 v50, v50, v51, s68
	s_waitcnt lgkmcnt(0)
	v_pk_add_f32 v[20:21], v[20:21], v[34:35]
	ds_bpermute_b32 v35, v167, v21
	ds_bpermute_b32 v34, v167, v20
	v_mul_f32_e32 v3, v161, v3
	global_store_short_d16_hi v[36:37], v50, off offset:1088
	v_bfe_u32 v50, v3, 16, 1
	v_add3_u32 v3, v3, v50, s68
	s_waitcnt lgkmcnt(0)
	v_pk_add_f32 v[20:21], v[20:21], v[34:35]
	ds_bpermute_b32 v35, v166, v21
	ds_bpermute_b32 v34, v166, v20
	v_mul_f32_e32 v2, v2, v66
	global_store_short_d16_hi v[36:37], v3, off offset:1152
	v_mul_f32_e32 v50, v130, v2
	v_bfe_u32 v51, v50, 16, 1
	s_waitcnt lgkmcnt(0)
	v_pk_add_f32 v[2:3], v[20:21], v[34:35]
	s_nop 0
	v_pk_fma_f32 v[2:3], v[2:3], s[24:25], v[92:93] op_sel_hi:[1,0,0]
	s_nop 0
	v_mul_f32_e32 v20, 0x4b800000, v3
	v_cmp_gt_f32_e32 vcc, s67, v3
	s_nop 1
	v_cndmask_b32_e32 v3, v3, v20, vcc
	v_rsq_f32_e32 v3, v3
	v_add3_u32 v20, v50, v51, s68
	global_store_short_d16_hi v[36:37], v20, off offset:1216
	v_lshl_add_u64 v[20:21], v[32:33], 0, v[134:135]
	v_mul_f32_e32 v34, 0x45800000, v3
	v_cndmask_b32_e32 v3, v3, v34, vcc
	v_mul_f32_e32 v3, 0x3f4ccccd, v3
	v_mul_f32_e32 v18, v18, v3
	v_mul_f32_e32 v18, v163, v18
	v_bfe_u32 v34, v18, 16, 1
	v_add3_u32 v18, v18, v34, s68
	global_store_short_d16_hi v[20:21], v18, off offset:1024
	v_mul_f32_e32 v18, v19, v3
	v_mul_f32_e32 v18, v162, v18
	v_bfe_u32 v19, v18, 16, 1
	v_mul_f32_e32 v1, v1, v3
	v_add3_u32 v18, v18, v19, s68
	v_mul_f32_e32 v1, v161, v1
	global_store_short_d16_hi v[20:21], v18, off offset:1088
	v_bfe_u32 v18, v1, 16, 1
	v_add3_u32 v1, v1, v18, s68
	global_store_short_d16_hi v[20:21], v1, off offset:1152
	v_mul_f32_e32 v1, 0x4b800000, v2
	v_cmp_gt_f32_e32 vcc, s67, v2
	v_mul_f32_e32 v0, v0, v3
	v_mul_f32_e32 v0, v130, v0
	v_cndmask_b32_e32 v1, v2, v1, vcc
	v_rsq_f32_e32 v1, v1
	v_bfe_u32 v2, v0, 16, 1
	v_add3_u32 v0, v0, v2, s68
	global_store_short_d16_hi v[20:21], v0, off offset:1216
	v_mul_f32_e32 v2, 0x45800000, v1
	v_rcp_f32_e32 v0, v70
	v_cndmask_b32_e32 v66, v1, v2, vcc
	v_mov_b32_e32 v2, v6
	v_rcp_f32_e32 v6, v71
	v_mov_b32_e32 v3, v54
	v_mov_b32_e32 v18, v38
	v_mov_b32_e32 v19, v22
	v_mov_b32_e32 v54, v7
	v_pk_mul_f32 v[2:3], v[2:3], v[0:1] op_sel_hi:[1,0]
	v_pk_mul_f32 v[0:1], v[18:19], v[0:1] op_sel_hi:[1,0]
	v_pk_mul_f32 v[18:19], v[54:55], v[6:7] op_sel_hi:[1,0]
	v_mov_b32_e32 v22, v39
	v_pk_fma_f32 v[2:3], v[128:129], v[2:3], v[132:133] neg_lo:[1,0,0] neg_hi:[1,0,0]
	v_pk_fma_f32 v[20:21], v[128:129], v[18:19], v[124:125] neg_lo:[1,0,0] neg_hi:[1,0,0]
	v_pk_mul_f32 v[6:7], v[22:23], v[6:7] op_sel_hi:[1,0]
	v_pk_mul_f32 v[34:35], v[2:3], v[2:3]
	v_pk_fma_f32 v[0:1], v[128:129], v[0:1], v[126:127] neg_lo:[1,0,0] neg_hi:[1,0,0]
	v_pk_mul_f32 v[50:51], v[20:21], v[20:21]
	v_pk_fma_f32 v[18:19], v[128:129], v[6:7], v[122:123] neg_lo:[1,0,0] neg_hi:[1,0,0]
	v_pk_mul_f32 v[36:37], v[0:1], v[0:1]
	v_pk_mul_f32 v[6:7], v[18:19], v[18:19]
	v_mov_b32_e32 v22, v50
	v_mov_b32_e32 v23, v34
	v_mov_b32_e32 v34, v51
	v_pk_add_f32 v[22:23], v[22:23], v[34:35]
	v_mov_b32_e32 v34, v7
	v_mov_b32_e32 v35, v37
	v_pk_add_f32 v[22:23], v[34:35], v[22:23]
	v_mov_b32_e32 v7, v36
	v_pk_add_f32 v[6:7], v[6:7], v[22:23]
	ds_bpermute_b32 v23, v164, v7
	ds_bpermute_b32 v22, v164, v6
	v_mul_f32_e32 v36, 0x3f4ccccd, v66
	v_mul_f32_e32 v37, v52, v36
	v_mul_f32_e32 v37, v163, v37
	v_bfe_u32 v38, v37, 16, 1
	s_waitcnt lgkmcnt(0)
	v_pk_add_f32 v[6:7], v[6:7], v[22:23]
	ds_bpermute_b32 v23, v165, v7
	ds_bpermute_b32 v22, v165, v6
	v_lshl_add_u64 v[34:35], v[32:33], 0, v[120:121]
	v_add3_u32 v37, v37, v38, s68
	global_store_short_d16_hi v[34:35], v37, off offset:1024
	v_mul_f32_e32 v37, v53, v36
	s_waitcnt lgkmcnt(0)
	v_pk_add_f32 v[6:7], v[6:7], v[22:23]
	ds_bpermute_b32 v23, v168, v7
	ds_bpermute_b32 v22, v168, v6
	v_mul_f32_e32 v37, v162, v37
	v_bfe_u32 v38, v37, 16, 1
	v_mul_f32_e32 v5, v5, v36
	v_add3_u32 v37, v37, v38, s68
	s_waitcnt lgkmcnt(0)
	v_pk_add_f32 v[6:7], v[6:7], v[22:23]
	ds_bpermute_b32 v23, v167, v7
	ds_bpermute_b32 v22, v167, v6
	v_mul_f32_e32 v5, v161, v5
	global_store_short_d16_hi v[34:35], v37, off offset:1088
	v_bfe_u32 v37, v5, 16, 1
	v_add3_u32 v5, v5, v37, s68
	s_waitcnt lgkmcnt(0)
	v_pk_add_f32 v[6:7], v[6:7], v[22:23]
	ds_bpermute_b32 v23, v166, v7
	ds_bpermute_b32 v22, v166, v6
	v_mul_f32_e32 v4, v4, v36
	global_store_short_d16_hi v[34:35], v5, off offset:1152
	v_mul_f32_e32 v36, v130, v4
	v_bfe_u32 v37, v36, 16, 1
	s_waitcnt lgkmcnt(0)
	v_pk_add_f32 v[4:5], v[6:7], v[22:23]
	v_lshl_add_u64 v[22:23], v[32:33], 0, v[118:119]
	v_pk_fma_f32 v[4:5], v[4:5], s[24:25], v[92:93] op_sel_hi:[1,0,0]
	s_nop 0
	v_mul_f32_e32 v6, 0x4b800000, v5
	v_cmp_gt_f32_e32 vcc, s67, v5
	s_nop 1
	v_cndmask_b32_e32 v5, v5, v6, vcc
	v_rsq_f32_e32 v5, v5
	v_add3_u32 v6, v36, v37, s68
	global_store_short_d16_hi v[34:35], v6, off offset:1216
	v_mov_b32_e32 v36, v40
	v_mul_f32_e32 v6, 0x45800000, v5
	v_cndmask_b32_e32 v5, v5, v6, vcc
	v_mul_f32_e32 v5, 0x3f4ccccd, v5
	v_mul_f32_e32 v2, v2, v5
	v_mul_f32_e32 v2, v163, v2
	v_bfe_u32 v6, v2, 16, 1
	v_add3_u32 v2, v2, v6, s68
	global_store_short_d16_hi v[22:23], v2, off offset:1024
	v_mul_f32_e32 v2, v3, v5
	v_mul_f32_e32 v2, v162, v2
	v_bfe_u32 v3, v2, 16, 1
	v_mul_f32_e32 v1, v1, v5
	v_add3_u32 v2, v2, v3, s68
	v_mul_f32_e32 v1, v161, v1
	global_store_short_d16_hi v[22:23], v2, off offset:1088
	v_bfe_u32 v2, v1, 16, 1
	v_add3_u32 v1, v1, v2, s68
	v_mul_f32_e32 v2, 0x4b800000, v4
	v_cmp_gt_f32_e32 vcc, s67, v4
	v_mul_f32_e32 v0, v0, v5
	v_mul_f32_e32 v0, v130, v0
	v_cndmask_b32_e32 v2, v4, v2, vcc
	ds_read_b128 v[4:7], v169 offset:64
	global_store_short_d16_hi v[22:23], v1, off offset:1152
	v_bfe_u32 v1, v0, 16, 1
	v_rsq_f32_e32 v34, v2
	v_add3_u32 v0, v0, v1, s68
	global_store_short_d16_hi v[22:23], v0, off offset:1216
	ds_read_b128 v[0:3], v169 offset:96
	s_waitcnt lgkmcnt(1)
; DI unsigned short f2bf(float x) { unsigned u = __float_as_uint(x); u += 0x7fffu + ((u >> 16) & 1u); return (unsigned short)(u >> 16); }
; DI float shx(float v, int mask, int lane) { return __int_as_float(__builtin_amdgcn_ds_bpermute((lane ^ mask) << 2, __float_as_int(v))); }
; DI int crow(int r, int hi) { return (r & 3) + 8 * (r >> 2) + 4 * hi; }
; template <int DQK, int MODE, int LDQ, int LDK, int LDV> ...
;     ...
;     for (int r = 0; r < 16; ++r) { const int orow = wid * 32 + crow(r, hi); const float rl = __builtin_amdgcn_rcpf(li_l[crow(r, hi)]);
;         if constexpr (MODE == 0) {
; #pragma unroll
;             for (int d0 = 0; d0 < 4; ++d0) AOb[(size_t)orow * 1024 + d0 * 32 + r32] = f2bf(o[d0][r] * rl);
;         } else if constexpr (MODE == 1) {
; #pragma unroll
;             for (int d0 = 0; d0 < 4; ++d0) S0[(size_t)orow * 512 + d0 * 32 + r32] = o[d0][r] * rl;
;         } else {
;             float v[4]; float ss = 0.f;
; #pragma unroll
;             for (int d0 = 0; d0 < 4; ++d0) { v[d0] = s0v[r][d0] - lam * (o[d0][r] * rl); ss += v[d0] * v[d0]; }
; #pragma unroll
;             for (int mk = 1; mk <= 16; mk <<= 1) ss += shx(ss, mk, lane2);
;             const float rs = rsqrtf(ss * (1.f / 128.f) + EPS) * 0.8f;
; #pragma unroll
;             for (int d0 = 0; d0 < 4; ++d0) AOb[(size_t)orow * 1024 + d0 * 32 + r32] = f2bf(v[d0] * rs * gout[d0 * 32 + r32]);
;         } }
	v_rcp_f32_e32 v4, v4
	v_mul_f32_e32 v22, 0x45800000, v34
	v_cndmask_b32_e32 v52, v34, v22, vcc
	v_mov_b32_e32 v22, v8
	v_mov_b32_e32 v23, v56
	v_mov_b32_e32 v37, v24
	v_pk_mul_f32 v[22:23], v[22:23], v[4:5] op_sel_hi:[1,0]
	v_pk_mul_f32 v[36:37], v[36:37], v[4:5] op_sel_hi:[1,0]
	v_rcp_f32_e32 v4, v5
	v_mov_b32_e32 v56, v9
	v_mov_b32_e32 v24, v41
	v_pk_fma_f32 v[22:23], v[128:129], v[22:23], v[100:101] neg_lo:[1,0,0] neg_hi:[1,0,0]
	v_pk_mul_f32 v[8:9], v[56:57], v[4:5] op_sel_hi:[1,0]
	v_pk_mul_f32 v[4:5], v[24:25], v[4:5] op_sel_hi:[1,0]
	v_pk_fma_f32 v[8:9], v[128:129], v[8:9], v[96:97] neg_lo:[1,0,0] neg_hi:[1,0,0]
	v_pk_mul_f32 v[34:35], v[22:23], v[22:23]
	v_pk_fma_f32 v[36:37], v[128:129], v[36:37], v[98:99] neg_lo:[1,0,0] neg_hi:[1,0,0]
	v_pk_mul_f32 v[50:51], v[8:9], v[8:9]
	v_pk_fma_f32 v[4:5], v[128:129], v[4:5], v[94:95] neg_lo:[1,0,0] neg_hi:[1,0,0]
	v_pk_mul_f32 v[38:39], v[36:37], v[36:37]
	v_pk_mul_f32 v[24:25], v[4:5], v[4:5]
	v_mov_b32_e32 v40, v50
	v_mov_b32_e32 v41, v34
	v_mov_b32_e32 v34, v51
	v_pk_add_f32 v[34:35], v[40:41], v[34:35]
	v_mov_b32_e32 v40, v25
	v_mov_b32_e32 v41, v39
	v_pk_add_f32 v[34:35], v[40:41], v[34:35]
	v_mov_b32_e32 v25, v38
	v_pk_add_f32 v[24:25], v[24:25], v[34:35]
	ds_bpermute_b32 v35, v164, v25
	ds_bpermute_b32 v34, v164, v24
	v_mul_f32_e32 v40, 0x3f4ccccd, v52
	v_mul_f32_e32 v20, v20, v40
	v_mul_f32_e32 v20, v163, v20
	v_bfe_u32 v41, v20, 16, 1
	s_waitcnt lgkmcnt(0)
	v_pk_add_f32 v[24:25], v[24:25], v[34:35]
	ds_bpermute_b32 v35, v165, v25
	ds_bpermute_b32 v34, v165, v24
	v_lshl_add_u64 v[38:39], v[32:33], 0, v[90:91]
	v_add3_u32 v20, v20, v41, s68
	global_store_short_d16_hi v[38:39], v20, off offset:1024
	v_mul_f32_e32 v41, v21, v40
	s_waitcnt lgkmcnt(0)
	v_pk_add_f32 v[20:21], v[24:25], v[34:35]
	ds_bpermute_b32 v25, v168, v21
	ds_bpermute_b32 v24, v168, v20
	v_mul_f32_e32 v34, v162, v41
	v_bfe_u32 v35, v34, 16, 1
	v_mul_f32_e32 v19, v19, v40
	v_add3_u32 v34, v34, v35, s68
	s_waitcnt lgkmcnt(0)
	v_pk_add_f32 v[20:21], v[20:21], v[24:25]
	ds_bpermute_b32 v25, v167, v21
	ds_bpermute_b32 v24, v167, v20
	v_mul_f32_e32 v19, v161, v19
	global_store_short_d16_hi v[38:39], v34, off offset:1088
	v_bfe_u32 v34, v19, 16, 1
	v_add3_u32 v19, v19, v34, s68
	s_waitcnt lgkmcnt(0)
	v_pk_add_f32 v[20:21], v[20:21], v[24:25]
	ds_bpermute_b32 v25, v166, v21
	ds_bpermute_b32 v24, v166, v20
	v_mul_f32_e32 v18, v18, v40
	global_store_short_d16_hi v[38:39], v19, off offset:1152
	v_mul_f32_e32 v34, v130, v18
	v_bfe_u32 v35, v34, 16, 1
	s_waitcnt lgkmcnt(0)
	v_pk_add_f32 v[18:19], v[20:21], v[24:25]
	v_rcp_f32_e32 v6, v6
	v_pk_fma_f32 v[18:19], v[18:19], s[24:25], v[92:93] op_sel_hi:[1,0,0]
	v_rcp_f32_e32 v0, v0
	v_mul_f32_e32 v20, 0x4b800000, v19
	v_cmp_gt_f32_e32 vcc, s67, v19
	v_rcp_f32_e32 v2, v2
	s_nop 0
	v_cndmask_b32_e32 v19, v19, v20, vcc
	v_rsq_f32_e32 v19, v19
	v_add3_u32 v20, v34, v35, s68
	global_store_short_d16_hi v[38:39], v20, off offset:1216
	v_lshl_add_u64 v[20:21], v[32:33], 0, v[86:87]
	v_mul_f32_e32 v24, 0x45800000, v19
	v_cndmask_b32_e32 v19, v19, v24, vcc
	v_mul_f32_e32 v19, 0x3f4ccccd, v19
	v_mul_f32_e32 v22, v22, v19
	v_mul_f32_e32 v22, v163, v22
	v_bfe_u32 v24, v22, 16, 1
	v_add3_u32 v22, v22, v24, s68
	global_store_short_d16_hi v[20:21], v22, off offset:1024
	v_mul_f32_e32 v22, v23, v19
	v_mul_f32_e32 v22, v162, v22
	v_bfe_u32 v23, v22, 16, 1
	v_add3_u32 v22, v22, v23, s68
	global_store_short_d16_hi v[20:21], v22, off offset:1088
	v_mul_f32_e32 v22, v37, v19
	v_mul_f32_e32 v22, v161, v22
	v_bfe_u32 v23, v22, 16, 1
	v_add3_u32 v22, v22, v23, s68
	global_store_short_d16_hi v[20:21], v22, off offset:1152
	v_mul_f32_e32 v22, 0x4b800000, v18
	v_cmp_gt_f32_e32 vcc, s67, v18
	v_mul_f32_e32 v19, v36, v19
	v_mul_f32_e32 v19, v130, v19
	v_cndmask_b32_e32 v18, v18, v22, vcc
	v_rsq_f32_e32 v18, v18
	v_bfe_u32 v22, v19, 16, 1
	v_add3_u32 v19, v19, v22, s68
	global_store_short_d16_hi v[20:21], v19, off offset:1216
	v_mul_f32_e32 v19, 0x45800000, v18
	v_cndmask_b32_e32 v38, v18, v19, vcc
	v_mov_b32_e32 v18, v10
	v_mov_b32_e32 v19, v58
	v_mov_b32_e32 v22, v42
	v_mov_b32_e32 v23, v26
	v_pk_mul_f32 v[18:19], v[18:19], v[6:7] op_sel_hi:[1,0]
	v_pk_mul_f32 v[22:23], v[22:23], v[6:7] op_sel_hi:[1,0]
	v_rcp_f32_e32 v6, v7
	v_mov_b32_e32 v58, v11
	v_mov_b32_e32 v26, v43
	v_pk_fma_f32 v[18:19], v[128:129], v[18:19], v[88:89] neg_lo:[1,0,0] neg_hi:[1,0,0]
	v_pk_mul_f32 v[10:11], v[58:59], v[6:7] op_sel_hi:[1,0]
	v_pk_mul_f32 v[6:7], v[26:27], v[6:7] op_sel_hi:[1,0]
	v_pk_fma_f32 v[10:11], v[128:129], v[10:11], v[82:83] neg_lo:[1,0,0] neg_hi:[1,0,0]
	v_pk_mul_f32 v[20:21], v[18:19], v[18:19]
	v_pk_fma_f32 v[22:23], v[128:129], v[22:23], v[84:85] neg_lo:[1,0,0] neg_hi:[1,0,0]
	v_pk_mul_f32 v[34:35], v[10:11], v[10:11]
	v_pk_fma_f32 v[6:7], v[128:129], v[6:7], v[80:81] neg_lo:[1,0,0] neg_hi:[1,0,0]
	v_pk_mul_f32 v[24:25], v[22:23], v[22:23]
	v_pk_mul_f32 v[26:27], v[6:7], v[6:7]
	v_mov_b32_e32 v36, v34
	v_mov_b32_e32 v37, v20
	v_mov_b32_e32 v20, v35
	v_pk_add_f32 v[20:21], v[36:37], v[20:21]
	v_mov_b32_e32 v34, v27
	v_mov_b32_e32 v35, v25
	v_pk_add_f32 v[20:21], v[34:35], v[20:21]
	v_mov_b32_e32 v27, v24
	v_pk_add_f32 v[20:21], v[26:27], v[20:21]
	ds_bpermute_b32 v25, v164, v21
	ds_bpermute_b32 v24, v164, v20
	v_mul_f32_e32 v34, 0x3f4ccccd, v38
	v_mul_f32_e32 v8, v8, v34
	v_mul_f32_e32 v8, v163, v8
	v_bfe_u32 v35, v8, 16, 1
	s_waitcnt lgkmcnt(0)
	v_pk_add_f32 v[20:21], v[20:21], v[24:25]
	ds_bpermute_b32 v25, v165, v21
	ds_bpermute_b32 v24, v165, v20
	v_lshl_add_u64 v[26:27], v[32:33], 0, v[78:79]
	v_add3_u32 v8, v8, v35, s68
	global_store_short_d16_hi v[26:27], v8, off offset:1024
	v_mul_f32_e32 v35, v9, v34
	s_waitcnt lgkmcnt(0)
; DI unsigned short f2bf(float x) { unsigned u = __float_as_uint(x); u += 0x7fffu + ((u >> 16) & 1u); return (unsigned short)(u >> 16); }
; DI float shx(float v, int mask, int lane) { return __int_as_float(__builtin_amdgcn_ds_bpermute((lane ^ mask) << 2, __float_as_int(v))); }
; DI int crow(int r, int hi) { return (r & 3) + 8 * (r >> 2) + 4 * hi; }
; template <int DQK, int MODE, int LDQ, int LDK, int LDV> ...
;     ...
;     for (int r = 0; r < 16; ++r) { const int orow = wid * 32 + crow(r, hi); const float rl = __builtin_amdgcn_rcpf(li_l[crow(r, hi)]);
;         if constexpr (MODE == 0) {
; #pragma unroll
;             for (int d0 = 0; d0 < 4; ++d0) AOb[(size_t)orow * 1024 + d0 * 32 + r32] = f2bf(o[d0][r] * rl);
;         } else if constexpr (MODE == 1) {
; #pragma unroll
;             for (int d0 = 0; d0 < 4; ++d0) S0[(size_t)orow * 512 + d0 * 32 + r32] = o[d0][r] * rl;
;         } else {
;             float v[4]; float ss = 0.f;
; #pragma unroll
;             for (int d0 = 0; d0 < 4; ++d0) { v[d0] = s0v[r][d0] - lam * (o[d0][r] * rl); ss += v[d0] * v[d0]; }
; #pragma unroll
;             for (int mk = 1; mk <= 16; mk <<= 1) ss += shx(ss, mk, lane2);
;             const float rs = rsqrtf(ss * (1.f / 128.f) + EPS) * 0.8f;
; #pragma unroll
;             for (int d0 = 0; d0 < 4; ++d0) AOb[(size_t)orow * 1024 + d0 * 32 + r32] = f2bf(v[d0] * rs * gout[d0 * 32 + r32]);
;         } }
	v_pk_add_f32 v[8:9], v[20:21], v[24:25]
	ds_bpermute_b32 v21, v168, v9
	ds_bpermute_b32 v20, v168, v8
	v_mul_f32_e32 v24, v162, v35
	v_bfe_u32 v25, v24, 16, 1
	v_mul_f32_e32 v5, v5, v34
	v_add3_u32 v24, v24, v25, s68
	s_waitcnt lgkmcnt(0)
	v_pk_add_f32 v[8:9], v[8:9], v[20:21]
	ds_bpermute_b32 v21, v167, v9
	ds_bpermute_b32 v20, v167, v8
	v_mul_f32_e32 v5, v161, v5
	global_store_short_d16_hi v[26:27], v24, off offset:1088
	v_bfe_u32 v24, v5, 16, 1
	v_add3_u32 v5, v5, v24, s68
	s_waitcnt lgkmcnt(0)
	v_pk_add_f32 v[8:9], v[8:9], v[20:21]
	ds_bpermute_b32 v21, v166, v9
	ds_bpermute_b32 v20, v166, v8
	v_mul_f32_e32 v4, v4, v34
	global_store_short_d16_hi v[26:27], v5, off offset:1152
	v_mul_f32_e32 v24, v130, v4
	v_bfe_u32 v25, v24, 16, 1
	s_waitcnt lgkmcnt(0)
	v_pk_add_f32 v[4:5], v[8:9], v[20:21]
	s_nop 0
	v_pk_fma_f32 v[4:5], v[4:5], s[24:25], v[92:93] op_sel_hi:[1,0,0]
	s_nop 0
	v_mul_f32_e32 v8, 0x4b800000, v5
	v_cmp_gt_f32_e32 vcc, s67, v5
	s_nop 1
	v_cndmask_b32_e32 v5, v5, v8, vcc
	v_rsq_f32_e32 v5, v5
	v_add3_u32 v8, v24, v25, s68
	global_store_short_d16_hi v[26:27], v8, off offset:1216
	v_lshl_add_u64 v[8:9], v[32:33], 0, v[76:77]
	v_mul_f32_e32 v20, 0x45800000, v5
	v_cndmask_b32_e32 v5, v5, v20, vcc
	v_mul_f32_e32 v5, 0x3f4ccccd, v5
	v_mul_f32_e32 v18, v18, v5
	v_mul_f32_e32 v18, v163, v18
	v_bfe_u32 v20, v18, 16, 1
	v_add3_u32 v18, v18, v20, s68
	global_store_short_d16_hi v[8:9], v18, off offset:1024
	v_mul_f32_e32 v18, v19, v5
	v_mul_f32_e32 v18, v162, v18
	v_bfe_u32 v19, v18, 16, 1
	v_add3_u32 v18, v18, v19, s68
	global_store_short_d16_hi v[8:9], v18, off offset:1088
	v_mul_f32_e32 v18, v23, v5
	v_mul_f32_e32 v18, v161, v18
	v_bfe_u32 v19, v18, 16, 1
	v_add3_u32 v18, v18, v19, s68
	global_store_short_d16_hi v[8:9], v18, off offset:1152
	v_mul_f32_e32 v18, 0x4b800000, v4
	v_cmp_gt_f32_e32 vcc, s67, v4
	v_mul_f32_e32 v5, v22, v5
	v_mul_f32_e32 v5, v130, v5
	v_cndmask_b32_e32 v4, v4, v18, vcc
	v_rsq_f32_e32 v4, v4
	v_bfe_u32 v18, v5, 16, 1
	v_add3_u32 v5, v5, v18, s68
	global_store_short_d16_hi v[8:9], v5, off offset:1216
	v_mul_f32_e32 v5, 0x45800000, v4
	v_cndmask_b32_e32 v34, v4, v5, vcc
	v_mov_b32_e32 v4, v12
	v_mov_b32_e32 v5, v60
	v_mov_b32_e32 v18, v44
	v_mov_b32_e32 v19, v28
	v_pk_mul_f32 v[4:5], v[4:5], v[0:1] op_sel_hi:[1,0]
	v_pk_mul_f32 v[18:19], v[18:19], v[0:1] op_sel_hi:[1,0]
	v_rcp_f32_e32 v0, v1
	v_mov_b32_e32 v60, v13
	v_mov_b32_e32 v28, v45
	s_waitcnt vmcnt(58)
	v_pk_fma_f32 v[4:5], v[128:129], v[4:5], v[116:117] neg_lo:[1,0,0] neg_hi:[1,0,0]
	v_pk_mul_f32 v[12:13], v[60:61], v[0:1] op_sel_hi:[1,0]
	v_pk_mul_f32 v[0:1], v[28:29], v[0:1] op_sel_hi:[1,0]
	s_waitcnt vmcnt(54)
	v_pk_fma_f32 v[12:13], v[128:129], v[12:13], v[112:113] neg_lo:[1,0,0] neg_hi:[1,0,0]
	v_pk_mul_f32 v[8:9], v[4:5], v[4:5]
	v_pk_fma_f32 v[18:19], v[128:129], v[18:19], v[114:115] neg_lo:[1,0,0] neg_hi:[1,0,0]
	v_pk_mul_f32 v[22:23], v[12:13], v[12:13]
	s_waitcnt vmcnt(52)
	v_pk_fma_f32 v[0:1], v[128:129], v[0:1], v[110:111] neg_lo:[1,0,0] neg_hi:[1,0,0]
	v_pk_mul_f32 v[20:21], v[18:19], v[18:19]
	v_pk_mul_f32 v[24:25], v[0:1], v[0:1]
	v_mov_b32_e32 v26, v22
	v_mov_b32_e32 v27, v8
	v_mov_b32_e32 v8, v23
	v_pk_add_f32 v[8:9], v[26:27], v[8:9]
	v_mov_b32_e32 v22, v25
	v_mov_b32_e32 v23, v21
	v_pk_add_f32 v[8:9], v[22:23], v[8:9]
	v_mov_b32_e32 v25, v20
	v_pk_add_f32 v[8:9], v[24:25], v[8:9]
	ds_bpermute_b32 v21, v164, v9
	ds_bpermute_b32 v20, v164, v8
	v_mul_f32_e32 v24, 0x3f4ccccd, v34
	v_mul_f32_e32 v10, v10, v24
	v_mul_f32_e32 v10, v163, v10
	v_bfe_u32 v25, v10, 16, 1
	s_waitcnt lgkmcnt(0)
	v_pk_add_f32 v[8:9], v[8:9], v[20:21]
	ds_bpermute_b32 v21, v165, v9
	ds_bpermute_b32 v20, v165, v8
	v_lshl_add_u64 v[22:23], v[32:33], 0, v[72:73]
	v_add3_u32 v10, v10, v25, s68
	global_store_short_d16_hi v[22:23], v10, off offset:1024
	v_mul_f32_e32 v25, v11, v24
	s_waitcnt lgkmcnt(0)
	v_pk_add_f32 v[8:9], v[8:9], v[20:21]
	ds_bpermute_b32 v11, v168, v9
	ds_bpermute_b32 v10, v168, v8
	v_mul_f32_e32 v20, v162, v25
	v_bfe_u32 v21, v20, 16, 1
	v_mul_f32_e32 v7, v7, v24
	v_add3_u32 v20, v20, v21, s68
	s_waitcnt lgkmcnt(0)
	v_pk_add_f32 v[8:9], v[8:9], v[10:11]
	ds_bpermute_b32 v11, v167, v9
	ds_bpermute_b32 v10, v167, v8
	v_mul_f32_e32 v7, v161, v7
	global_store_short_d16_hi v[22:23], v20, off offset:1088
	v_bfe_u32 v20, v7, 16, 1
	v_add3_u32 v7, v7, v20, s68
	s_waitcnt lgkmcnt(0)
	v_pk_add_f32 v[8:9], v[8:9], v[10:11]
	ds_bpermute_b32 v11, v166, v9
	ds_bpermute_b32 v10, v166, v8
	v_mul_f32_e32 v6, v6, v24
	global_store_short_d16_hi v[22:23], v7, off offset:1152
	v_mul_f32_e32 v20, v130, v6
	v_bfe_u32 v21, v20, 16, 1
	s_waitcnt lgkmcnt(0)
; DI unsigned short f2bf(float x) { unsigned u = __float_as_uint(x); u += 0x7fffu + ((u >> 16) & 1u); return (unsigned short)(u >> 16); }
; DI float shx(float v, int mask, int lane) { return __int_as_float(__builtin_amdgcn_ds_bpermute((lane ^ mask) << 2, __float_as_int(v))); }
; DI int crow(int r, int hi) { return (r & 3) + 8 * (r >> 2) + 4 * hi; }
; template <int DQK, int MODE, int LDQ, int LDK, int LDV> ...
;     ...
;     for (int r = 0; r < 16; ++r) { const int orow = wid * 32 + crow(r, hi); const float rl = __builtin_amdgcn_rcpf(li_l[crow(r, hi)]);
;         if constexpr (MODE == 0) {
; #pragma unroll
;             for (int d0 = 0; d0 < 4; ++d0) AOb[(size_t)orow * 1024 + d0 * 32 + r32] = f2bf(o[d0][r] * rl);
;         } else if constexpr (MODE == 1) {
; #pragma unroll
;             for (int d0 = 0; d0 < 4; ++d0) S0[(size_t)orow * 512 + d0 * 32 + r32] = o[d0][r] * rl;
;         } else {
;             float v[4]; float ss = 0.f;
; #pragma unroll
;             for (int d0 = 0; d0 < 4; ++d0) { v[d0] = s0v[r][d0] - lam * (o[d0][r] * rl); ss += v[d0] * v[d0]; }
; #pragma unroll
;             for (int mk = 1; mk <= 16; mk <<= 1) ss += shx(ss, mk, lane2);
;             const float rs = rsqrtf(ss * (1.f / 128.f) + EPS) * 0.8f;
; #pragma unroll
;             for (int d0 = 0; d0 < 4; ++d0) AOb[(size_t)orow * 1024 + d0 * 32 + r32] = f2bf(v[d0] * rs * gout[d0 * 32 + r32]);
;         } }
; DI void phase4(const Params& p, LAS unsigned char* lds, int wv) {
;     ...
;             __syncthreads();
	v_pk_add_f32 v[6:7], v[8:9], v[10:11]
	s_nop 0
	v_pk_fma_f32 v[6:7], v[6:7], s[24:25], v[92:93] op_sel_hi:[1,0,0]
	s_nop 0
	v_mul_f32_e32 v8, 0x4b800000, v7
	v_cmp_gt_f32_e32 vcc, s67, v7
	s_nop 1
	v_cndmask_b32_e32 v7, v7, v8, vcc
	v_rsq_f32_e32 v7, v7
	v_add3_u32 v8, v20, v21, s68
	global_store_short_d16_hi v[22:23], v8, off offset:1216
	v_lshl_add_u64 v[8:9], v[32:33], 0, v[74:75]
	v_mul_f32_e32 v10, 0x45800000, v7
	v_cndmask_b32_e32 v7, v7, v10, vcc
	v_mul_f32_e32 v7, 0x3f4ccccd, v7
	v_mul_f32_e32 v4, v4, v7
	v_mul_f32_e32 v4, v163, v4
	v_bfe_u32 v10, v4, 16, 1
	v_add3_u32 v4, v4, v10, s68
	global_store_short_d16_hi v[8:9], v4, off offset:1024
	v_mul_f32_e32 v4, v5, v7
	v_mul_f32_e32 v4, v162, v4
	v_bfe_u32 v5, v4, 16, 1
	v_add3_u32 v4, v4, v5, s68
	global_store_short_d16_hi v[8:9], v4, off offset:1088
	v_mul_f32_e32 v4, v19, v7
	v_mul_f32_e32 v4, v161, v4
	v_bfe_u32 v5, v4, 16, 1
	v_add3_u32 v4, v4, v5, s68
	v_mul_f32_e32 v5, 0x4b800000, v6
	v_cmp_gt_f32_e32 vcc, s67, v6
	global_store_short_d16_hi v[8:9], v4, off offset:1152
	v_mul_f32_e32 v4, v18, v7
	v_cndmask_b32_e32 v5, v6, v5, vcc
	v_rsq_f32_e32 v5, v5
	v_mul_f32_e32 v4, v130, v4
	v_bfe_u32 v6, v4, 16, 1
	v_add3_u32 v4, v4, v6, s68
	global_store_short_d16_hi v[8:9], v4, off offset:1216
	v_mul_f32_e32 v4, 0x45800000, v5
	v_cndmask_b32_e32 v24, v5, v4, vcc
	v_mov_b32_e32 v4, v14
	v_mov_b32_e32 v5, v62
	v_mov_b32_e32 v8, v46
	v_mov_b32_e32 v9, v30
	v_pk_mul_f32 v[4:5], v[4:5], v[2:3] op_sel_hi:[1,0]
	v_pk_mul_f32 v[8:9], v[8:9], v[2:3] op_sel_hi:[1,0]
	v_rcp_f32_e32 v2, v3
	v_mov_b32_e32 v62, v15
	v_mov_b32_e32 v30, v47
	s_waitcnt vmcnt(58)
	v_pk_fma_f32 v[4:5], v[128:129], v[4:5], v[108:109] neg_lo:[1,0,0] neg_hi:[1,0,0]
	v_pk_mul_f32 v[14:15], v[62:63], v[2:3] op_sel_hi:[1,0]
	v_pk_mul_f32 v[2:3], v[30:31], v[2:3] op_sel_hi:[1,0]
	s_waitcnt vmcnt(54)
	v_pk_fma_f32 v[14:15], v[128:129], v[14:15], v[104:105] neg_lo:[1,0,0] neg_hi:[1,0,0]
	v_pk_mul_f32 v[6:7], v[4:5], v[4:5]
	v_pk_fma_f32 v[8:9], v[128:129], v[8:9], v[106:107] neg_lo:[1,0,0] neg_hi:[1,0,0]
	v_pk_mul_f32 v[18:19], v[14:15], v[14:15]
	s_waitcnt vmcnt(52)
	v_pk_fma_f32 v[2:3], v[128:129], v[2:3], v[102:103] neg_lo:[1,0,0] neg_hi:[1,0,0]
	v_pk_mul_f32 v[10:11], v[8:9], v[8:9]
	v_pk_mul_f32 v[20:21], v[2:3], v[2:3]
	v_mov_b32_e32 v22, v18
	v_mov_b32_e32 v23, v6
	v_mov_b32_e32 v6, v19
	v_pk_add_f32 v[6:7], v[22:23], v[6:7]
	v_mov_b32_e32 v18, v21
	v_mov_b32_e32 v19, v11
	v_pk_add_f32 v[6:7], v[18:19], v[6:7]
	v_mov_b32_e32 v21, v10
	v_pk_add_f32 v[6:7], v[20:21], v[6:7]
	ds_bpermute_b32 v11, v164, v7
	ds_bpermute_b32 v10, v164, v6
	v_mul_f32_e32 v20, 0x3f4ccccd, v24
	v_mul_f32_e32 v12, v12, v20
	v_mul_f32_e32 v12, v163, v12
	v_bfe_u32 v21, v12, 16, 1
	s_waitcnt lgkmcnt(0)
	v_pk_add_f32 v[6:7], v[6:7], v[10:11]
	ds_bpermute_b32 v11, v165, v7
	ds_bpermute_b32 v10, v165, v6
	v_lshl_add_u64 v[18:19], v[32:33], 0, v[64:65]
	v_add3_u32 v12, v12, v21, s68
	global_store_short_d16_hi v[18:19], v12, off offset:1024
	v_mul_f32_e32 v12, v13, v20
	s_waitcnt lgkmcnt(0)
	v_pk_add_f32 v[6:7], v[6:7], v[10:11]
	ds_bpermute_b32 v11, v168, v7
	ds_bpermute_b32 v10, v168, v6
	v_mul_f32_e32 v12, v162, v12
	v_bfe_u32 v13, v12, 16, 1
	v_mul_f32_e32 v1, v1, v20
	v_add3_u32 v12, v12, v13, s68
	s_waitcnt lgkmcnt(0)
	v_pk_add_f32 v[6:7], v[6:7], v[10:11]
	ds_bpermute_b32 v11, v167, v7
	ds_bpermute_b32 v10, v167, v6
	v_mul_f32_e32 v1, v161, v1
	global_store_short_d16_hi v[18:19], v12, off offset:1088
	v_bfe_u32 v12, v1, 16, 1
	v_add3_u32 v1, v1, v12, s68
	s_waitcnt lgkmcnt(0)
	v_pk_add_f32 v[6:7], v[6:7], v[10:11]
	ds_bpermute_b32 v11, v166, v7
	ds_bpermute_b32 v10, v166, v6
	v_mul_f32_e32 v0, v0, v20
	global_store_short_d16_hi v[18:19], v1, off offset:1152
	v_mul_f32_e32 v12, v130, v0
	v_bfe_u32 v13, v12, 16, 1
	s_waitcnt lgkmcnt(0)
	v_pk_add_f32 v[0:1], v[6:7], v[10:11]
	s_nop 0
	v_pk_fma_f32 v[0:1], v[0:1], s[24:25], v[92:93] op_sel_hi:[1,0,0]
	s_nop 0
	v_mul_f32_e32 v6, 0x4b800000, v1
	v_cmp_gt_f32_e32 vcc, s67, v1
	s_nop 1
	v_cndmask_b32_e32 v1, v1, v6, vcc
	v_rsq_f32_e32 v1, v1
	v_add3_u32 v6, v12, v13, s68
	global_store_short_d16_hi v[18:19], v6, off offset:1216
	v_lshl_add_u64 v[6:7], v[32:33], 0, v[48:49]
	v_mul_f32_e32 v10, 0x45800000, v1
	v_cndmask_b32_e32 v1, v1, v10, vcc
	v_mul_f32_e32 v1, 0x3f4ccccd, v1
	v_mul_f32_e32 v4, v4, v1
	v_mul_f32_e32 v4, v163, v4
	v_bfe_u32 v10, v4, 16, 1
	v_add3_u32 v4, v4, v10, s68
	global_store_short_d16_hi v[6:7], v4, off offset:1024
	v_mul_f32_e32 v4, v5, v1
	v_mul_f32_e32 v4, v162, v4
	v_bfe_u32 v5, v4, 16, 1
	v_add3_u32 v4, v4, v5, s68
	global_store_short_d16_hi v[6:7], v4, off offset:1088
	v_mul_f32_e32 v4, v9, v1
	v_mul_f32_e32 v4, v161, v4
	v_bfe_u32 v5, v4, 16, 1
	v_add3_u32 v4, v4, v5, s68
	global_store_short_d16_hi v[6:7], v4, off offset:1152
	v_mul_f32_e32 v4, 0x4b800000, v0
	v_cmp_gt_f32_e32 vcc, s67, v0
	v_mul_f32_e32 v1, v8, v1
	v_mul_f32_e32 v1, v130, v1
	v_cndmask_b32_e32 v0, v0, v4, vcc
	v_rsq_f32_e32 v0, v0
	v_bfe_u32 v4, v1, 16, 1
	v_add3_u32 v1, v1, v4, s68
	global_store_short_d16_hi v[6:7], v1, off offset:1216
	v_mul_f32_e32 v1, 0x45800000, v0
	v_cndmask_b32_e32 v0, v0, v1, vcc
	v_mul_f32_e32 v4, 0x3f4ccccd, v0
	v_mul_f32_e32 v5, v14, v4
	v_mul_f32_e32 v5, v163, v5
	v_bfe_u32 v6, v5, 16, 1
	v_lshl_add_u64 v[0:1], v[32:33], 0, v[16:17]
	v_add3_u32 v5, v5, v6, s68
	global_store_short_d16_hi v[0:1], v5, off offset:1024
	v_mul_f32_e32 v5, v15, v4
	v_mul_f32_e32 v5, v162, v5
	v_bfe_u32 v6, v5, 16, 1
	v_mul_f32_e32 v3, v3, v4
	v_add3_u32 v5, v5, v6, s68
	v_mul_f32_e32 v3, v161, v3
	global_store_short_d16_hi v[0:1], v5, off offset:1088
	v_bfe_u32 v5, v3, 16, 1
	v_mul_f32_e32 v2, v2, v4
	v_add3_u32 v3, v3, v5, s68
	v_mul_f32_e32 v2, v130, v2
	global_store_short_d16_hi v[0:1], v3, off offset:1152
	v_bfe_u32 v3, v2, 16, 1
	v_add3_u32 v2, v2, v3, s68
	global_store_short_d16_hi v[0:1], v2, off offset:1216
	s_waitcnt vmcnt(63) expcnt(7) lgkmcnt(15)
	s_barrier

; #define LAS __attribute__((address_space(3)))
; DI void expsum(f32x16& p, float& l_reg, bf16x8& pa0, bf16x8& pa1) {
; #pragma unroll
;     for (int r = 0; r < 16; ++r) p[r] = __builtin_amdgcn_exp2f(p[r]);
;     float ps = 0.f;
; #pragma unroll
;     for (int r = 0; r < 16; ++r) ps += p[r];
;     l_reg += ps; asm volatile("" : "+v"(l_reg));
;     ...
;     ATT_PK4(p, 0, pa0); ATT_PK4(p, 8, pa1);
;     ...
; }
; DI int v_rd_base(int lane) { return ((lane & 3) << 3) | (((lane >> 2) & 3) << 6) | (((lane >> 4) & 1) << 5) | (((lane >> 5) & 1) << 8); }
; template <int OFF> DI s16x4 tr_read(int vb) { s16x4 r; asm volatile("ds_read_b64_tr_b16 %0, %1 offset:%2" : "=&v"(r) : "v"(vb), "i"(OFF) : "memory"); return r; }
; template <int H> DI void v_reads(s16x4* vf, int vb) {
;     vf[0] = tr_read<v_rd_off(0, 2 * H, 0)>(vb); vf[1] = tr_read<v_rd_off(0, 2 * H, 1)>(vb); vf[2] = tr_read<v_rd_off(0, 2 * H + 1, 0)>(vb); vf[3] = tr_read<v_rd_off(0, 2 * H + 1, 1)>(vb);
;     vf[4] = tr_read<v_rd_off(1, 2 * H, 0)>(vb); vf[5] = tr_read<v_rd_off(1, 2 * H, 1)>(vb); vf[6] = tr_read<v_rd_off(1, 2 * H + 1, 0)>(vb); vf[7] = tr_read<v_rd_off(1, 2 * H + 1, 1)>(vb);
;     vf[8] = tr_read<v_rd_off(2, 2 * H, 0)>(vb); vf[9] = tr_read<v_rd_off(2, 2 * H, 1)>(vb); vf[10] = tr_read<v_rd_off(2, 2 * H + 1, 0)>(vb); vf[11] = tr_read<v_rd_off(2, 2 * H + 1, 1)>(vb);
;     vf[12] = tr_read<v_rd_off(3, 2 * H, 0)>(vb); vf[13] = tr_read<v_rd_off(3, 2 * H, 1)>(vb); vf[14] = tr_read<v_rd_off(3, 2 * H + 1, 0)>(vb); vf[15] = tr_read<v_rd_off(3, 2 * H + 1, 1)>(vb);
; }
; DI void pv_mma(f32x16* o, const s16x4* vf, bf16x8 pa0, bf16x8 pa1) {
;     ...
; #pragma unroll
;     for (int d0 = 0; d0 < 4; ++d0) {
;         o[d0] = __builtin_amdgcn_mfma_f32_32x32x16_bf16(pa0, ATT_PK(vf[4 * d0], vf[4 * d0 + 1]), o[d0], 0, 0, 0);
;         o[d0] = __builtin_amdgcn_mfma_f32_32x32x16_bf16(pa1, ATT_PK(vf[4 * d0 + 2], vf[4 * d0 + 3]), o[d0], 0, 0, 0); }
;     ...
; }
; template <int DQK, int D0A, int D0B> DI void k_reads(bf16x8* kf, const LAS unsigned char* Ks, int half, int r32, int hi) {
; #pragma unroll
;     for (int d0 = D0A; d0 < D0B; ++d0) kf[d0 - D0A] = *(const LAS bf16x8*)(Ks + half * (32 * DQK * 2) + kswz<DQK>(r32, (d0 * 16 + hi * 8) * 2));
; }
; template <int D0A, int D0B> DI void qk_mma(f32x16& p, const bf16x8* kf, const bf16x8* qr) {
; #pragma unroll
;     for (int d0 = D0A; d0 < D0B; ++d0) {
.Lstg_mla_top_2:
	s_setprio 0
	s_mov_b32 m0, s1
	s_mov_b32 s0, s5
	s_mov_b32 s5, s44
	s_mov_b32 s44, s4
	s_lshl_b32 s4, s4, 14
	global_load_lds_dwordx4 v136, s[34:35]
	s_add_i32 m0, s1, 0x2000
	s_add_i32 s4, s52, s4
	global_load_lds_dwordx4 v138, s[34:35]
	s_add_i32 m0, s1, 0x4000
	s_add_i32 s6, s4, 0x400
	global_load_lds_dwordx4 v140, s[34:35]
	s_mov_b32 m0, s4
	s_add_i32 s1, s43, -3
	global_load_lds_dwordx4 v144, s[34:35]
	s_mov_b32 m0, s6
	s_nop 0
	global_load_lds_dwordx4 v142, s[34:35]
	s_and_b32 s1, s1, 3
	s_mulk_i32 s1, 0x6000
	v_add_u32_e32 v246, s1, v158
	v_add_u32_e32 v174, v246, v151
	v_add_u32_e32 v178, v246, v149
	v_add_u32_e32 v182, v246, v148
	v_add_u32_e32 v186, v246, v147
	s_lshl_b32 s1, s0, 14
	ds_read_b128 v[190:193], v174 offset:12416
	ds_read_b128 v[194:197], v178 offset:12416
	ds_read_b128 v[174:177], v174 offset:12288
	ds_read_b128 v[178:181], v178 offset:12288
	ds_read_b128 v[182:185], v182 offset:12288
	ds_read_b128 v[186:189], v186 offset:12288
	v_add_u32_e32 v254, s1, v130
	ds_read_b64_tr_b16 v[198:199], v254 offset:0
	ds_read_b64_tr_b16 v[200:201], v254 offset:0x800
	ds_read_b64_tr_b16 v[202:203], v254 offset:0x1000
	ds_read_b64_tr_b16 v[204:205], v254 offset:0x1800
	ds_read_b64_tr_b16 v[206:207], v254 offset:0x200
	ds_read_b64_tr_b16 v[208:209], v254 offset:0xa00
	ds_read_b64_tr_b16 v[210:211], v254 offset:0x1200
	ds_read_b64_tr_b16 v[212:213], v254 offset:0x1a00
	ds_read_b64_tr_b16 v[214:215], v254 offset:0x400
	ds_read_b64_tr_b16 v[216:217], v254 offset:0xc00
	ds_read_b64_tr_b16 v[218:219], v254 offset:0x1400
	ds_read_b64_tr_b16 v[220:221], v254 offset:0x1c00
	ds_read_b64_tr_b16 v[222:223], v254 offset:0x600
	ds_read_b64_tr_b16 v[224:225], v254 offset:0xe00
	ds_read_b64_tr_b16 v[226:227], v254 offset:0x1600
	ds_read_b64_tr_b16 v[228:229], v254 offset:0x1e00
	s_setprio 2
	v_exp_f32_e32 v64, v64
	v_exp_f32_e32 v65, v65
	v_exp_f32_e32 v66, v66
	v_exp_f32_e32 v67, v67
	v_exp_f32_e32 v68, v68
	v_exp_f32_e32 v69, v69
	v_add_f32_e32 v230, v65, v64
	v_exp_f32_e32 v70, v70
	v_add_f32_e32 v230, v66, v230
	v_exp_f32_e32 v71, v71
	v_add_f32_e32 v230, v67, v230
	v_exp_f32_e32 v72, v72
	v_add_f32_e32 v230, v68, v230
	v_exp_f32_e32 v73, v73
	v_add_f32_e32 v230, v69, v230
	v_exp_f32_e32 v74, v74
	v_add_f32_e32 v230, v70, v230
	v_exp_f32_e32 v75, v75
	v_add_f32_e32 v230, v71, v230
	v_exp_f32_e32 v76, v76
	v_add_f32_e32 v230, v72, v230
	v_exp_f32_e32 v77, v77
	v_add_f32_e32 v230, v73, v230
	v_exp_f32_e32 v78, v78
	v_add_f32_e32 v230, v74, v230
	v_exp_f32_e32 v79, v79
	v_add_f32_e32 v230, v75, v230
	v_add_f32_e32 v230, v76, v230
	v_add_f32_e32 v230, v77, v230
	v_add_f32_e32 v230, v78, v230
	v_add_f32_e32 v230, v79, v230
	v_add_f32_e32 v173, v173, v230
	v_cvt_pk_bf16_f32 v64, v64, v65
	v_cvt_pk_bf16_f32 v65, v66, v67
	v_cvt_pk_bf16_f32 v66, v68, v69
	v_cvt_pk_bf16_f32 v67, v70, v71
	v_cvt_pk_bf16_f32 v68, v72, v73
	v_cvt_pk_bf16_f32 v69, v74, v75
	v_cvt_pk_bf16_f32 v70, v76, v77
	v_cvt_pk_bf16_f32 v71, v78, v79
	s_nop 0
	v_permlane32_swap_b32_e32 v64, v66
	v_permlane32_swap_b32_e32 v65, v67
	v_permlane32_swap_b32_e32 v68, v70
	v_permlane32_swap_b32_e32 v69, v71
	s_waitcnt lgkmcnt(0)
	v_add_u32_e32 v72, v246, v151
	v_add_u32_e32 v73, v246, v149
	v_add_u32_e32 v74, v246, v148
	v_add_u32_e32 v75, v246, v147
	ds_read_b128 v[230:233], v74 offset:12416
	ds_read_b128 v[234:237], v75 offset:12416
	ds_read_b128 v[238:241], v72 offset:12544
	ds_read_b128 v[242:245], v73 offset:12544
	ds_read_b128 v[246:249], v74 offset:12544
	ds_read_b128 v[250:253], v75 offset:12544
	s_setprio 1
	v_mfma_f32_32x32x16_bf16 v[48:63], v[64:67], v[198:201], v[48:63]
	v_mfma_f32_32x32x16_bf16 v[32:47], v[64:67], v[206:209], v[32:47]
	v_mfma_f32_32x32x16_bf16 v[16:31], v[64:67], v[214:217], v[16:31]
	v_mfma_f32_32x32x16_bf16 v[0:15], v[64:67], v[222:225], v[0:15]
	v_mfma_f32_32x32x16_bf16 v[48:63], v[68:71], v[202:205], v[48:63]
	v_mfma_f32_32x32x16_bf16 v[32:47], v[68:71], v[210:213], v[32:47]
	v_mfma_f32_32x32x16_bf16 v[16:31], v[68:71], v[218:221], v[16:31]
	v_mfma_f32_32x32x16_bf16 v[0:15], v[68:71], v[226:229], v[0:15]
	s_waitcnt lgkmcnt(0)
; #define LAS __attribute__((address_space(3)))
; DI void expsum(f32x16& p, float& l_reg, bf16x8& pa0, bf16x8& pa1) {
; #pragma unroll
;     for (int r = 0; r < 16; ++r) p[r] = __builtin_amdgcn_exp2f(p[r]);
;     float ps = 0.f;
; #pragma unroll
;     for (int r = 0; r < 16; ++r) ps += p[r];
;     l_reg += ps; asm volatile("" : "+v"(l_reg));
;     ...
;     ATT_PK4(p, 0, pa0); ATT_PK4(p, 8, pa1);
;     ...
; }
; DI int v_rd_base(int lane) { return ((lane & 3) << 3) | (((lane >> 2) & 3) << 6) | (((lane >> 4) & 1) << 5) | (((lane >> 5) & 1) << 8); }
; template <int OFF> DI s16x4 tr_read(int vb) { s16x4 r; asm volatile("ds_read_b64_tr_b16 %0, %1 offset:%2" : "=&v"(r) : "v"(vb), "i"(OFF) : "memory"); return r; }
; template <int H> DI void v_reads(s16x4* vf, int vb) {
;     vf[0] = tr_read<v_rd_off(0, 2 * H, 0)>(vb); vf[1] = tr_read<v_rd_off(0, 2 * H, 1)>(vb); vf[2] = tr_read<v_rd_off(0, 2 * H + 1, 0)>(vb); vf[3] = tr_read<v_rd_off(0, 2 * H + 1, 1)>(vb);
;     vf[4] = tr_read<v_rd_off(1, 2 * H, 0)>(vb); vf[5] = tr_read<v_rd_off(1, 2 * H, 1)>(vb); vf[6] = tr_read<v_rd_off(1, 2 * H + 1, 0)>(vb); vf[7] = tr_read<v_rd_off(1, 2 * H + 1, 1)>(vb);
;     vf[8] = tr_read<v_rd_off(2, 2 * H, 0)>(vb); vf[9] = tr_read<v_rd_off(2, 2 * H, 1)>(vb); vf[10] = tr_read<v_rd_off(2, 2 * H + 1, 0)>(vb); vf[11] = tr_read<v_rd_off(2, 2 * H + 1, 1)>(vb);
;     vf[12] = tr_read<v_rd_off(3, 2 * H, 0)>(vb); vf[13] = tr_read<v_rd_off(3, 2 * H, 1)>(vb); vf[14] = tr_read<v_rd_off(3, 2 * H + 1, 0)>(vb); vf[15] = tr_read<v_rd_off(3, 2 * H + 1, 1)>(vb);
; }
; DI void pv_mma(f32x16* o, const s16x4* vf, bf16x8 pa0, bf16x8 pa1) {
;     ...
; #pragma unroll
;     for (int d0 = 0; d0 < 4; ++d0) {
;         o[d0] = __builtin_amdgcn_mfma_f32_32x32x16_bf16(pa0, ATT_PK(vf[4 * d0], vf[4 * d0 + 1]), o[d0], 0, 0, 0);
;         o[d0] = __builtin_amdgcn_mfma_f32_32x32x16_bf16(pa1, ATT_PK(vf[4 * d0 + 2], vf[4 * d0 + 3]), o[d0], 0, 0, 0); }
;     ...
; }
; template <int DQK, int D0A, int D0B> DI void k_reads(bf16x8* kf, const LAS unsigned char* Ks, int half, int r32, int hi) {
; #pragma unroll
;     for (int d0 = D0A; d0 < D0B; ++d0) kf[d0 - D0A] = *(const LAS bf16x8*)(Ks + half * (32 * DQK * 2) + kswz<DQK>(r32, (d0 * 16 + hi * 8) * 2));
; }
; template <int D0A, int D0B> DI void qk_mma(f32x16& p, const bf16x8* kf, const bf16x8* qr) {
; #pragma unroll
;     for (int d0 = D0A; d0 < D0B; ++d0) {
	v_mfma_f32_32x32x16_bf16 v[64:79], v[174:177], v[80:83], 0
	v_mfma_f32_32x32x16_bf16 v[64:79], v[178:181], v[84:87], v[64:79]
	v_mfma_f32_32x32x16_bf16 v[64:79], v[182:185], v[88:91], v[64:79]
	v_mfma_f32_32x32x16_bf16 v[64:79], v[186:189], v[92:95], v[64:79]
	v_mfma_f32_32x32x16_bf16 v[64:79], v[190:193], v[96:99], v[64:79]
	v_mfma_f32_32x32x16_bf16 v[64:79], v[194:197], v[100:103], v[64:79]
	v_mfma_f32_32x32x16_bf16 v[64:79], v[230:233], v[104:107], v[64:79]
	v_mfma_f32_32x32x16_bf16 v[64:79], v[234:237], v[108:111], v[64:79]
	v_mfma_f32_32x32x16_bf16 v[64:79], v[238:241], v[112:115], v[64:79]
	v_mfma_f32_32x32x16_bf16 v[64:79], v[242:245], v[116:119], v[64:79]
	v_mfma_f32_32x32x16_bf16 v[64:79], v[246:249], v[120:123], v[64:79]
	v_mfma_f32_32x32x16_bf16 v[64:79], v[250:253], v[124:127], v[64:79]
	s_setprio 0
	s_add_i32 s4, s43, -2
	s_and_b32 s4, s4, 3
	s_mulk_i32 s4, 0x6000
	v_add_u32_e32 v246, s4, v158
	v_add_u32_e32 v174, v246, v151
	v_add_u32_e32 v178, v246, v149
	v_add_u32_e32 v182, v246, v148
	v_add_u32_e32 v186, v246, v147
	ds_read_b128 v[190:193], v174 offset:128
	ds_read_b128 v[194:197], v178 offset:128
	ds_read_b128 v[174:177], v174
	ds_read_b128 v[178:181], v178
	ds_read_b128 v[182:185], v182
	ds_read_b128 v[186:189], v186
	ds_read_b64_tr_b16 v[198:199], v254 offset:0x2000
	ds_read_b64_tr_b16 v[200:201], v254 offset:0x2800
	ds_read_b64_tr_b16 v[202:203], v254 offset:0x3000
	ds_read_b64_tr_b16 v[204:205], v254 offset:0x3800
	ds_read_b64_tr_b16 v[206:207], v254 offset:0x2200
	ds_read_b64_tr_b16 v[208:209], v254 offset:0x2a00
	ds_read_b64_tr_b16 v[210:211], v254 offset:0x3200
	ds_read_b64_tr_b16 v[212:213], v254 offset:0x3a00
	ds_read_b64_tr_b16 v[214:215], v254 offset:0x2400
	ds_read_b64_tr_b16 v[216:217], v254 offset:0x2c00
	ds_read_b64_tr_b16 v[218:219], v254 offset:0x3400
	ds_read_b64_tr_b16 v[220:221], v254 offset:0x3c00
	ds_read_b64_tr_b16 v[222:223], v254 offset:0x2600
	ds_read_b64_tr_b16 v[224:225], v254 offset:0x2e00
	ds_read_b64_tr_b16 v[226:227], v254 offset:0x3600
	ds_read_b64_tr_b16 v[228:229], v254 offset:0x3e00
	s_setprio 2
	v_exp_f32_e32 v64, v64
	v_exp_f32_e32 v65, v65
	v_exp_f32_e32 v66, v66
	v_exp_f32_e32 v67, v67
	v_exp_f32_e32 v68, v68
	v_exp_f32_e32 v69, v69
	v_add_f32_e32 v230, v65, v64
	v_exp_f32_e32 v70, v70
	v_add_f32_e32 v230, v66, v230
	v_exp_f32_e32 v71, v71
	v_add_f32_e32 v230, v67, v230
	v_exp_f32_e32 v72, v72
	v_add_f32_e32 v230, v68, v230
	v_exp_f32_e32 v73, v73
	v_add_f32_e32 v230, v69, v230
	v_exp_f32_e32 v74, v74
	v_add_f32_e32 v230, v70, v230
	v_exp_f32_e32 v75, v75
	v_add_f32_e32 v230, v71, v230
	v_exp_f32_e32 v76, v76
	v_add_f32_e32 v230, v72, v230
	v_exp_f32_e32 v77, v77
	v_add_f32_e32 v230, v73, v230
	v_exp_f32_e32 v78, v78
	v_add_f32_e32 v230, v74, v230
	v_exp_f32_e32 v79, v79
	v_add_f32_e32 v230, v75, v230
	v_add_f32_e32 v230, v76, v230
	v_add_f32_e32 v230, v77, v230
	v_add_f32_e32 v230, v78, v230
	v_add_f32_e32 v230, v79, v230
	v_add_f32_e32 v173, v173, v230
	v_cvt_pk_bf16_f32 v64, v64, v65
	v_cvt_pk_bf16_f32 v65, v66, v67
	v_cvt_pk_bf16_f32 v66, v68, v69
	v_cvt_pk_bf16_f32 v67, v70, v71
	v_cvt_pk_bf16_f32 v68, v72, v73
	v_cvt_pk_bf16_f32 v69, v74, v75
	v_cvt_pk_bf16_f32 v70, v76, v77
	v_cvt_pk_bf16_f32 v71, v78, v79
	s_nop 0
	v_permlane32_swap_b32_e32 v64, v66
	v_permlane32_swap_b32_e32 v65, v67
	v_permlane32_swap_b32_e32 v68, v70
	v_permlane32_swap_b32_e32 v69, v71
	s_waitcnt lgkmcnt(0)
	v_add_u32_e32 v72, v246, v151
	v_add_u32_e32 v73, v246, v149
	v_add_u32_e32 v74, v246, v148
	v_add_u32_e32 v75, v246, v147
	ds_read_b128 v[230:233], v74 offset:128
	ds_read_b128 v[234:237], v75 offset:128
	ds_read_b128 v[238:241], v72 offset:256
	ds_read_b128 v[242:245], v73 offset:256
	ds_read_b128 v[246:249], v74 offset:256
	ds_read_b128 v[250:253], v75 offset:256
	s_setprio 1
	s_cmp_lt_u32 s33, 0x100
	s_cbranch_scc1 .Lstg_mla_mid_3
	s_waitcnt vmcnt(5)
	s_barrier

; #define LAS __attribute__((address_space(3)))
; DI void expsum(f32x16& p, float& l_reg, bf16x8& pa0, bf16x8& pa1) {
; #pragma unroll
;     for (int r = 0; r < 16; ++r) p[r] = __builtin_amdgcn_exp2f(p[r]);
;     float ps = 0.f;
; #pragma unroll
;     for (int r = 0; r < 16; ++r) ps += p[r];
;     l_reg += ps; asm volatile("" : "+v"(l_reg));
;     ...
;     ATT_PK4(p, 0, pa0); ATT_PK4(p, 8, pa1);
;     ...
; }
; DI int v_rd_base(int lane) { return ((lane & 3) << 3) | (((lane >> 2) & 3) << 6) | (((lane >> 4) & 1) << 5) | (((lane >> 5) & 1) << 8); }
; template <int OFF> DI s16x4 tr_read(int vb) { s16x4 r; asm volatile("ds_read_b64_tr_b16 %0, %1 offset:%2" : "=&v"(r) : "v"(vb), "i"(OFF) : "memory"); return r; }
; template <int H> DI void v_reads(s16x4* vf, int vb) {
;     vf[0] = tr_read<v_rd_off(0, 2 * H, 0)>(vb); vf[1] = tr_read<v_rd_off(0, 2 * H, 1)>(vb); vf[2] = tr_read<v_rd_off(0, 2 * H + 1, 0)>(vb); vf[3] = tr_read<v_rd_off(0, 2 * H + 1, 1)>(vb);
;     vf[4] = tr_read<v_rd_off(1, 2 * H, 0)>(vb); vf[5] = tr_read<v_rd_off(1, 2 * H, 1)>(vb); vf[6] = tr_read<v_rd_off(1, 2 * H + 1, 0)>(vb); vf[7] = tr_read<v_rd_off(1, 2 * H + 1, 1)>(vb);
;     vf[8] = tr_read<v_rd_off(2, 2 * H, 0)>(vb); vf[9] = tr_read<v_rd_off(2, 2 * H, 1)>(vb); vf[10] = tr_read<v_rd_off(2, 2 * H + 1, 0)>(vb); vf[11] = tr_read<v_rd_off(2, 2 * H + 1, 1)>(vb);
;     vf[12] = tr_read<v_rd_off(3, 2 * H, 0)>(vb); vf[13] = tr_read<v_rd_off(3, 2 * H, 1)>(vb); vf[14] = tr_read<v_rd_off(3, 2 * H + 1, 0)>(vb); vf[15] = tr_read<v_rd_off(3, 2 * H + 1, 1)>(vb);
; }
; DI void pv_mma(f32x16* o, const s16x4* vf, bf16x8 pa0, bf16x8 pa1) {
;     ...
; #pragma unroll
;     for (int d0 = 0; d0 < 4; ++d0) {
;         o[d0] = __builtin_amdgcn_mfma_f32_32x32x16_bf16(pa0, ATT_PK(vf[4 * d0], vf[4 * d0 + 1]), o[d0], 0, 0, 0);
;         o[d0] = __builtin_amdgcn_mfma_f32_32x32x16_bf16(pa1, ATT_PK(vf[4 * d0 + 2], vf[4 * d0 + 3]), o[d0], 0, 0, 0); }
;     ...
; }
; template <int DQK, int D0A, int D0B> DI void k_reads(bf16x8* kf, const LAS unsigned char* Ks, int half, int r32, int hi) {
; #pragma unroll
;     for (int d0 = D0A; d0 < D0B; ++d0) kf[d0 - D0A] = *(const LAS bf16x8*)(Ks + half * (32 * DQK * 2) + kswz<DQK>(r32, (d0 * 16 + hi * 8) * 2));
; }
; template <int D0A, int D0B> DI void qk_mma(f32x16& p, const bf16x8* kf, const bf16x8* qr) {
; #pragma unroll
;     for (int d0 = D0A; d0 < D0B; ++d0) {
.Lstg_mla_t61_4:
	s_setprio 0
	v_lshl_add_u64 v[132:133], v[132:133], 1, s[0:1]
	s_mov_b32 m0, s6
	v_lshl_add_u64 v[134:135], v[134:135], 1, s[0:1]
	global_load_lds_dwordx4 v[132:133], off
	s_mov_b32 m0, s7
	s_nop 0
	global_load_lds_dwordx4 v[134:135], off
	ds_read_b128 v[132:135], v161 offset:36864
	ds_read_b128 v[136:139], v162 offset:36864
	ds_read_b128 v[140:143], v163 offset:36864
	ds_read_b128 v[174:177], v164 offset:36864
	ds_read_b128 v[178:181], v165 offset:36864
	ds_read_b128 v[182:185], v166 offset:36864
	v_lshl_add_u32 v144, s5, 14, v130
	ds_read_b64_tr_b16 v[186:187], v144 offset:0
	ds_read_b64_tr_b16 v[188:189], v144 offset:0x800
	ds_read_b64_tr_b16 v[190:191], v144 offset:0x1000
	ds_read_b64_tr_b16 v[192:193], v144 offset:0x1800
	ds_read_b64_tr_b16 v[194:195], v144 offset:0x200
	ds_read_b64_tr_b16 v[196:197], v144 offset:0xa00
	ds_read_b64_tr_b16 v[198:199], v144 offset:0x1200
	ds_read_b64_tr_b16 v[200:201], v144 offset:0x1a00
	ds_read_b64_tr_b16 v[202:203], v144 offset:0x400
	ds_read_b64_tr_b16 v[204:205], v144 offset:0xc00
	ds_read_b64_tr_b16 v[206:207], v144 offset:0x1400
	ds_read_b64_tr_b16 v[208:209], v144 offset:0x1c00
	ds_read_b64_tr_b16 v[210:211], v144 offset:0x600
	ds_read_b64_tr_b16 v[212:213], v144 offset:0xe00
	ds_read_b64_tr_b16 v[214:215], v144 offset:0x1600
	ds_read_b64_tr_b16 v[216:217], v144 offset:0x1e00
	s_setprio 2
	v_exp_f32_e32 v64, v64
	v_exp_f32_e32 v65, v65
	v_exp_f32_e32 v66, v66
	v_exp_f32_e32 v67, v67
	v_exp_f32_e32 v68, v68
	v_exp_f32_e32 v69, v69
	v_add_f32_e32 v145, v65, v64
	v_exp_f32_e32 v70, v70
	v_add_f32_e32 v145, v66, v145
	v_exp_f32_e32 v71, v71
	v_add_f32_e32 v145, v67, v145
	v_exp_f32_e32 v72, v72
	v_add_f32_e32 v145, v68, v145
	v_exp_f32_e32 v73, v73
	v_add_f32_e32 v145, v69, v145
	v_exp_f32_e32 v74, v74
	v_add_f32_e32 v145, v70, v145
	v_exp_f32_e32 v75, v75
	v_add_f32_e32 v145, v71, v145
	v_exp_f32_e32 v76, v76
	v_add_f32_e32 v145, v72, v145
	v_exp_f32_e32 v77, v77
	v_add_f32_e32 v145, v73, v145
	v_exp_f32_e32 v78, v78
	v_add_f32_e32 v145, v74, v145
	v_exp_f32_e32 v79, v79
	v_add_f32_e32 v145, v75, v145
	v_add_f32_e32 v145, v76, v145
	v_add_f32_e32 v145, v77, v145
	v_add_f32_e32 v145, v78, v145
	v_add_f32_e32 v145, v79, v145
	v_add_f32_e32 v145, v173, v145
	v_cvt_pk_bf16_f32 v64, v64, v65
	v_cvt_pk_bf16_f32 v65, v66, v67
	v_cvt_pk_bf16_f32 v66, v68, v69
	v_cvt_pk_bf16_f32 v67, v70, v71
	v_cvt_pk_bf16_f32 v68, v72, v73
	v_cvt_pk_bf16_f32 v69, v74, v75
	v_cvt_pk_bf16_f32 v70, v76, v77
	v_cvt_pk_bf16_f32 v71, v78, v79
	s_nop 0
	v_permlane32_swap_b32_e32 v64, v66
	v_permlane32_swap_b32_e32 v65, v67
	v_permlane32_swap_b32_e32 v68, v70
	v_permlane32_swap_b32_e32 v69, v71
	s_waitcnt lgkmcnt(0)
	ds_read_b128 v[218:221], v167 offset:36864
	ds_read_b128 v[222:225], v168 offset:36864
	ds_read_b128 v[226:229], v169 offset:36864
	ds_read_b128 v[230:233], v170 offset:36864
	ds_read_b128 v[234:237], v171 offset:36864
	ds_read_b128 v[238:241], v172 offset:36864
	s_setprio 1
	v_mfma_f32_32x32x16_bf16 v[48:63], v[64:67], v[186:189], v[48:63]
	v_mfma_f32_32x32x16_bf16 v[32:47], v[64:67], v[194:197], v[32:47]
	v_mfma_f32_32x32x16_bf16 v[16:31], v[64:67], v[202:205], v[16:31]
	v_mfma_f32_32x32x16_bf16 v[0:15], v[64:67], v[210:213], v[0:15]
	v_mfma_f32_32x32x16_bf16 v[48:63], v[68:71], v[190:193], v[48:63]
	v_mfma_f32_32x32x16_bf16 v[32:47], v[68:71], v[198:201], v[32:47]
	v_mfma_f32_32x32x16_bf16 v[16:31], v[68:71], v[206:209], v[16:31]
	v_mfma_f32_32x32x16_bf16 v[0:15], v[68:71], v[214:217], v[0:15]
	s_waitcnt lgkmcnt(0)
; #define LAS __attribute__((address_space(3)))
; DI void expsum(f32x16& p, float& l_reg, bf16x8& pa0, bf16x8& pa1) {
; #pragma unroll
;     for (int r = 0; r < 16; ++r) p[r] = __builtin_amdgcn_exp2f(p[r]);
;     float ps = 0.f;
; #pragma unroll
;     for (int r = 0; r < 16; ++r) ps += p[r];
;     l_reg += ps; asm volatile("" : "+v"(l_reg));
;     ...
;     ATT_PK4(p, 0, pa0); ATT_PK4(p, 8, pa1);
;     ...
; }
; DI int v_rd_base(int lane) { return ((lane & 3) << 3) | (((lane >> 2) & 3) << 6) | (((lane >> 4) & 1) << 5) | (((lane >> 5) & 1) << 8); }
; template <int OFF> DI s16x4 tr_read(int vb) { s16x4 r; asm volatile("ds_read_b64_tr_b16 %0, %1 offset:%2" : "=&v"(r) : "v"(vb), "i"(OFF) : "memory"); return r; }
; template <int H> DI void v_reads(s16x4* vf, int vb) {
;     vf[0] = tr_read<v_rd_off(0, 2 * H, 0)>(vb); vf[1] = tr_read<v_rd_off(0, 2 * H, 1)>(vb); vf[2] = tr_read<v_rd_off(0, 2 * H + 1, 0)>(vb); vf[3] = tr_read<v_rd_off(0, 2 * H + 1, 1)>(vb);
;     vf[4] = tr_read<v_rd_off(1, 2 * H, 0)>(vb); vf[5] = tr_read<v_rd_off(1, 2 * H, 1)>(vb); vf[6] = tr_read<v_rd_off(1, 2 * H + 1, 0)>(vb); vf[7] = tr_read<v_rd_off(1, 2 * H + 1, 1)>(vb);
;     vf[8] = tr_read<v_rd_off(2, 2 * H, 0)>(vb); vf[9] = tr_read<v_rd_off(2, 2 * H, 1)>(vb); vf[10] = tr_read<v_rd_off(2, 2 * H + 1, 0)>(vb); vf[11] = tr_read<v_rd_off(2, 2 * H + 1, 1)>(vb);
;     vf[12] = tr_read<v_rd_off(3, 2 * H, 0)>(vb); vf[13] = tr_read<v_rd_off(3, 2 * H, 1)>(vb); vf[14] = tr_read<v_rd_off(3, 2 * H + 1, 0)>(vb); vf[15] = tr_read<v_rd_off(3, 2 * H + 1, 1)>(vb);
; }
; DI void pv_mma(f32x16* o, const s16x4* vf, bf16x8 pa0, bf16x8 pa1) {
;     ...
; #pragma unroll
;     for (int d0 = 0; d0 < 4; ++d0) {
;         o[d0] = __builtin_amdgcn_mfma_f32_32x32x16_bf16(pa0, ATT_PK(vf[4 * d0], vf[4 * d0 + 1]), o[d0], 0, 0, 0);
;         o[d0] = __builtin_amdgcn_mfma_f32_32x32x16_bf16(pa1, ATT_PK(vf[4 * d0 + 2], vf[4 * d0 + 3]), o[d0], 0, 0, 0); }
;     ...
; }
; template <int DQK, int D0A, int D0B> DI void k_reads(bf16x8* kf, const LAS unsigned char* Ks, int half, int r32, int hi) {
; #pragma unroll
;     for (int d0 = D0A; d0 < D0B; ++d0) kf[d0 - D0A] = *(const LAS bf16x8*)(Ks + half * (32 * DQK * 2) + kswz<DQK>(r32, (d0 * 16 + hi * 8) * 2));
; }
; template <int D0A, int D0B> DI void qk_mma(f32x16& p, const bf16x8* kf, const bf16x8* qr) {
; #pragma unroll
;     for (int d0 = D0A; d0 < D0B; ++d0) {
	v_mfma_f32_32x32x16_bf16 v[64:79], v[132:135], v[80:83], 0
	v_mfma_f32_32x32x16_bf16 v[64:79], v[136:139], v[84:87], v[64:79]
	v_mfma_f32_32x32x16_bf16 v[64:79], v[140:143], v[88:91], v[64:79]
	v_mfma_f32_32x32x16_bf16 v[64:79], v[174:177], v[92:95], v[64:79]
	v_mfma_f32_32x32x16_bf16 v[64:79], v[178:181], v[96:99], v[64:79]
	v_mfma_f32_32x32x16_bf16 v[64:79], v[182:185], v[100:103], v[64:79]
	s_waitcnt lgkmcnt(0)
	v_mfma_f32_32x32x16_bf16 v[64:79], v[218:221], v[104:107], v[64:79]
	v_mfma_f32_32x32x16_bf16 v[64:79], v[222:225], v[108:111], v[64:79]
	v_mfma_f32_32x32x16_bf16 v[64:79], v[226:229], v[112:115], v[64:79]
	v_mfma_f32_32x32x16_bf16 v[64:79], v[230:233], v[116:119], v[64:79]
	v_mfma_f32_32x32x16_bf16 v[64:79], v[234:237], v[120:123], v[64:79]
	v_mfma_f32_32x32x16_bf16 v[64:79], v[238:241], v[124:127], v[64:79]
	s_setprio 0
	ds_read_b128 v[132:135], v161 offset:49152
	ds_read_b128 v[136:139], v162 offset:49152
	ds_read_b128 v[140:143], v163 offset:49152
	ds_read_b128 v[174:177], v164 offset:49152
	ds_read_b128 v[178:181], v165 offset:49152
	ds_read_b128 v[182:185], v166 offset:49152
	ds_read_b64_tr_b16 v[186:187], v144 offset:0x2000
	ds_read_b64_tr_b16 v[188:189], v144 offset:0x2800
	ds_read_b64_tr_b16 v[190:191], v144 offset:0x3000
	ds_read_b64_tr_b16 v[192:193], v144 offset:0x3800
	ds_read_b64_tr_b16 v[194:195], v144 offset:0x2200
	ds_read_b64_tr_b16 v[196:197], v144 offset:0x2a00
	ds_read_b64_tr_b16 v[198:199], v144 offset:0x3200
	ds_read_b64_tr_b16 v[200:201], v144 offset:0x3a00
	ds_read_b64_tr_b16 v[202:203], v144 offset:0x2400
	ds_read_b64_tr_b16 v[204:205], v144 offset:0x2c00
	ds_read_b64_tr_b16 v[206:207], v144 offset:0x3400
	ds_read_b64_tr_b16 v[208:209], v144 offset:0x3c00
	ds_read_b64_tr_b16 v[210:211], v144 offset:0x2600
	ds_read_b64_tr_b16 v[212:213], v144 offset:0x2e00
	ds_read_b64_tr_b16 v[214:215], v144 offset:0x3600
	ds_read_b64_tr_b16 v[216:217], v144 offset:0x3e00
	s_nop 5
	s_setprio 2
	v_exp_f32_e32 v64, v64
	v_exp_f32_e32 v65, v65
	v_exp_f32_e32 v66, v66
	v_exp_f32_e32 v67, v67
	v_exp_f32_e32 v68, v68
	v_exp_f32_e32 v69, v69
	v_add_f32_e32 v144, v65, v64
	v_exp_f32_e32 v70, v70
	v_add_f32_e32 v144, v66, v144
	v_exp_f32_e32 v71, v71
	v_add_f32_e32 v144, v67, v144
	v_exp_f32_e32 v72, v72
	v_add_f32_e32 v144, v68, v144
	v_exp_f32_e32 v73, v73
	v_add_f32_e32 v144, v69, v144
	v_exp_f32_e32 v74, v74
	v_add_f32_e32 v144, v70, v144
	v_exp_f32_e32 v75, v75
	v_add_f32_e32 v144, v71, v144
	v_exp_f32_e32 v76, v76
	v_add_f32_e32 v144, v72, v144
	v_exp_f32_e32 v77, v77
	v_add_f32_e32 v144, v73, v144
	v_exp_f32_e32 v78, v78
	v_add_f32_e32 v144, v74, v144
	v_exp_f32_e32 v79, v79
	v_add_f32_e32 v144, v75, v144
	v_add_f32_e32 v144, v76, v144
	v_add_f32_e32 v144, v77, v144
	v_add_f32_e32 v144, v78, v144
	v_add_f32_e32 v144, v79, v144
	v_add_f32_e32 v144, v145, v144
	v_cvt_pk_bf16_f32 v64, v64, v65
	v_cvt_pk_bf16_f32 v65, v66, v67
	v_cvt_pk_bf16_f32 v66, v68, v69
	v_cvt_pk_bf16_f32 v67, v70, v71
	v_cvt_pk_bf16_f32 v68, v72, v73
	v_cvt_pk_bf16_f32 v69, v74, v75
	v_cvt_pk_bf16_f32 v70, v76, v77
	v_cvt_pk_bf16_f32 v71, v78, v79
	s_nop 0
	v_permlane32_swap_b32_e32 v64, v66
	v_permlane32_swap_b32_e32 v65, v67
	v_permlane32_swap_b32_e32 v68, v70
	v_permlane32_swap_b32_e32 v69, v71
	s_waitcnt lgkmcnt(0)
	ds_read_b128 v[218:221], v167 offset:49152
	ds_read_b128 v[222:225], v168 offset:49152
	ds_read_b128 v[226:229], v169 offset:49152
	ds_read_b128 v[230:233], v170 offset:49152
	ds_read_b128 v[234:237], v171 offset:49152
	ds_read_b128 v[238:241], v172 offset:49152
	s_setprio 1
	s_cmp_lt_u32 s33, 0x100
	s_cbranch_scc1 .Lstg_mla_m61_5
	s_waitcnt vmcnt(0)
	s_barrier

; #define LAS __attribute__((address_space(3)))
; DI void expsum(f32x16& p, float& l_reg, bf16x8& pa0, bf16x8& pa1) {
; #pragma unroll
;     for (int r = 0; r < 16; ++r) p[r] = __builtin_amdgcn_exp2f(p[r]);
;     float ps = 0.f;
; #pragma unroll
;     for (int r = 0; r < 16; ++r) ps += p[r];
;     l_reg += ps; asm volatile("" : "+v"(l_reg));
;     ...
;     ATT_PK4(p, 0, pa0); ATT_PK4(p, 8, pa1);
;     ...
; }
; DI int v_rd_base(int lane) { return ((lane & 3) << 3) | (((lane >> 2) & 3) << 6) | (((lane >> 4) & 1) << 5) | (((lane >> 5) & 1) << 8); }
; template <int OFF> DI s16x4 tr_read(int vb) { s16x4 r; asm volatile("ds_read_b64_tr_b16 %0, %1 offset:%2" : "=&v"(r) : "v"(vb), "i"(OFF) : "memory"); return r; }
; template <int H> DI void v_reads(s16x4* vf, int vb) {
;     vf[0] = tr_read<v_rd_off(0, 2 * H, 0)>(vb); vf[1] = tr_read<v_rd_off(0, 2 * H, 1)>(vb); vf[2] = tr_read<v_rd_off(0, 2 * H + 1, 0)>(vb); vf[3] = tr_read<v_rd_off(0, 2 * H + 1, 1)>(vb);
;     vf[4] = tr_read<v_rd_off(1, 2 * H, 0)>(vb); vf[5] = tr_read<v_rd_off(1, 2 * H, 1)>(vb); vf[6] = tr_read<v_rd_off(1, 2 * H + 1, 0)>(vb); vf[7] = tr_read<v_rd_off(1, 2 * H + 1, 1)>(vb);
;     vf[8] = tr_read<v_rd_off(2, 2 * H, 0)>(vb); vf[9] = tr_read<v_rd_off(2, 2 * H, 1)>(vb); vf[10] = tr_read<v_rd_off(2, 2 * H + 1, 0)>(vb); vf[11] = tr_read<v_rd_off(2, 2 * H + 1, 1)>(vb);
;     vf[12] = tr_read<v_rd_off(3, 2 * H, 0)>(vb); vf[13] = tr_read<v_rd_off(3, 2 * H, 1)>(vb); vf[14] = tr_read<v_rd_off(3, 2 * H + 1, 0)>(vb); vf[15] = tr_read<v_rd_off(3, 2 * H + 1, 1)>(vb);
; }
; DI void pv_mma(f32x16* o, const s16x4* vf, bf16x8 pa0, bf16x8 pa1) {
;     ...
; #pragma unroll
;     for (int d0 = 0; d0 < 4; ++d0) {
;         o[d0] = __builtin_amdgcn_mfma_f32_32x32x16_bf16(pa0, ATT_PK(vf[4 * d0], vf[4 * d0 + 1]), o[d0], 0, 0, 0);
;         o[d0] = __builtin_amdgcn_mfma_f32_32x32x16_bf16(pa1, ATT_PK(vf[4 * d0 + 2], vf[4 * d0 + 3]), o[d0], 0, 0, 0); }
;     ...
; }
; template <int DQK, int D0A, int D0B> DI void k_reads(bf16x8* kf, const LAS unsigned char* Ks, int half, int r32, int hi) {
; #pragma unroll
;     for (int d0 = D0A; d0 < D0B; ++d0) kf[d0 - D0A] = *(const LAS bf16x8*)(Ks + half * (32 * DQK * 2) + kswz<DQK>(r32, (d0 * 16 + hi * 8) * 2));
; }
; template <int D0A, int D0B> DI void qk_mma(f32x16& p, const bf16x8* kf, const bf16x8* qr) {
; #pragma unroll
;     for (int d0 = D0A; d0 < D0B; ++d0) {
.Lstg_mla_t62_6:
	s_setprio 0
	ds_read_b128 v[132:135], v161 offset:61440
	ds_read_b128 v[136:139], v162 offset:61440
	ds_read_b128 v[140:143], v163 offset:61440
	ds_read_b128 v[174:177], v164 offset:61440
	ds_read_b128 v[162:165], v165 offset:61440
	ds_read_b128 v[178:181], v166 offset:61440
	v_add_u32_e32 v145, 0x8000, v130
	ds_read_b64_tr_b16 v[182:183], v145 offset:0
	ds_read_b64_tr_b16 v[184:185], v145 offset:0x800
	ds_read_b64_tr_b16 v[186:187], v145 offset:0x1000
	ds_read_b64_tr_b16 v[188:189], v145 offset:0x1800
	ds_read_b64_tr_b16 v[190:191], v145 offset:0x200
	ds_read_b64_tr_b16 v[192:193], v145 offset:0xa00
	ds_read_b64_tr_b16 v[194:195], v145 offset:0x1200
	ds_read_b64_tr_b16 v[196:197], v145 offset:0x1a00
	ds_read_b64_tr_b16 v[198:199], v145 offset:0x400
	ds_read_b64_tr_b16 v[200:201], v145 offset:0xc00
	ds_read_b64_tr_b16 v[202:203], v145 offset:0x1400
	ds_read_b64_tr_b16 v[204:205], v145 offset:0x1c00
	ds_read_b64_tr_b16 v[206:207], v145 offset:0x600
	ds_read_b64_tr_b16 v[208:209], v145 offset:0xe00
	ds_read_b64_tr_b16 v[210:211], v145 offset:0x1600
	ds_read_b64_tr_b16 v[212:213], v145 offset:0x1e00
	s_nop 3
	s_setprio 2
	v_exp_f32_e32 v64, v64
	v_exp_f32_e32 v65, v65
	v_exp_f32_e32 v66, v66
	v_exp_f32_e32 v67, v67
	v_exp_f32_e32 v68, v68
	v_exp_f32_e32 v69, v69
	v_add_f32_e32 v161, v65, v64
	v_exp_f32_e32 v70, v70
	v_add_f32_e32 v161, v66, v161
	v_exp_f32_e32 v71, v71
	v_add_f32_e32 v161, v67, v161
	v_exp_f32_e32 v72, v72
	v_add_f32_e32 v161, v68, v161
	v_exp_f32_e32 v73, v73
	v_add_f32_e32 v161, v69, v161
	v_exp_f32_e32 v74, v74
	v_add_f32_e32 v161, v70, v161
	v_exp_f32_e32 v75, v75
	v_add_f32_e32 v161, v71, v161
	v_exp_f32_e32 v76, v76
	v_add_f32_e32 v161, v72, v161
	v_exp_f32_e32 v77, v77
	v_add_f32_e32 v161, v73, v161
	v_exp_f32_e32 v78, v78
	v_add_f32_e32 v161, v74, v161
	v_exp_f32_e32 v79, v79
	v_add_f32_e32 v161, v75, v161
	v_add_f32_e32 v161, v76, v161
	v_add_f32_e32 v161, v77, v161
	v_add_f32_e32 v161, v78, v161
	v_add_f32_e32 v161, v79, v161
	v_add_f32_e32 v144, v144, v161
	v_cvt_pk_bf16_f32 v64, v64, v65
	v_cvt_pk_bf16_f32 v65, v66, v67
	v_cvt_pk_bf16_f32 v66, v68, v69
	v_cvt_pk_bf16_f32 v67, v70, v71
	v_cvt_pk_bf16_f32 v68, v72, v73
	v_cvt_pk_bf16_f32 v69, v74, v75
	v_cvt_pk_bf16_f32 v70, v76, v77
	v_cvt_pk_bf16_f32 v71, v78, v79
	s_nop 0
	v_permlane32_swap_b32_e32 v64, v66
	v_permlane32_swap_b32_e32 v65, v67
	v_permlane32_swap_b32_e32 v68, v70
	v_permlane32_swap_b32_e32 v69, v71
	s_waitcnt lgkmcnt(0)
	ds_read_b128 v[214:217], v167 offset:61440
	ds_read_b128 v[218:221], v168 offset:61440
	ds_read_b128 v[166:169], v169 offset:61440
	ds_read_b128 v[222:225], v170 offset:61440
	ds_read_b128 v[226:229], v171 offset:61440
	ds_read_b128 v[170:173], v172 offset:61440
	s_setprio 1
	v_mfma_f32_32x32x16_bf16 v[48:63], v[64:67], v[182:185], v[48:63]
	v_mfma_f32_32x32x16_bf16 v[32:47], v[64:67], v[190:193], v[32:47]
	v_mfma_f32_32x32x16_bf16 v[16:31], v[64:67], v[198:201], v[16:31]
	v_mfma_f32_32x32x16_bf16 v[0:15], v[64:67], v[206:209], v[0:15]
	v_mfma_f32_32x32x16_bf16 v[48:63], v[68:71], v[186:189], v[48:63]
	v_mfma_f32_32x32x16_bf16 v[32:47], v[68:71], v[194:197], v[32:47]
	v_mfma_f32_32x32x16_bf16 v[16:31], v[68:71], v[202:205], v[16:31]
	v_mfma_f32_32x32x16_bf16 v[0:15], v[68:71], v[210:213], v[0:15]
	s_waitcnt lgkmcnt(0)
	v_mfma_f32_32x32x16_bf16 v[64:79], v[132:135], v[80:83], 0
	v_mfma_f32_32x32x16_bf16 v[64:79], v[136:139], v[84:87], v[64:79]
	v_mfma_f32_32x32x16_bf16 v[64:79], v[140:143], v[88:91], v[64:79]
	v_mfma_f32_32x32x16_bf16 v[64:79], v[174:177], v[92:95], v[64:79]
	v_mfma_f32_32x32x16_bf16 v[64:79], v[162:165], v[96:99], v[64:79]
	v_mfma_f32_32x32x16_bf16 v[64:79], v[178:181], v[100:103], v[64:79]
	s_waitcnt lgkmcnt(0)
; #define LAS __attribute__((address_space(3)))
; DI void expsum(f32x16& p, float& l_reg, bf16x8& pa0, bf16x8& pa1) {
; #pragma unroll
;     for (int r = 0; r < 16; ++r) p[r] = __builtin_amdgcn_exp2f(p[r]);
;     float ps = 0.f;
; #pragma unroll
;     for (int r = 0; r < 16; ++r) ps += p[r];
;     l_reg += ps; asm volatile("" : "+v"(l_reg));
;     ...
;     ATT_PK4(p, 0, pa0); ATT_PK4(p, 8, pa1);
;     ...
; }
; DI int v_rd_base(int lane) { return ((lane & 3) << 3) | (((lane >> 2) & 3) << 6) | (((lane >> 4) & 1) << 5) | (((lane >> 5) & 1) << 8); }
; template <int OFF> DI s16x4 tr_read(int vb) { s16x4 r; asm volatile("ds_read_b64_tr_b16 %0, %1 offset:%2" : "=&v"(r) : "v"(vb), "i"(OFF) : "memory"); return r; }
; template <int H> DI void v_reads(s16x4* vf, int vb) {
;     vf[0] = tr_read<v_rd_off(0, 2 * H, 0)>(vb); vf[1] = tr_read<v_rd_off(0, 2 * H, 1)>(vb); vf[2] = tr_read<v_rd_off(0, 2 * H + 1, 0)>(vb); vf[3] = tr_read<v_rd_off(0, 2 * H + 1, 1)>(vb);
;     vf[4] = tr_read<v_rd_off(1, 2 * H, 0)>(vb); vf[5] = tr_read<v_rd_off(1, 2 * H, 1)>(vb); vf[6] = tr_read<v_rd_off(1, 2 * H + 1, 0)>(vb); vf[7] = tr_read<v_rd_off(1, 2 * H + 1, 1)>(vb);
;     vf[8] = tr_read<v_rd_off(2, 2 * H, 0)>(vb); vf[9] = tr_read<v_rd_off(2, 2 * H, 1)>(vb); vf[10] = tr_read<v_rd_off(2, 2 * H + 1, 0)>(vb); vf[11] = tr_read<v_rd_off(2, 2 * H + 1, 1)>(vb);
;     vf[12] = tr_read<v_rd_off(3, 2 * H, 0)>(vb); vf[13] = tr_read<v_rd_off(3, 2 * H, 1)>(vb); vf[14] = tr_read<v_rd_off(3, 2 * H + 1, 0)>(vb); vf[15] = tr_read<v_rd_off(3, 2 * H + 1, 1)>(vb);
; }
; DI void pv_mma(f32x16* o, const s16x4* vf, bf16x8 pa0, bf16x8 pa1) {
;     ...
; #pragma unroll
;     for (int d0 = 0; d0 < 4; ++d0) {
;         o[d0] = __builtin_amdgcn_mfma_f32_32x32x16_bf16(pa0, ATT_PK(vf[4 * d0], vf[4 * d0 + 1]), o[d0], 0, 0, 0);
;         o[d0] = __builtin_amdgcn_mfma_f32_32x32x16_bf16(pa1, ATT_PK(vf[4 * d0 + 2], vf[4 * d0 + 3]), o[d0], 0, 0, 0); }
;     ...
; }
; template <int DQK, int D0A, int D0B> DI void k_reads(bf16x8* kf, const LAS unsigned char* Ks, int half, int r32, int hi) {
; #pragma unroll
;     for (int d0 = D0A; d0 < D0B; ++d0) kf[d0 - D0A] = *(const LAS bf16x8*)(Ks + half * (32 * DQK * 2) + kswz<DQK>(r32, (d0 * 16 + hi * 8) * 2));
; }
; template <int D0A, int D0B> DI void qk_mma(f32x16& p, const bf16x8* kf, const bf16x8* qr) {
; #pragma unroll
;     for (int d0 = D0A; d0 < D0B; ++d0) {
	v_mfma_f32_32x32x16_bf16 v[64:79], v[214:217], v[104:107], v[64:79]
	v_mfma_f32_32x32x16_bf16 v[64:79], v[218:221], v[108:111], v[64:79]
	v_mfma_f32_32x32x16_bf16 v[64:79], v[166:169], v[112:115], v[64:79]
	v_mfma_f32_32x32x16_bf16 v[64:79], v[222:225], v[116:119], v[64:79]
	v_mfma_f32_32x32x16_bf16 v[64:79], v[226:229], v[120:123], v[64:79]
	v_mfma_f32_32x32x16_bf16 v[64:79], v[170:173], v[124:127], v[64:79]
	s_setprio 0
	v_add_u32_e32 v158, 0x12000, v158
	v_add_u32_e32 v132, v158, v151
	v_add_u32_e32 v136, v158, v149
	v_add_u32_e32 v140, v158, v148
	v_add_u32_e32 v161, v158, v147
	ds_read_b128 v[132:135], v132
	ds_read_b128 v[136:139], v136
	ds_read_b128 v[140:143], v140
	ds_read_b128 v[162:165], v161
	v_add_u32_e32 v161, v158, v146
	v_add_u32_e32 v170, v158, v150
	ds_read_b128 v[166:169], v161
	ds_read_b128 v[170:173], v170
	ds_read_b64_tr_b16 v[174:175], v145 offset:0x2000
	ds_read_b64_tr_b16 v[176:177], v145 offset:0x2800
	ds_read_b64_tr_b16 v[178:179], v145 offset:0x3000
	ds_read_b64_tr_b16 v[180:181], v145 offset:0x3800
	ds_read_b64_tr_b16 v[182:183], v145 offset:0x2200
	ds_read_b64_tr_b16 v[184:185], v145 offset:0x2a00
	ds_read_b64_tr_b16 v[186:187], v145 offset:0x3200
	ds_read_b64_tr_b16 v[188:189], v145 offset:0x3a00
	ds_read_b64_tr_b16 v[190:191], v145 offset:0x2400
	ds_read_b64_tr_b16 v[192:193], v145 offset:0x2c00
	ds_read_b64_tr_b16 v[194:195], v145 offset:0x3400
	ds_read_b64_tr_b16 v[196:197], v145 offset:0x3c00
	ds_read_b64_tr_b16 v[198:199], v145 offset:0x2600
	ds_read_b64_tr_b16 v[200:201], v145 offset:0x2e00
	ds_read_b64_tr_b16 v[202:203], v145 offset:0x3600
	ds_read_b64_tr_b16 v[204:205], v145 offset:0x3e00
	s_setprio 2
	v_exp_f32_e32 v64, v64
	v_exp_f32_e32 v65, v65
	v_exp_f32_e32 v66, v66
	v_exp_f32_e32 v67, v67
	v_exp_f32_e32 v68, v68
	v_exp_f32_e32 v69, v69
	v_add_f32_e32 v145, v65, v64
	v_exp_f32_e32 v70, v70
	v_add_f32_e32 v145, v66, v145
	v_exp_f32_e32 v71, v71
	v_add_f32_e32 v145, v67, v145
	v_exp_f32_e32 v72, v72
	v_add_f32_e32 v145, v68, v145
	v_exp_f32_e32 v73, v73
	v_add_f32_e32 v145, v69, v145
	v_exp_f32_e32 v74, v74
	v_add_f32_e32 v145, v70, v145
	v_exp_f32_e32 v75, v75
	v_add_f32_e32 v145, v71, v145
	v_exp_f32_e32 v76, v76
	v_add_f32_e32 v145, v72, v145
	v_exp_f32_e32 v77, v77
	v_add_f32_e32 v145, v73, v145
	v_exp_f32_e32 v78, v78
	v_add_f32_e32 v145, v74, v145
	v_exp_f32_e32 v79, v79
	v_add_f32_e32 v145, v75, v145
	v_add_f32_e32 v145, v76, v145
	v_add_f32_e32 v145, v77, v145
	v_add_f32_e32 v145, v78, v145
	v_add_f32_e32 v145, v79, v145
	v_add_f32_e32 v161, v144, v145
	v_cvt_pk_bf16_f32 v64, v64, v65
	v_cvt_pk_bf16_f32 v65, v66, v67
	v_cvt_pk_bf16_f32 v66, v68, v69
	v_cvt_pk_bf16_f32 v67, v70, v71
	v_cvt_pk_bf16_f32 v68, v72, v73
	v_cvt_pk_bf16_f32 v69, v74, v75
	v_cvt_pk_bf16_f32 v70, v76, v77
	v_cvt_pk_bf16_f32 v71, v78, v79
	s_nop 0
	v_permlane32_swap_b32_e32 v64, v66
	v_permlane32_swap_b32_e32 v65, v67
	v_permlane32_swap_b32_e32 v68, v70
	v_permlane32_swap_b32_e32 v69, v71
	s_waitcnt lgkmcnt(0)
	v_add_u32_e32 v72, v158, v152
	v_add_u32_e32 v73, v158, v153
	ds_read_b128 v[206:209], v72
	ds_read_b128 v[210:213], v73
	v_add_u32_e32 v72, v158, v154
	v_add_u32_e32 v73, v158, v155
	ds_read_b128 v[214:217], v72
	ds_read_b128 v[218:221], v73
	v_add_u32_e32 v72, v158, v156
	v_add_u32_e32 v73, v158, v157
	ds_read_b128 v[222:225], v72
	ds_read_b128 v[226:229], v73
	s_setprio 1
	s_cmp_lt_u32 s33, 0x100
	s_cbranch_scc1 .Lstg_mla_m62_7
	s_waitcnt vmcnt(0)
	s_barrier

; #define LAS __attribute__((address_space(3)))
; DI void expsum(f32x16& p, float& l_reg, bf16x8& pa0, bf16x8& pa1) {
; #pragma unroll
;     for (int r = 0; r < 16; ++r) p[r] = __builtin_amdgcn_exp2f(p[r]);
;     float ps = 0.f;
; #pragma unroll
;     for (int r = 0; r < 16; ++r) ps += p[r];
;     l_reg += ps; asm volatile("" : "+v"(l_reg));
;     ...
;     ATT_PK4(p, 0, pa0); ATT_PK4(p, 8, pa1);
;     ...
; }
; DI int v_rd_base(int lane) { return ((lane & 3) << 3) | (((lane >> 2) & 3) << 6) | (((lane >> 4) & 1) << 5) | (((lane >> 5) & 1) << 8); }
; template <int OFF> DI s16x4 tr_read(int vb) { s16x4 r; asm volatile("ds_read_b64_tr_b16 %0, %1 offset:%2" : "=&v"(r) : "v"(vb), "i"(OFF) : "memory"); return r; }
; template <int H> DI void v_reads(s16x4* vf, int vb) {
;     vf[0] = tr_read<v_rd_off(0, 2 * H, 0)>(vb); vf[1] = tr_read<v_rd_off(0, 2 * H, 1)>(vb); vf[2] = tr_read<v_rd_off(0, 2 * H + 1, 0)>(vb); vf[3] = tr_read<v_rd_off(0, 2 * H + 1, 1)>(vb);
;     vf[4] = tr_read<v_rd_off(1, 2 * H, 0)>(vb); vf[5] = tr_read<v_rd_off(1, 2 * H, 1)>(vb); vf[6] = tr_read<v_rd_off(1, 2 * H + 1, 0)>(vb); vf[7] = tr_read<v_rd_off(1, 2 * H + 1, 1)>(vb);
;     vf[8] = tr_read<v_rd_off(2, 2 * H, 0)>(vb); vf[9] = tr_read<v_rd_off(2, 2 * H, 1)>(vb); vf[10] = tr_read<v_rd_off(2, 2 * H + 1, 0)>(vb); vf[11] = tr_read<v_rd_off(2, 2 * H + 1, 1)>(vb);
;     vf[12] = tr_read<v_rd_off(3, 2 * H, 0)>(vb); vf[13] = tr_read<v_rd_off(3, 2 * H, 1)>(vb); vf[14] = tr_read<v_rd_off(3, 2 * H + 1, 0)>(vb); vf[15] = tr_read<v_rd_off(3, 2 * H + 1, 1)>(vb);
; }
; DI void pv_mma(f32x16* o, const s16x4* vf, bf16x8 pa0, bf16x8 pa1) {
;     ...
; #pragma unroll
;     for (int d0 = 0; d0 < 4; ++d0) {
;         o[d0] = __builtin_amdgcn_mfma_f32_32x32x16_bf16(pa0, ATT_PK(vf[4 * d0], vf[4 * d0 + 1]), o[d0], 0, 0, 0);
;         o[d0] = __builtin_amdgcn_mfma_f32_32x32x16_bf16(pa1, ATT_PK(vf[4 * d0 + 2], vf[4 * d0 + 3]), o[d0], 0, 0, 0); }
;     ...
; }
; template <int DQK, int D0A, int D0B> DI void k_reads(bf16x8* kf, const LAS unsigned char* Ks, int half, int r32, int hi) {
; #pragma unroll
;     for (int d0 = D0A; d0 < D0B; ++d0) kf[d0 - D0A] = *(const LAS bf16x8*)(Ks + half * (32 * DQK * 2) + kswz<DQK>(r32, (d0 * 16 + hi * 8) * 2));
; }
; template <int D0A, int D0B> DI void qk_mma(f32x16& p, const bf16x8* kf, const bf16x8* qr) {
; #pragma unroll
;     for (int d0 = D0A; d0 < D0B; ++d0) {
.Lstg_mla_t63_8:
	s_setprio 0
	v_add_u32_e32 v158, s82, v159
	v_add_u32_e32 v132, v158, v151
	v_add_u32_e32 v136, v158, v149
	v_add_u32_e32 v140, v158, v148
	v_add_u32_e32 v144, v158, v147
	ds_read_b128 v[132:135], v132
	ds_read_b128 v[136:139], v136
	ds_read_b128 v[140:143], v140
	ds_read_b128 v[162:165], v144
	v_add_u32_e32 v144, v158, v146
	v_add_u32_e32 v148, v158, v150
	ds_read_b128 v[144:147], v144
	ds_read_b128 v[148:151], v148
	ds_read_b64_tr_b16 v[166:167], v130 offset:0
	ds_read_b64_tr_b16 v[168:169], v130 offset:0x800
	ds_read_b64_tr_b16 v[170:171], v130 offset:0x1000
	ds_read_b64_tr_b16 v[172:173], v130 offset:0x1800
	ds_read_b64_tr_b16 v[174:175], v130 offset:0x200
	ds_read_b64_tr_b16 v[176:177], v130 offset:0xa00
	ds_read_b64_tr_b16 v[178:179], v130 offset:0x1200
	ds_read_b64_tr_b16 v[180:181], v130 offset:0x1a00
	ds_read_b64_tr_b16 v[182:183], v130 offset:0x400
	ds_read_b64_tr_b16 v[184:185], v130 offset:0xc00
	ds_read_b64_tr_b16 v[186:187], v130 offset:0x1400
	ds_read_b64_tr_b16 v[188:189], v130 offset:0x1c00
	ds_read_b64_tr_b16 v[190:191], v130 offset:0x600
	ds_read_b64_tr_b16 v[192:193], v130 offset:0xe00
	ds_read_b64_tr_b16 v[194:195], v130 offset:0x1600
	ds_read_b64_tr_b16 v[196:197], v130 offset:0x1e00
	s_setprio 2
	v_exp_f32_e32 v64, v64
	v_exp_f32_e32 v65, v65
	v_exp_f32_e32 v66, v66
	v_exp_f32_e32 v67, v67
	v_exp_f32_e32 v68, v68
	v_exp_f32_e32 v69, v69
	v_add_f32_e32 v159, v65, v64
	v_exp_f32_e32 v70, v70
	v_add_f32_e32 v159, v66, v159
	v_exp_f32_e32 v71, v71
	v_add_f32_e32 v159, v67, v159
	v_exp_f32_e32 v72, v72
	v_add_f32_e32 v159, v68, v159
	v_exp_f32_e32 v73, v73
	v_add_f32_e32 v159, v69, v159
	v_exp_f32_e32 v74, v74
	v_add_f32_e32 v159, v70, v159
	v_exp_f32_e32 v75, v75
	v_add_f32_e32 v159, v71, v159
	v_exp_f32_e32 v76, v76
	v_add_f32_e32 v159, v72, v159
	v_exp_f32_e32 v77, v77
	v_add_f32_e32 v159, v73, v159
	v_exp_f32_e32 v78, v78
	v_add_f32_e32 v159, v74, v159
	v_exp_f32_e32 v79, v79
	v_add_f32_e32 v159, v75, v159
	v_add_f32_e32 v159, v76, v159
	v_add_f32_e32 v159, v77, v159
	v_add_f32_e32 v159, v78, v159
	v_add_f32_e32 v159, v79, v159
	v_add_f32_e32 v161, v161, v159
	v_cvt_pk_bf16_f32 v64, v64, v65
	v_cvt_pk_bf16_f32 v65, v66, v67
	v_cvt_pk_bf16_f32 v66, v68, v69
	v_cvt_pk_bf16_f32 v67, v70, v71
	v_cvt_pk_bf16_f32 v68, v72, v73
	v_cvt_pk_bf16_f32 v69, v74, v75
	v_cvt_pk_bf16_f32 v70, v76, v77
	v_cvt_pk_bf16_f32 v71, v78, v79
	s_nop 0
	v_permlane32_swap_b32_e32 v64, v66
	v_permlane32_swap_b32_e32 v65, v67
	v_permlane32_swap_b32_e32 v68, v70
	v_permlane32_swap_b32_e32 v69, v71
	s_waitcnt lgkmcnt(0)
	v_add_u32_e32 v72, v158, v152
	v_add_u32_e32 v73, v158, v153
	ds_read_b128 v[198:201], v72
	ds_read_b128 v[202:205], v73
	v_add_u32_e32 v72, v158, v154
	v_add_u32_e32 v73, v158, v155
	ds_read_b128 v[152:155], v72
	ds_read_b128 v[206:209], v73
	v_add_u32_e32 v72, v158, v156
	v_add_u32_e32 v73, v158, v157
	ds_read_b128 v[156:159], v72
	ds_read_b128 v[210:213], v73
	s_setprio 1
	v_mfma_f32_32x32x16_bf16 v[48:63], v[64:67], v[166:169], v[48:63]
	v_mfma_f32_32x32x16_bf16 v[32:47], v[64:67], v[174:177], v[32:47]
	v_mfma_f32_32x32x16_bf16 v[16:31], v[64:67], v[182:185], v[16:31]
	v_mfma_f32_32x32x16_bf16 v[0:15], v[64:67], v[190:193], v[0:15]
	v_mfma_f32_32x32x16_bf16 v[48:63], v[68:71], v[170:173], v[48:63]
	v_mfma_f32_32x32x16_bf16 v[32:47], v[68:71], v[178:181], v[32:47]
	v_mfma_f32_32x32x16_bf16 v[16:31], v[68:71], v[186:189], v[16:31]
	v_mfma_f32_32x32x16_bf16 v[0:15], v[68:71], v[194:197], v[0:15]
	s_waitcnt lgkmcnt(0)
; DI void expsum(f32x16& p, float& l_reg, bf16x8& pa0, bf16x8& pa1) {
; #pragma unroll
;     for (int r = 0; r < 16; ++r) p[r] = __builtin_amdgcn_exp2f(p[r]);
;     float ps = 0.f;
; #pragma unroll
;     for (int r = 0; r < 16; ++r) ps += p[r];
;     l_reg += ps; asm volatile("" : "+v"(l_reg));
;     ...
;     ATT_PK4(p, 0, pa0); ATT_PK4(p, 8, pa1);
;     ...
; }
; DI int v_rd_base(int lane) { return ((lane & 3) << 3) | (((lane >> 2) & 3) << 6) | (((lane >> 4) & 1) << 5) | (((lane >> 5) & 1) << 8); }
; template <int OFF> DI s16x4 tr_read(int vb) { s16x4 r; asm volatile("ds_read_b64_tr_b16 %0, %1 offset:%2" : "=&v"(r) : "v"(vb), "i"(OFF) : "memory"); return r; }
; template <int H> DI void v_reads(s16x4* vf, int vb) {
;     vf[0] = tr_read<v_rd_off(0, 2 * H, 0)>(vb); vf[1] = tr_read<v_rd_off(0, 2 * H, 1)>(vb); vf[2] = tr_read<v_rd_off(0, 2 * H + 1, 0)>(vb); vf[3] = tr_read<v_rd_off(0, 2 * H + 1, 1)>(vb);
;     vf[4] = tr_read<v_rd_off(1, 2 * H, 0)>(vb); vf[5] = tr_read<v_rd_off(1, 2 * H, 1)>(vb); vf[6] = tr_read<v_rd_off(1, 2 * H + 1, 0)>(vb); vf[7] = tr_read<v_rd_off(1, 2 * H + 1, 1)>(vb);
;     vf[8] = tr_read<v_rd_off(2, 2 * H, 0)>(vb); vf[9] = tr_read<v_rd_off(2, 2 * H, 1)>(vb); vf[10] = tr_read<v_rd_off(2, 2 * H + 1, 0)>(vb); vf[11] = tr_read<v_rd_off(2, 2 * H + 1, 1)>(vb);
; template <int DQK, int MODE, int LDQ, int LDK, int LDV> ...
;     ...
;     f32x16 pA, pB; bf16x8 pa0, pa1;
;     int v0 = 0, v1 = 1, v2 = 2;
;     ATT_TOP(NKP + 2);
;     { bf16x8 kf[NDA]; k_reads<DQK, 0, NDA>(kf, lds, 0, r32, hi); ATT_LGKM0(); qk_mma<0, NDA>(pA, kf, qr);
;       if constexpr (ND0 > NDA) { bf16x8 kg[ND0 - NDA]; k_reads<DQK, NDA, ND0>(kg, lds, 0, r32, hi); ATT_LGKM0(); qk_mma<NDA, ND0>(pA, kg, qr); }
;       ATT_BIAS(pA, 0, 0); }
;     if (wid >= 4) __builtin_amdgcn_s_setprio(1);
;     for (int j = 0; j < NT; ++j) {
;         if (j + 2 < NT) ATT_TOP(NKP + 2); else ATT_TOP(0);
;         if (j + 3 < NT) ATT_DMA_K(j + 3);
;         if (j + 2 < NT) ATT_DMA_V(j + 2, v2);
;         ATT_SEG(j); SBAR();
;         ATT_STEP(pA, pB, 0, v0, true, 1, j);
;         ATT_STEP(pB, pA, 1, v0, (j + 1 < NT), 0, j + 1);
;         { const int t_ = v0; v0 = v1; v1 = v2; v2 = t_; }
;     }
;     __builtin_amdgcn_s_setprio(0);
;     ...
;     l_reg = swap_sum(l_reg);
;     { const int lane2 = fresh_tid<110 + MODE>(wv) & 63, r32 = lane2 & 31, hi = lane2 >> 5;
;     if (hi == 0) li_l[r32] = l_reg;
	v_mfma_f32_32x32x16_bf16 v[64:79], v[132:135], v[80:83], 0
	v_mfma_f32_32x32x16_bf16 v[64:79], v[136:139], v[84:87], v[64:79]
	v_mfma_f32_32x32x16_bf16 v[64:79], v[140:143], v[88:91], v[64:79]
	v_mfma_f32_32x32x16_bf16 v[64:79], v[162:165], v[92:95], v[64:79]
	v_mfma_f32_32x32x16_bf16 v[64:79], v[144:147], v[96:99], v[64:79]
	v_mfma_f32_32x32x16_bf16 v[64:79], v[148:151], v[100:103], v[64:79]
	s_waitcnt lgkmcnt(0)
	v_mfma_f32_32x32x16_bf16 v[64:79], v[198:201], v[104:107], v[64:79]
	v_mfma_f32_32x32x16_bf16 v[64:79], v[202:205], v[108:111], v[64:79]
	v_mfma_f32_32x32x16_bf16 v[64:79], v[152:155], v[112:115], v[64:79]
	v_mfma_f32_32x32x16_bf16 v[64:79], v[206:209], v[116:119], v[64:79]
	v_mfma_f32_32x32x16_bf16 v[64:79], v[156:159], v[120:123], v[64:79]
	v_mfma_f32_32x32x16_bf16 v[64:79], v[210:213], v[124:127], v[64:79]
	s_setprio 0
	ds_read_b64_tr_b16 v[80:81], v130 offset:0x2000
	ds_read_b64_tr_b16 v[82:83], v130 offset:0x2800
	ds_read_b64_tr_b16 v[84:85], v130 offset:0x3000
	ds_read_b64_tr_b16 v[86:87], v130 offset:0x3800
	ds_read_b64_tr_b16 v[88:89], v130 offset:0x2200
	ds_read_b64_tr_b16 v[90:91], v130 offset:0x2a00
	ds_read_b64_tr_b16 v[92:93], v130 offset:0x3200
	ds_read_b64_tr_b16 v[94:95], v130 offset:0x3a00
	ds_read_b64_tr_b16 v[96:97], v130 offset:0x2400
	ds_read_b64_tr_b16 v[98:99], v130 offset:0x2c00
	ds_read_b64_tr_b16 v[100:101], v130 offset:0x3400
	ds_read_b64_tr_b16 v[102:103], v130 offset:0x3c00
	ds_read_b64_tr_b16 v[104:105], v130 offset:0x2600
	ds_read_b64_tr_b16 v[106:107], v130 offset:0x2e00
	ds_read_b64_tr_b16 v[108:109], v130 offset:0x3600
	ds_read_b64_tr_b16 v[110:111], v130 offset:0x3e00
	s_nop 11
	s_setprio 2
	v_exp_f32_e32 v112, v64
	v_exp_f32_e32 v65, v65
	v_exp_f32_e32 v113, v66
	v_exp_f32_e32 v67, v67
	v_exp_f32_e32 v68, v68
	v_exp_f32_e32 v69, v69
	v_add_f32_e32 v64, v65, v112
	v_exp_f32_e32 v70, v70
	v_add_f32_e32 v64, v113, v64
	v_exp_f32_e32 v71, v71
	v_add_f32_e32 v64, v67, v64
	v_exp_f32_e32 v72, v72
	v_add_f32_e32 v64, v68, v64
	v_exp_f32_e32 v73, v73
	v_add_f32_e32 v64, v69, v64
	v_exp_f32_e32 v74, v74
	v_add_f32_e32 v64, v70, v64
	v_exp_f32_e32 v75, v75
	v_add_f32_e32 v64, v71, v64
	v_exp_f32_e32 v76, v76
	v_add_f32_e32 v64, v72, v64
	v_exp_f32_e32 v77, v77
	v_add_f32_e32 v64, v73, v64
	v_exp_f32_e32 v78, v78
	v_add_f32_e32 v64, v74, v64
	v_exp_f32_e32 v79, v79
	v_add_f32_e32 v64, v75, v64
	v_add_f32_e32 v64, v76, v64
	v_add_f32_e32 v64, v77, v64
	v_add_f32_e32 v64, v78, v64
	v_add_f32_e32 v64, v79, v64
	v_add_f32_e32 v64, v161, v64
	v_cvt_pk_bf16_f32 v66, v112, v65
	v_cvt_pk_bf16_f32 v67, v113, v67
	v_cvt_pk_bf16_f32 v68, v68, v69
	v_cvt_pk_bf16_f32 v69, v70, v71
	v_cvt_pk_bf16_f32 v70, v72, v73
	v_cvt_pk_bf16_f32 v71, v74, v75
	v_cvt_pk_bf16_f32 v72, v76, v77
	v_cvt_pk_bf16_f32 v73, v78, v79
	s_nop 0
	v_permlane32_swap_b32_e32 v66, v68
	v_permlane32_swap_b32_e32 v67, v69
	v_permlane32_swap_b32_e32 v70, v72
	v_permlane32_swap_b32_e32 v71, v73
	s_waitcnt lgkmcnt(0)
	s_setprio 1
	v_mfma_f32_32x32x16_bf16 v[48:63], v[66:69], v[80:83], v[48:63]
	v_mfma_f32_32x32x16_bf16 v[32:47], v[66:69], v[88:91], v[32:47]
	v_mfma_f32_32x32x16_bf16 v[16:31], v[66:69], v[96:99], v[16:31]
	v_mfma_f32_32x32x16_bf16 v[0:15], v[66:69], v[104:107], v[0:15]
	v_mfma_f32_32x32x16_bf16 v[48:63], v[70:73], v[84:87], v[48:63]
	v_mfma_f32_32x32x16_bf16 v[32:47], v[70:73], v[92:95], v[32:47]
	v_mfma_f32_32x32x16_bf16 v[16:31], v[70:73], v[100:103], v[16:31]
	v_mfma_f32_32x32x16_bf16 v[0:15], v[70:73], v[108:111], v[0:15]
	s_setprio 0
	v_mbcnt_lo_u32_b32 v66, -1, 0
	v_mbcnt_hi_u32_b32 v66, -1, v66
	v_mov_b32_e32 v67, v64
	v_and_b32_e32 v65, 31, v66
	v_bfe_u32 v66, v66, 5, 1
	v_permlane32_swap_b32_e32 v64, v67
	v_cmp_eq_u32_e32 vcc, 0, v66
	s_and_saveexec_b64 s[2:3], vcc
	s_cbranch_execz .LBB0_1910
	v_lshl_add_u32 v68, v65, 2, s4
	v_add_f32_e32 v64, v64, v67
	ds_write_b32 v68, v64
	s_branch .LBB0_1910
